# ds_reads-first ordering in GEMM load segments (all ds_read_b128 ahead of SALU/addr/LDS-DMA issue) on top of astat+noscale+handoff+LN staging
# speedup vs baseline: 1.0005x; 1.0005x over previous
.LBB0_197:
	ds_read_b128 v[18:21], v190
	ds_read_b128 v[22:25], v190 offset:1024
	ds_read_b128 v[26:29], v190 offset:2048
	ds_read_b128 v[30:33], v190 offset:3072
	ds_read_b128 v[2:5], v190 offset:16384
	ds_read_b128 v[6:9], v190 offset:17408
	ds_read_b128 v[10:13], v190 offset:18432
	ds_read_b128 v[14:17], v190 offset:19456
	ds_read_b128 v[180:183], v191
	ds_read_b128 v[184:187], v191 offset:1024
	ds_read_b128 v[192:195], v191 offset:2048
	ds_read_b128 v[196:199], v191 offset:3072
	ds_read_b128 v[200:203], v191 offset:4096
	ds_read_b128 v[204:207], v191 offset:5120
	ds_read_b128 v[208:211], v191 offset:6144
	ds_read_b128 v[212:215], v191 offset:7168
	s_ashr_i32 s47, s46, 31
	s_lshl_b64 s[8:9], s[46:47], 20
	s_add_u32 s48, s22, s8
	s_addc_u32 s49, s23, s9
	s_and_b64 s[8:9], s[2:3], exec
	s_cselect_b32 s47, s49, s73
	s_cselect_b32 s70, s48, s72
	s_ashr_i32 s45, s44, 31
	s_lshl_b64 s[8:9], s[44:45], 20
	s_add_u32 s50, s27, s8
	s_addc_u32 s51, s68, s9
	s_and_b64 s[8:9], s[2:3], exec
	s_cselect_b32 s45, s51, s55
	s_cselect_b32 s71, s50, s54
	s_add_u32 s8, s72, 0x80080
	s_addc_u32 s9, s73, 0
	s_mov_b32 m0, s92
	v_lshl_add_u64 v[216:217], s[8:9], 0, v[164:165]
	global_load_lds_dwordx4 v[216:217], off
	v_lshl_add_u64 v[216:217], s[8:9], 0, v[168:169]
	s_mov_b32 m0, s93
	s_nop 0
	global_load_lds_dwordx4 v[216:217], off
	s_waitcnt vmcnt(8)
	s_waitcnt lgkmcnt(0)
	s_setprio 1
	s_barrier
	v_mfma_f32_16x16x128_f8f6f4 v[158:161], v[18:25], v[180:187], 0
	v_mfma_f32_16x16x128_f8f6f4 v[154:157], v[26:33], v[180:187], 0
	v_mfma_f32_16x16x128_f8f6f4 v[122:125], v[10:17], v[180:187], 0
	v_mfma_f32_16x16x128_f8f6f4 v[126:129], v[2:9], v[180:187], 0
	v_mfma_f32_16x16x128_f8f6f4 v[118:121], v[2:9], v[192:199], 0
	v_mfma_f32_16x16x128_f8f6f4 v[114:117], v[10:17], v[192:199], 0
	v_mfma_f32_16x16x128_f8f6f4 v[146:149], v[26:33], v[192:199], 0
	v_mfma_f32_16x16x128_f8f6f4 v[150:153], v[18:25], v[192:199], 0
	s_setprio 0
	s_setprio 1
	v_mfma_f32_16x16x128_f8f6f4 v[142:145], v[18:25], v[200:207], 0
	v_mfma_f32_16x16x128_f8f6f4 v[138:141], v[26:33], v[200:207], 0
	v_mfma_f32_16x16x128_f8f6f4 v[106:109], v[10:17], v[200:207], 0
	v_mfma_f32_16x16x128_f8f6f4 v[110:113], v[2:9], v[200:207], 0
	v_mfma_f32_16x16x128_f8f6f4 v[102:105], v[2:9], v[208:215], 0
	v_mfma_f32_16x16x128_f8f6f4 v[98:101], v[10:17], v[208:215], 0
	v_mfma_f32_16x16x128_f8f6f4 v[130:133], v[26:33], v[208:215], 0
	v_mfma_f32_16x16x128_f8f6f4 v[134:137], v[18:25], v[208:215], 0
	s_barrier
	s_setprio 0
	ds_read_b128 v[192:195], v191 offset:16384
	ds_read_b128 v[196:199], v191 offset:17408
	ds_read_b128 v[200:203], v191 offset:18432
	ds_read_b128 v[204:207], v191 offset:19456
	ds_read_b128 v[208:211], v191 offset:20480
	ds_read_b128 v[212:215], v191 offset:21504
	ds_read_b128 v[216:219], v191 offset:22528
	ds_read_b128 v[220:223], v191 offset:23552
	v_lshl_add_u64 v[180:181], s[54:55], 0, v[166:167]
	s_mov_b32 m0, s77
	v_lshl_add_u64 v[182:183], v[180:181], 0, s[16:17]
	global_load_lds_dwordx4 v[182:183], off
	v_lshl_add_u64 v[182:183], s[54:55], 0, v[170:171]
	s_add_u32 s8, s54, 0x80100
	v_lshl_add_u64 v[184:185], v[182:183], 0, s[16:17]
	s_mov_b32 m0, s78
	s_addc_u32 s9, s55, 0
	global_load_lds_dwordx4 v[184:185], off
	v_lshl_add_u64 v[184:185], s[8:9], 0, v[166:167]
	s_mov_b32 m0, s79
	s_nop 0
	global_load_lds_dwordx4 v[184:185], off
	v_lshl_add_u64 v[184:185], s[8:9], 0, v[170:171]
	s_mov_b32 m0, s80
	s_nop 0
	global_load_lds_dwordx4 v[184:185], off
	v_lshl_add_u64 v[184:185], s[72:73], 0, v[164:165]
	v_lshl_add_u64 v[186:187], v[184:185], 0, s[16:17]
	s_mov_b32 m0, s53
	s_nop 0
	global_load_lds_dwordx4 v[186:187], off
	v_lshl_add_u64 v[186:187], s[72:73], 0, v[168:169]
	v_lshl_add_u64 v[224:225], v[186:187], 0, s[16:17]
	s_mov_b32 m0, s81
	s_nop 0
	global_load_lds_dwordx4 v[224:225], off
	s_waitcnt vmcnt(8)
	s_waitcnt lgkmcnt(0)
	s_setprio 1
	s_barrier
	v_mfma_f32_16x16x128_f8f6f4 v[94:97], v[18:25], v[192:199], 0
	v_mfma_f32_16x16x128_f8f6f4 v[90:93], v[26:33], v[192:199], 0
	v_mfma_f32_16x16x128_f8f6f4 v[58:61], v[10:17], v[192:199], 0
	v_mfma_f32_16x16x128_f8f6f4 v[62:65], v[2:9], v[192:199], 0
	v_mfma_f32_16x16x128_f8f6f4 v[54:57], v[2:9], v[200:207], 0
	v_mfma_f32_16x16x128_f8f6f4 v[50:53], v[10:17], v[200:207], 0
	v_mfma_f32_16x16x128_f8f6f4 v[82:85], v[26:33], v[200:207], 0
	v_mfma_f32_16x16x128_f8f6f4 v[86:89], v[18:25], v[200:207], 0
	s_setprio 0
	s_setprio 1
	v_mfma_f32_16x16x128_f8f6f4 v[78:81], v[18:25], v[208:215], 0
	v_mfma_f32_16x16x128_f8f6f4 v[74:77], v[26:33], v[208:215], 0
	v_mfma_f32_16x16x128_f8f6f4 v[42:45], v[10:17], v[208:215], 0
	v_mfma_f32_16x16x128_f8f6f4 v[46:49], v[2:9], v[208:215], 0
	v_mfma_f32_16x16x128_f8f6f4 v[38:41], v[2:9], v[216:223], 0
	v_mfma_f32_16x16x128_f8f6f4 v[34:37], v[10:17], v[216:223], 0
	v_mfma_f32_16x16x128_f8f6f4 v[66:69], v[26:33], v[216:223], 0
	v_mfma_f32_16x16x128_f8f6f4 v[70:73], v[18:25], v[216:223], 0
	s_barrier
	s_setprio 0
	ds_read_b128 v[18:21], v190 offset:32768
	ds_read_b128 v[22:25], v190 offset:33792
	ds_read_b128 v[26:29], v190 offset:34816
	ds_read_b128 v[30:33], v190 offset:35840
	ds_read_b128 v[2:5], v190 offset:49152
	ds_read_b128 v[6:9], v190 offset:50176
	ds_read_b128 v[10:13], v190 offset:51200
	ds_read_b128 v[14:17], v190 offset:52224
	ds_read_b128 v[192:195], v191 offset:32768
	ds_read_b128 v[196:199], v191 offset:33792
	ds_read_b128 v[200:203], v191 offset:34816
	ds_read_b128 v[204:207], v191 offset:35840
	ds_read_b128 v[208:211], v191 offset:36864
	ds_read_b128 v[212:215], v191 offset:37888
	ds_read_b128 v[216:219], v191 offset:38912
	ds_read_b128 v[220:223], v191 offset:39936
	s_add_u32 s8, s72, 0x80100
	s_addc_u32 s9, s73, 0
	s_mov_b32 m0, s82
	v_lshl_add_u64 v[224:225], s[8:9], 0, v[164:165]
	global_load_lds_dwordx4 v[224:225], off
	v_lshl_add_u64 v[224:225], s[8:9], 0, v[168:169]
	s_mov_b32 m0, s83
	s_nop 0
	global_load_lds_dwordx4 v[224:225], off
	s_waitcnt vmcnt(8)
	s_waitcnt lgkmcnt(0)
	s_setprio 1
	s_barrier
	v_mfma_f32_16x16x128_f8f6f4 v[158:161], v[18:25], v[192:199], v[158:161]
	v_mfma_f32_16x16x128_f8f6f4 v[154:157], v[26:33], v[192:199], v[154:157]
	v_mfma_f32_16x16x128_f8f6f4 v[122:125], v[10:17], v[192:199], v[122:125]
	v_mfma_f32_16x16x128_f8f6f4 v[126:129], v[2:9], v[192:199], v[126:129]
	v_mfma_f32_16x16x128_f8f6f4 v[118:121], v[2:9], v[200:207], v[118:121]
	v_mfma_f32_16x16x128_f8f6f4 v[114:117], v[10:17], v[200:207], v[114:117]
	v_mfma_f32_16x16x128_f8f6f4 v[146:149], v[26:33], v[200:207], v[146:149]
	v_mfma_f32_16x16x128_f8f6f4 v[150:153], v[18:25], v[200:207], v[150:153]
	s_setprio 0
	s_setprio 1
	v_mfma_f32_16x16x128_f8f6f4 v[142:145], v[18:25], v[208:215], v[142:145]
	v_mfma_f32_16x16x128_f8f6f4 v[138:141], v[26:33], v[208:215], v[138:141]
	v_mfma_f32_16x16x128_f8f6f4 v[106:109], v[10:17], v[208:215], v[106:109]
	v_mfma_f32_16x16x128_f8f6f4 v[110:113], v[2:9], v[208:215], v[110:113]
	v_mfma_f32_16x16x128_f8f6f4 v[102:105], v[2:9], v[216:223], v[102:105]
	v_mfma_f32_16x16x128_f8f6f4 v[98:101], v[10:17], v[216:223], v[98:101]
	v_mfma_f32_16x16x128_f8f6f4 v[130:133], v[26:33], v[216:223], v[130:133]
	v_mfma_f32_16x16x128_f8f6f4 v[134:137], v[18:25], v[216:223], v[134:137]
	s_barrier
	s_setprio 0
	ds_read_b128 v[192:195], v191 offset:49152
	ds_read_b128 v[196:199], v191 offset:50176
	ds_read_b128 v[200:203], v191 offset:51200
	ds_read_b128 v[204:207], v191 offset:52224
	ds_read_b128 v[208:211], v191 offset:53248
	ds_read_b128 v[212:215], v191 offset:54272
	ds_read_b128 v[216:219], v191 offset:55296
	ds_read_b128 v[220:223], v191 offset:56320
	s_mov_b32 m0, s86
	v_lshl_add_u64 v[180:181], v[180:181], 0, s[20:21]
	s_add_u32 s8, s54, 0x80180
	global_load_lds_dwordx4 v[180:181], off
	v_lshl_add_u64 v[180:181], v[182:183], 0, s[20:21]
	s_mov_b32 m0, s87
	s_addc_u32 s9, s55, 0
	global_load_lds_dwordx4 v[180:181], off
	v_lshl_add_u64 v[180:181], s[8:9], 0, v[166:167]
	s_mov_b32 m0, s90
	s_nop 0
	global_load_lds_dwordx4 v[180:181], off
	v_lshl_add_u64 v[180:181], s[8:9], 0, v[170:171]
	s_mov_b32 m0, s91
	s_nop 0
	global_load_lds_dwordx4 v[180:181], off
	v_lshl_add_u64 v[180:181], v[184:185], 0, s[20:21]
	s_mov_b32 m0, s88
	s_nop 0
	global_load_lds_dwordx4 v[180:181], off
	v_lshl_add_u64 v[180:181], v[186:187], 0, s[20:21]
	s_mov_b32 m0, s89
	s_nop 0
	global_load_lds_dwordx4 v[180:181], off
	s_waitcnt vmcnt(8)
	s_waitcnt lgkmcnt(0)
	s_setprio 1
	s_barrier
	v_mfma_f32_16x16x128_f8f6f4 v[94:97], v[18:25], v[192:199], v[94:97]
	v_mfma_f32_16x16x128_f8f6f4 v[90:93], v[26:33], v[192:199], v[90:93]
	v_mfma_f32_16x16x128_f8f6f4 v[58:61], v[10:17], v[192:199], v[58:61]
	v_mfma_f32_16x16x128_f8f6f4 v[62:65], v[2:9], v[192:199], v[62:65]
	v_mfma_f32_16x16x128_f8f6f4 v[54:57], v[2:9], v[200:207], v[54:57]
	v_mfma_f32_16x16x128_f8f6f4 v[50:53], v[10:17], v[200:207], v[50:53]
	v_mfma_f32_16x16x128_f8f6f4 v[82:85], v[26:33], v[200:207], v[82:85]
	v_mfma_f32_16x16x128_f8f6f4 v[86:89], v[18:25], v[200:207], v[86:89]
	s_setprio 0
	s_setprio 1
	v_mfma_f32_16x16x128_f8f6f4 v[78:81], v[18:25], v[208:215], v[78:81]
	v_mfma_f32_16x16x128_f8f6f4 v[74:77], v[26:33], v[208:215], v[74:77]
	v_mfma_f32_16x16x128_f8f6f4 v[42:45], v[10:17], v[208:215], v[42:45]
	v_mfma_f32_16x16x128_f8f6f4 v[46:49], v[2:9], v[208:215], v[46:49]
	v_mfma_f32_16x16x128_f8f6f4 v[38:41], v[2:9], v[216:223], v[38:41]
	v_mfma_f32_16x16x128_f8f6f4 v[34:37], v[10:17], v[216:223], v[34:37]
	v_mfma_f32_16x16x128_f8f6f4 v[66:69], v[26:33], v[216:223], v[66:69]
	v_mfma_f32_16x16x128_f8f6f4 v[70:73], v[18:25], v[216:223], v[70:73]
	s_barrier
	s_setprio 0
	s_add_u32 s72, s72, 0x80180
	s_addc_u32 s73, s73, 0
	s_add_u32 s8, s54, 0x200
	s_addc_u32 s9, s55, 0
	s_mov_b32 s62, 0
.LBB0_198:
	ds_read_b128 v[2:5], v190
	ds_read_b128 v[6:9], v190 offset:1024
	ds_read_b128 v[18:21], v190 offset:2048
	ds_read_b128 v[22:25], v190 offset:3072
	ds_read_b128 v[26:29], v190 offset:16384
	ds_read_b128 v[30:33], v190 offset:17408
	ds_read_b128 v[180:183], v190 offset:18432
	ds_read_b128 v[184:187], v190 offset:19456
	ds_read_b128 v[10:13], v191
	ds_read_b128 v[14:17], v191 offset:1024
	ds_read_b128 v[192:195], v191 offset:2048
	ds_read_b128 v[196:199], v191 offset:3072
	ds_read_b128 v[200:203], v191 offset:4096
	ds_read_b128 v[204:207], v191 offset:5120
	ds_read_b128 v[208:211], v191 offset:6144
	ds_read_b128 v[212:215], v191 offset:7168
	s_add_u32 s54, s72, 0xfff80080
	s_addc_u32 s55, s73, -1
	s_cmp_eq_u32 s62, 28
	s_cselect_b32 s75, s47, s55
	s_cselect_b32 s74, s70, s54
	s_cselect_b32 s55, s45, s9
	s_cselect_b32 s54, s71, s8
	s_mov_b32 m0, s92
	v_lshl_add_u64 v[216:217], s[72:73], 0, v[172:173]
	global_load_lds_dwordx4 v[216:217], off
	v_lshl_add_u64 v[216:217], s[72:73], 0, v[174:175]
	s_mov_b32 m0, s93
	s_nop 0
	global_load_lds_dwordx4 v[216:217], off
	s_waitcnt vmcnt(8)
	s_waitcnt lgkmcnt(0)
	s_setprio 1
	s_barrier
	v_mfma_f32_16x16x128_f8f6f4 v[158:161], v[2:9], v[10:17], v[158:161]
	v_mfma_f32_16x16x128_f8f6f4 v[154:157], v[18:25], v[10:17], v[154:157]
	v_mfma_f32_16x16x128_f8f6f4 v[122:125], v[180:187], v[10:17], v[122:125]
	v_mfma_f32_16x16x128_f8f6f4 v[126:129], v[26:33], v[10:17], v[126:129]
	v_mfma_f32_16x16x128_f8f6f4 v[118:121], v[26:33], v[192:199], v[118:121]
	v_mfma_f32_16x16x128_f8f6f4 v[114:117], v[180:187], v[192:199], v[114:117]
	v_mfma_f32_16x16x128_f8f6f4 v[146:149], v[18:25], v[192:199], v[146:149]
	v_mfma_f32_16x16x128_f8f6f4 v[150:153], v[2:9], v[192:199], v[150:153]
	s_setprio 0
	s_setprio 1
	v_mfma_f32_16x16x128_f8f6f4 v[142:145], v[2:9], v[200:207], v[142:145]
	v_mfma_f32_16x16x128_f8f6f4 v[138:141], v[18:25], v[200:207], v[138:141]
	v_mfma_f32_16x16x128_f8f6f4 v[106:109], v[180:187], v[200:207], v[106:109]
	v_mfma_f32_16x16x128_f8f6f4 v[110:113], v[26:33], v[200:207], v[110:113]
	v_mfma_f32_16x16x128_f8f6f4 v[102:105], v[26:33], v[208:215], v[102:105]
	v_mfma_f32_16x16x128_f8f6f4 v[98:101], v[180:187], v[208:215], v[98:101]
	v_mfma_f32_16x16x128_f8f6f4 v[130:133], v[18:25], v[208:215], v[130:133]
	v_mfma_f32_16x16x128_f8f6f4 v[134:137], v[2:9], v[208:215], v[134:137]
	s_barrier
	s_setprio 0
	ds_read_b128 v[192:195], v191 offset:16384
	ds_read_b128 v[196:199], v191 offset:17408
	ds_read_b128 v[200:203], v191 offset:18432
	ds_read_b128 v[204:207], v191 offset:19456
	ds_read_b128 v[208:211], v191 offset:20480
	ds_read_b128 v[212:215], v191 offset:21504
	ds_read_b128 v[216:219], v191 offset:22528
	ds_read_b128 v[220:223], v191 offset:23552
	s_mov_b32 m0, s77
	v_lshl_add_u64 v[10:11], s[54:55], 0, v[166:167]
	s_add_u32 vcc_lo, s54, 0x80000
	global_load_lds_dwordx4 v[10:11], off
	v_lshl_add_u64 v[12:13], s[54:55], 0, v[170:171]
	s_mov_b32 m0, s78
	s_addc_u32 vcc_hi, s55, 0
	global_load_lds_dwordx4 v[12:13], off
	v_lshl_add_u64 v[14:15], vcc, 0, v[166:167]
	s_mov_b32 m0, s79
	v_lshl_add_u64 v[16:17], s[74:75], 0, v[168:169]
	global_load_lds_dwordx4 v[14:15], off
	v_lshl_add_u64 v[14:15], vcc, 0, v[170:171]
	s_mov_b32 m0, s80
	s_nop 0
	global_load_lds_dwordx4 v[14:15], off
	v_lshl_add_u64 v[14:15], s[74:75], 0, v[164:165]
	s_mov_b32 m0, s53
	s_nop 0
	global_load_lds_dwordx4 v[14:15], off
	s_mov_b32 m0, s81
	s_nop 0
	global_load_lds_dwordx4 v[16:17], off
	s_waitcnt vmcnt(8)
	s_waitcnt lgkmcnt(0)
	s_setprio 1
	s_barrier
	v_mfma_f32_16x16x128_f8f6f4 v[94:97], v[2:9], v[192:199], v[94:97]
	v_mfma_f32_16x16x128_f8f6f4 v[90:93], v[18:25], v[192:199], v[90:93]
	v_mfma_f32_16x16x128_f8f6f4 v[58:61], v[180:187], v[192:199], v[58:61]
	v_mfma_f32_16x16x128_f8f6f4 v[62:65], v[26:33], v[192:199], v[62:65]
	v_mfma_f32_16x16x128_f8f6f4 v[54:57], v[26:33], v[200:207], v[54:57]
	v_mfma_f32_16x16x128_f8f6f4 v[50:53], v[180:187], v[200:207], v[50:53]
	v_mfma_f32_16x16x128_f8f6f4 v[82:85], v[18:25], v[200:207], v[82:85]
	v_mfma_f32_16x16x128_f8f6f4 v[86:89], v[2:9], v[200:207], v[86:89]
	s_setprio 0
	s_setprio 1
	v_mfma_f32_16x16x128_f8f6f4 v[78:81], v[2:9], v[208:215], v[78:81]
	v_mfma_f32_16x16x128_f8f6f4 v[74:77], v[18:25], v[208:215], v[74:77]
	v_mfma_f32_16x16x128_f8f6f4 v[42:45], v[180:187], v[208:215], v[42:45]
	v_mfma_f32_16x16x128_f8f6f4 v[46:49], v[26:33], v[208:215], v[46:49]
	v_mfma_f32_16x16x128_f8f6f4 v[38:41], v[26:33], v[216:223], v[38:41]
	v_mfma_f32_16x16x128_f8f6f4 v[34:37], v[180:187], v[216:223], v[34:37]
	v_mfma_f32_16x16x128_f8f6f4 v[66:69], v[18:25], v[216:223], v[66:69]
	v_mfma_f32_16x16x128_f8f6f4 v[70:73], v[2:9], v[216:223], v[70:73]
	s_barrier
	s_setprio 0
	ds_read_b128 v[18:21], v190 offset:32768
	ds_read_b128 v[22:25], v190 offset:33792
	ds_read_b128 v[26:29], v190 offset:34816
	ds_read_b128 v[30:33], v190 offset:35840
	ds_read_b128 v[2:5], v190 offset:49152
	ds_read_b128 v[6:9], v190 offset:50176
	ds_read_b128 v[180:183], v190 offset:51200
	ds_read_b128 v[184:187], v190 offset:52224
	ds_read_b128 v[192:195], v191 offset:32768
	ds_read_b128 v[196:199], v191 offset:33792
	ds_read_b128 v[200:203], v191 offset:34816
	ds_read_b128 v[204:207], v191 offset:35840
	ds_read_b128 v[208:211], v191 offset:36864
	ds_read_b128 v[212:215], v191 offset:37888
	ds_read_b128 v[216:219], v191 offset:38912
	ds_read_b128 v[220:223], v191 offset:39936
	s_add_u32 s74, s74, 0x80000
	s_addc_u32 s75, s75, 0
	s_mov_b32 m0, s82
	v_lshl_add_u64 v[224:225], s[74:75], 0, v[164:165]
	global_load_lds_dwordx4 v[224:225], off
	v_lshl_add_u64 v[224:225], s[74:75], 0, v[168:169]
	s_mov_b32 m0, s83
	s_nop 0
	global_load_lds_dwordx4 v[224:225], off
	s_waitcnt vmcnt(8)
	s_waitcnt lgkmcnt(0)
	s_setprio 1
	s_barrier
	v_mfma_f32_16x16x128_f8f6f4 v[158:161], v[18:25], v[192:199], v[158:161]
	v_mfma_f32_16x16x128_f8f6f4 v[154:157], v[26:33], v[192:199], v[154:157]
	v_mfma_f32_16x16x128_f8f6f4 v[122:125], v[180:187], v[192:199], v[122:125]
	v_mfma_f32_16x16x128_f8f6f4 v[126:129], v[2:9], v[192:199], v[126:129]
	v_mfma_f32_16x16x128_f8f6f4 v[118:121], v[2:9], v[200:207], v[118:121]
	v_mfma_f32_16x16x128_f8f6f4 v[114:117], v[180:187], v[200:207], v[114:117]
	v_mfma_f32_16x16x128_f8f6f4 v[146:149], v[26:33], v[200:207], v[146:149]
	v_mfma_f32_16x16x128_f8f6f4 v[150:153], v[18:25], v[200:207], v[150:153]
	s_setprio 0
	s_setprio 1
	v_mfma_f32_16x16x128_f8f6f4 v[142:145], v[18:25], v[208:215], v[142:145]
	v_mfma_f32_16x16x128_f8f6f4 v[138:141], v[26:33], v[208:215], v[138:141]
	v_mfma_f32_16x16x128_f8f6f4 v[106:109], v[180:187], v[208:215], v[106:109]
	v_mfma_f32_16x16x128_f8f6f4 v[110:113], v[2:9], v[208:215], v[110:113]
	v_mfma_f32_16x16x128_f8f6f4 v[102:105], v[2:9], v[216:223], v[102:105]
	v_mfma_f32_16x16x128_f8f6f4 v[98:101], v[180:187], v[216:223], v[98:101]
	v_mfma_f32_16x16x128_f8f6f4 v[130:133], v[26:33], v[216:223], v[130:133]
	v_mfma_f32_16x16x128_f8f6f4 v[134:137], v[18:25], v[216:223], v[134:137]
	s_barrier
	s_setprio 0
	ds_read_b128 v[192:195], v191 offset:49152
	ds_read_b128 v[196:199], v191 offset:50176
	ds_read_b128 v[200:203], v191 offset:51200
	ds_read_b128 v[204:207], v191 offset:52224
	ds_read_b128 v[208:211], v191 offset:53248
	ds_read_b128 v[212:215], v191 offset:54272
	ds_read_b128 v[216:219], v191 offset:55296
	ds_read_b128 v[220:223], v191 offset:56320
	s_mov_b32 m0, s86
	v_lshl_add_u64 v[10:11], v[10:11], 0, s[4:5]
	s_add_u32 s54, s54, 0x80080
	global_load_lds_dwordx4 v[10:11], off
	v_lshl_add_u64 v[10:11], v[12:13], 0, s[4:5]
	s_mov_b32 m0, s87
	s_addc_u32 s55, s55, 0
	global_load_lds_dwordx4 v[10:11], off
	v_lshl_add_u64 v[10:11], s[54:55], 0, v[166:167]
	s_mov_b32 m0, s90
	s_nop 0
	global_load_lds_dwordx4 v[10:11], off
	v_lshl_add_u64 v[10:11], s[54:55], 0, v[170:171]
	s_mov_b32 m0, s91
	s_nop 0
	global_load_lds_dwordx4 v[10:11], off
	v_lshl_add_u64 v[10:11], v[14:15], 0, s[4:5]
	s_mov_b32 m0, s88
	s_nop 0
	global_load_lds_dwordx4 v[10:11], off
	v_lshl_add_u64 v[10:11], v[16:17], 0, s[4:5]
	s_mov_b32 m0, s89
	s_nop 0
	global_load_lds_dwordx4 v[10:11], off
	s_waitcnt vmcnt(8)
	s_waitcnt lgkmcnt(0)
	s_setprio 1
	s_barrier
	v_mfma_f32_16x16x128_f8f6f4 v[94:97], v[18:25], v[192:199], v[94:97]
	v_mfma_f32_16x16x128_f8f6f4 v[90:93], v[26:33], v[192:199], v[90:93]
	v_mfma_f32_16x16x128_f8f6f4 v[58:61], v[180:187], v[192:199], v[58:61]
	v_mfma_f32_16x16x128_f8f6f4 v[62:65], v[2:9], v[192:199], v[62:65]
	v_mfma_f32_16x16x128_f8f6f4 v[54:57], v[2:9], v[200:207], v[54:57]
	v_mfma_f32_16x16x128_f8f6f4 v[50:53], v[180:187], v[200:207], v[50:53]
	v_mfma_f32_16x16x128_f8f6f4 v[82:85], v[26:33], v[200:207], v[82:85]
	v_mfma_f32_16x16x128_f8f6f4 v[86:89], v[18:25], v[200:207], v[86:89]
	s_setprio 0
	s_setprio 1
	v_mfma_f32_16x16x128_f8f6f4 v[78:81], v[18:25], v[208:215], v[78:81]
	v_mfma_f32_16x16x128_f8f6f4 v[74:77], v[26:33], v[208:215], v[74:77]
	v_mfma_f32_16x16x128_f8f6f4 v[42:45], v[180:187], v[208:215], v[42:45]
	v_mfma_f32_16x16x128_f8f6f4 v[46:49], v[2:9], v[208:215], v[46:49]
	v_mfma_f32_16x16x128_f8f6f4 v[38:41], v[2:9], v[216:223], v[38:41]
	v_mfma_f32_16x16x128_f8f6f4 v[34:37], v[180:187], v[216:223], v[34:37]
	v_mfma_f32_16x16x128_f8f6f4 v[66:69], v[26:33], v[216:223], v[66:69]
	v_mfma_f32_16x16x128_f8f6f4 v[70:73], v[18:25], v[216:223], v[70:73]
	s_barrier
	s_setprio 0
	s_add_i32 s62, s62, 2
	s_add_u32 s72, s72, 0x100
	s_addc_u32 s73, s73, 0
	s_add_u32 s8, s8, 0x100
	s_addc_u32 s9, s9, 0
	s_cmp_gt_u32 s62, 29
	s_cbranch_scc0 .LBB0_198
	s_and_b64 vcc, exec, s[6:7]
	s_cbranch_vccz .LBB0_201
	s_barrier

.LBB0_282:
	ds_read_b128 v[2:5], v187
	ds_read_b128 v[6:9], v187 offset:1024
	ds_read_b128 v[174:177], v187 offset:2048
	ds_read_b128 v[178:181], v187 offset:3072
	ds_read_b128 v[190:193], v187 offset:16384
	ds_read_b128 v[194:197], v187 offset:17408
	ds_read_b128 v[198:201], v187 offset:18432
	ds_read_b128 v[202:205], v187 offset:19456
	ds_read_b128 v[206:209], v188
	ds_read_b128 v[210:213], v188 offset:1024
	ds_read_b128 v[214:217], v188 offset:2048
	ds_read_b128 v[218:221], v188 offset:3072
	ds_read_b128 v[222:225], v188 offset:4096
	ds_read_b128 v[226:229], v188 offset:5120
	ds_read_b128 v[230:233], v188 offset:6144
	ds_read_b128 v[234:237], v188 offset:7168
	s_add_u32 s49, s52, 0x100
	s_addc_u32 s71, s53, 0
	s_and_b64 s[62:63], s[54:55], exec
	s_cselect_b32 s73, s1, s71
	s_cselect_b32 s72, s0, s49
	s_add_u32 s49, s50, 0x100
	s_addc_u32 s62, s51, 0
	s_and_b64 s[54:55], s[54:55], exec
	s_cselect_b32 s55, s5, s62
	s_cselect_b32 s54, s4, s49
	s_add_u32 s62, s52, 0x158080
	s_addc_u32 s63, s53, 0
	s_add_i32 s49, s33, 0xc000
	v_lshl_add_u64 v[182:183], s[62:63], 0, v[154:155]
	s_mov_b32 m0, s49
	s_add_i32 s71, s33, 0xe000
	global_load_lds_dwordx4 v[182:183], off
	v_lshl_add_u64 v[182:183], s[62:63], 0, v[158:159]
	s_mov_b32 m0, s71
	s_nop 0
	global_load_lds_dwordx4 v[182:183], off
	s_waitcnt vmcnt(8)
	s_waitcnt lgkmcnt(0)
	s_setprio 1
	s_barrier
	v_mfma_f32_16x16x128_f8f6f4 v[134:137], v[2:9], v[206:213], 0
	v_mfma_f32_16x16x128_f8f6f4 v[130:133], v[174:181], v[206:213], 0
	v_mfma_f32_16x16x128_f8f6f4 v[98:101], v[198:205], v[206:213], 0
	v_mfma_f32_16x16x128_f8f6f4 v[102:105], v[190:197], v[206:213], 0
	v_mfma_f32_16x16x128_f8f6f4 v[94:97], v[190:197], v[214:221], 0
	v_mfma_f32_16x16x128_f8f6f4 v[90:93], v[198:205], v[214:221], 0
	v_mfma_f32_16x16x128_f8f6f4 v[122:125], v[174:181], v[214:221], 0
	v_mfma_f32_16x16x128_f8f6f4 v[126:129], v[2:9], v[214:221], 0
	s_setprio 0
	s_setprio 1
	v_mfma_f32_16x16x128_f8f6f4 v[118:121], v[2:9], v[222:229], 0
	v_mfma_f32_16x16x128_f8f6f4 v[114:117], v[174:181], v[222:229], 0
	v_mfma_f32_16x16x128_f8f6f4 v[82:85], v[198:205], v[222:229], 0
	v_mfma_f32_16x16x128_f8f6f4 v[86:89], v[190:197], v[222:229], 0
	v_mfma_f32_16x16x128_f8f6f4 v[78:81], v[190:197], v[230:237], 0
	v_mfma_f32_16x16x128_f8f6f4 v[74:77], v[198:205], v[230:237], 0
	v_mfma_f32_16x16x128_f8f6f4 v[106:109], v[174:181], v[230:237], 0
	v_mfma_f32_16x16x128_f8f6f4 v[110:113], v[2:9], v[230:237], 0
	s_barrier
	s_setprio 0
	ds_read_b128 v[206:209], v188 offset:16384
	ds_read_b128 v[210:213], v188 offset:17408
	ds_read_b128 v[214:217], v188 offset:18432
	ds_read_b128 v[218:221], v188 offset:19456
	ds_read_b128 v[222:225], v188 offset:20480
	ds_read_b128 v[226:229], v188 offset:21504
	ds_read_b128 v[230:233], v188 offset:22528
	ds_read_b128 v[234:237], v188 offset:23552
	s_mov_b32 m0, s47
	v_lshl_add_u64 v[182:183], s[54:55], 0, v[156:157]
	s_add_u32 s62, s54, 0x158000
	global_load_lds_dwordx4 v[182:183], off
	v_lshl_add_u64 v[238:239], s[54:55], 0, v[160:161]
	s_mov_b32 m0, s68
	s_addc_u32 s63, s55, 0
	global_load_lds_dwordx4 v[238:239], off
	v_lshl_add_u64 v[242:243], s[62:63], 0, v[156:157]
	s_mov_b32 m0, s69
	v_lshl_add_u64 v[244:245], s[72:73], 0, v[158:159]
	global_load_lds_dwordx4 v[242:243], off
	v_lshl_add_u64 v[242:243], s[62:63], 0, v[160:161]
	s_mov_b32 m0, s74
	s_nop 0
	global_load_lds_dwordx4 v[242:243], off
	v_lshl_add_u64 v[242:243], s[72:73], 0, v[154:155]
	s_mov_b32 m0, s33
	s_nop 0
	global_load_lds_dwordx4 v[242:243], off
	s_mov_b32 m0, s75
	s_nop 0
	global_load_lds_dwordx4 v[244:245], off
	s_waitcnt vmcnt(8)
	s_waitcnt lgkmcnt(0)
	s_setprio 1
	s_barrier
	v_mfma_f32_16x16x128_f8f6f4 v[70:73], v[2:9], v[206:213], 0
	v_mfma_f32_16x16x128_f8f6f4 v[66:69], v[174:181], v[206:213], 0
	v_mfma_f32_16x16x128_f8f6f4 v[34:37], v[198:205], v[206:213], 0
	v_mfma_f32_16x16x128_f8f6f4 v[38:41], v[190:197], v[206:213], 0
	v_mfma_f32_16x16x128_f8f6f4 v[30:33], v[190:197], v[214:221], 0
	v_mfma_f32_16x16x128_f8f6f4 v[26:29], v[198:205], v[214:221], 0
	v_mfma_f32_16x16x128_f8f6f4 v[58:61], v[174:181], v[214:221], 0
	v_mfma_f32_16x16x128_f8f6f4 v[62:65], v[2:9], v[214:221], 0
	s_setprio 0
	s_setprio 1
	v_mfma_f32_16x16x128_f8f6f4 v[54:57], v[2:9], v[222:229], 0
	v_mfma_f32_16x16x128_f8f6f4 v[50:53], v[174:181], v[222:229], 0
	v_mfma_f32_16x16x128_f8f6f4 v[18:21], v[198:205], v[222:229], 0
	v_mfma_f32_16x16x128_f8f6f4 v[22:25], v[190:197], v[222:229], 0
	v_mfma_f32_16x16x128_f8f6f4 v[14:17], v[190:197], v[230:237], 0
	v_mfma_f32_16x16x128_f8f6f4 v[10:13], v[198:205], v[230:237], 0
	v_mfma_f32_16x16x128_f8f6f4 v[42:45], v[174:181], v[230:237], 0
	v_mfma_f32_16x16x128_f8f6f4 v[46:49], v[2:9], v[230:237], 0
	s_barrier
	s_setprio 0
	ds_read_b128 v[2:5], v187 offset:32768
	ds_read_b128 v[6:9], v187 offset:33792
	ds_read_b128 v[174:177], v187 offset:34816
	ds_read_b128 v[178:181], v187 offset:35840
	ds_read_b128 v[190:193], v187 offset:49152
	ds_read_b128 v[194:197], v187 offset:50176
	ds_read_b128 v[198:201], v187 offset:51200
	ds_read_b128 v[202:205], v187 offset:52224
	ds_read_b128 v[206:209], v188 offset:32768
	ds_read_b128 v[210:213], v188 offset:33792
	ds_read_b128 v[214:217], v188 offset:34816
	ds_read_b128 v[218:221], v188 offset:35840
	ds_read_b128 v[222:225], v188 offset:36864
	ds_read_b128 v[226:229], v188 offset:37888
	ds_read_b128 v[230:233], v188 offset:38912
	ds_read_b128 v[234:237], v188 offset:39936
	s_add_u32 s62, s72, 0x158000
	s_addc_u32 s63, s73, 0
	s_mov_b32 m0, s76
	v_lshl_add_u64 v[246:247], s[62:63], 0, v[154:155]
	global_load_lds_dwordx4 v[246:247], off
	v_lshl_add_u64 v[246:247], s[62:63], 0, v[158:159]
	s_mov_b32 m0, s77
	s_nop 0
	global_load_lds_dwordx4 v[246:247], off
	s_waitcnt vmcnt(8)
	s_waitcnt lgkmcnt(0)
	s_setprio 1
	s_barrier
	v_mfma_f32_16x16x128_f8f6f4 v[134:137], v[2:9], v[206:213], v[134:137]
	v_mfma_f32_16x16x128_f8f6f4 v[130:133], v[174:181], v[206:213], v[130:133]
	v_mfma_f32_16x16x128_f8f6f4 v[98:101], v[198:205], v[206:213], v[98:101]
	v_mfma_f32_16x16x128_f8f6f4 v[102:105], v[190:197], v[206:213], v[102:105]
	v_mfma_f32_16x16x128_f8f6f4 v[94:97], v[190:197], v[214:221], v[94:97]
	v_mfma_f32_16x16x128_f8f6f4 v[90:93], v[198:205], v[214:221], v[90:93]
	v_mfma_f32_16x16x128_f8f6f4 v[122:125], v[174:181], v[214:221], v[122:125]
	v_mfma_f32_16x16x128_f8f6f4 v[126:129], v[2:9], v[214:221], v[126:129]
	s_setprio 0
	s_setprio 1
	v_mfma_f32_16x16x128_f8f6f4 v[118:121], v[2:9], v[222:229], v[118:121]
	v_mfma_f32_16x16x128_f8f6f4 v[114:117], v[174:181], v[222:229], v[114:117]
	v_mfma_f32_16x16x128_f8f6f4 v[82:85], v[198:205], v[222:229], v[82:85]
	v_mfma_f32_16x16x128_f8f6f4 v[86:89], v[190:197], v[222:229], v[86:89]
	v_mfma_f32_16x16x128_f8f6f4 v[78:81], v[190:197], v[230:237], v[78:81]
	v_mfma_f32_16x16x128_f8f6f4 v[74:77], v[198:205], v[230:237], v[74:77]
	v_mfma_f32_16x16x128_f8f6f4 v[106:109], v[174:181], v[230:237], v[106:109]
	v_mfma_f32_16x16x128_f8f6f4 v[110:113], v[2:9], v[230:237], v[110:113]
	s_barrier
	s_setprio 0
	ds_read_b128 v[206:209], v188 offset:49152
	ds_read_b128 v[210:213], v188 offset:50176
	ds_read_b128 v[214:217], v188 offset:51200
	ds_read_b128 v[218:221], v188 offset:52224
	ds_read_b128 v[222:225], v188 offset:53248
	ds_read_b128 v[226:229], v188 offset:54272
	ds_read_b128 v[230:233], v188 offset:55296
	ds_read_b128 v[234:237], v188 offset:56320
	s_mov_b32 m0, s83
	v_lshl_add_u64 v[182:183], v[182:183], 0, s[26:27]
	s_add_u32 s54, s54, 0x158080
	global_load_lds_dwordx4 v[182:183], off
	v_lshl_add_u64 v[182:183], v[238:239], 0, s[26:27]
	s_mov_b32 m0, s84
	s_addc_u32 s55, s55, 0
	global_load_lds_dwordx4 v[182:183], off
	v_lshl_add_u64 v[182:183], s[54:55], 0, v[156:157]
	s_mov_b32 m0, s87
	s_nop 0
	global_load_lds_dwordx4 v[182:183], off
	v_lshl_add_u64 v[182:183], s[54:55], 0, v[160:161]
	s_mov_b32 m0, s88
	s_nop 0
	global_load_lds_dwordx4 v[182:183], off
	v_lshl_add_u64 v[182:183], v[242:243], 0, s[26:27]
	s_mov_b32 m0, s85
	s_nop 0
	global_load_lds_dwordx4 v[182:183], off
	v_lshl_add_u64 v[182:183], v[244:245], 0, s[26:27]
	s_mov_b32 m0, s86
	s_nop 0
	global_load_lds_dwordx4 v[182:183], off
	s_waitcnt vmcnt(8)
	s_waitcnt lgkmcnt(0)
	s_setprio 1
	s_barrier
	v_mfma_f32_16x16x128_f8f6f4 v[70:73], v[2:9], v[206:213], v[70:73]
	v_mfma_f32_16x16x128_f8f6f4 v[66:69], v[174:181], v[206:213], v[66:69]
	v_mfma_f32_16x16x128_f8f6f4 v[34:37], v[198:205], v[206:213], v[34:37]
	v_mfma_f32_16x16x128_f8f6f4 v[38:41], v[190:197], v[206:213], v[38:41]
	v_mfma_f32_16x16x128_f8f6f4 v[30:33], v[190:197], v[214:221], v[30:33]
	v_mfma_f32_16x16x128_f8f6f4 v[26:29], v[198:205], v[214:221], v[26:29]
	v_mfma_f32_16x16x128_f8f6f4 v[58:61], v[174:181], v[214:221], v[58:61]
	v_mfma_f32_16x16x128_f8f6f4 v[62:65], v[2:9], v[214:221], v[62:65]
	s_setprio 0
	s_setprio 1
	v_mfma_f32_16x16x128_f8f6f4 v[54:57], v[2:9], v[222:229], v[54:57]
	v_mfma_f32_16x16x128_f8f6f4 v[50:53], v[174:181], v[222:229], v[50:53]
	v_mfma_f32_16x16x128_f8f6f4 v[18:21], v[198:205], v[222:229], v[18:21]
	v_mfma_f32_16x16x128_f8f6f4 v[22:25], v[190:197], v[222:229], v[22:25]
	v_mfma_f32_16x16x128_f8f6f4 v[14:17], v[190:197], v[230:237], v[14:17]
	v_mfma_f32_16x16x128_f8f6f4 v[10:13], v[198:205], v[230:237], v[10:13]
	v_mfma_f32_16x16x128_f8f6f4 v[42:45], v[174:181], v[230:237], v[42:45]
	v_mfma_f32_16x16x128_f8f6f4 v[46:49], v[2:9], v[230:237], v[46:49]
	s_barrier
	s_setprio 0
	s_cmp_lt_u32 s95, 3
	s_cbranch_scc1 .LBB0_287
	s_add_u32 s54, s79, s9
	s_addc_u32 s55, s80, s8
	s_add_u32 s52, s52, 0x158180
	s_addc_u32 s53, s53, 0
	s_add_u32 s8, s50, 0x200
	v_lshl_add_u64 v[174:175], v[172:173], 2, s[54:55]
	s_addc_u32 s9, s51, 0
	s_mov_b32 s72, 4
	s_cmp_eq_u32 s95, s72
	s_cselect_b64 s[50:51], -1, 0
	s_cmp_lg_u32 s95, s72
	s_cbranch_scc1 .LBB0_285

.LBB0_285:
	ds_read_b128 v[2:5], v187
	ds_read_b128 v[6:9], v187 offset:1024
	ds_read_b128 v[190:193], v187 offset:2048
	ds_read_b128 v[194:197], v187 offset:3072
	ds_read_b128 v[198:201], v187 offset:16384
	ds_read_b128 v[202:205], v187 offset:17408
	ds_read_b128 v[206:209], v187 offset:18432
	ds_read_b128 v[210:213], v187 offset:19456
	ds_read_b128 v[176:179], v188
	ds_read_b128 v[180:183], v188 offset:1024
	ds_read_b128 v[214:217], v188 offset:2048
	ds_read_b128 v[218:221], v188 offset:3072
	ds_read_b128 v[222:225], v188 offset:4096
	ds_read_b128 v[226:229], v188 offset:5120
	ds_read_b128 v[230:233], v188 offset:6144
	ds_read_b128 v[234:237], v188 offset:7168
	s_add_u32 s54, s52, 0xffea8080
	s_addc_u32 s55, s53, -1
	s_and_b64 s[50:51], s[50:51], exec
	s_cselect_b32 s50, s4, s8
	s_cselect_b32 s55, s1, s55
	s_cselect_b32 s54, s0, s54
	s_cselect_b32 s51, s5, s9
	s_mov_b32 m0, s49
	v_lshl_add_u64 v[238:239], s[52:53], 0, v[162:163]
	global_load_lds_dwordx4 v[238:239], off
	v_lshl_add_u64 v[238:239], s[52:53], 0, v[164:165]
	s_mov_b32 m0, s71
	s_nop 0
	global_load_lds_dwordx4 v[238:239], off
	s_waitcnt vmcnt(8)
	s_waitcnt lgkmcnt(0)
	s_setprio 1
	s_barrier
	v_mfma_f32_16x16x128_f8f6f4 v[134:137], v[2:9], v[176:183], v[134:137]
	v_mfma_f32_16x16x128_f8f6f4 v[130:133], v[190:197], v[176:183], v[130:133]
	v_mfma_f32_16x16x128_f8f6f4 v[98:101], v[206:213], v[176:183], v[98:101]
	v_mfma_f32_16x16x128_f8f6f4 v[102:105], v[198:205], v[176:183], v[102:105]
	v_mfma_f32_16x16x128_f8f6f4 v[94:97], v[198:205], v[214:221], v[94:97]
	v_mfma_f32_16x16x128_f8f6f4 v[90:93], v[206:213], v[214:221], v[90:93]
	v_mfma_f32_16x16x128_f8f6f4 v[122:125], v[190:197], v[214:221], v[122:125]
	v_mfma_f32_16x16x128_f8f6f4 v[126:129], v[2:9], v[214:221], v[126:129]
	s_setprio 0
	s_setprio 1
	v_mfma_f32_16x16x128_f8f6f4 v[118:121], v[2:9], v[222:229], v[118:121]
	v_mfma_f32_16x16x128_f8f6f4 v[114:117], v[190:197], v[222:229], v[114:117]
	v_mfma_f32_16x16x128_f8f6f4 v[82:85], v[206:213], v[222:229], v[82:85]
	v_mfma_f32_16x16x128_f8f6f4 v[86:89], v[198:205], v[222:229], v[86:89]
	v_mfma_f32_16x16x128_f8f6f4 v[78:81], v[198:205], v[230:237], v[78:81]
	v_mfma_f32_16x16x128_f8f6f4 v[74:77], v[206:213], v[230:237], v[74:77]
	v_mfma_f32_16x16x128_f8f6f4 v[106:109], v[190:197], v[230:237], v[106:109]
	v_mfma_f32_16x16x128_f8f6f4 v[110:113], v[2:9], v[230:237], v[110:113]
	s_barrier
	s_setprio 0
	ds_read_b128 v[214:217], v188 offset:16384
	ds_read_b128 v[218:221], v188 offset:17408
	ds_read_b128 v[222:225], v188 offset:18432
	ds_read_b128 v[226:229], v188 offset:19456
	ds_read_b128 v[230:233], v188 offset:20480
	ds_read_b128 v[234:237], v188 offset:21504
	ds_read_b128 v[242:245], v188 offset:22528
	ds_read_b128 v[246:249], v188 offset:23552
	s_mov_b32 m0, s47
	v_lshl_add_u64 v[176:177], s[50:51], 0, v[156:157]
	s_add_u32 s62, s50, 0x158000
	global_load_lds_dwordx4 v[176:177], off
	v_lshl_add_u64 v[178:179], s[50:51], 0, v[160:161]
	s_mov_b32 m0, s68
	s_addc_u32 s63, s51, 0
	global_load_lds_dwordx4 v[178:179], off
	v_lshl_add_u64 v[180:181], s[62:63], 0, v[156:157]
	s_mov_b32 m0, s69
	v_lshl_add_u64 v[182:183], s[54:55], 0, v[158:159]
	global_load_lds_dwordx4 v[180:181], off
	v_lshl_add_u64 v[180:181], s[62:63], 0, v[160:161]
	s_mov_b32 m0, s74
	s_nop 0
	global_load_lds_dwordx4 v[180:181], off
	v_lshl_add_u64 v[180:181], s[54:55], 0, v[154:155]
	s_mov_b32 m0, s33
	s_nop 0
	global_load_lds_dwordx4 v[180:181], off
	s_mov_b32 m0, s75
	s_nop 0
	global_load_lds_dwordx4 v[182:183], off
	s_waitcnt vmcnt(8)
	s_waitcnt lgkmcnt(0)
	s_setprio 1
	s_barrier
	v_mfma_f32_16x16x128_f8f6f4 v[70:73], v[2:9], v[214:221], v[70:73]
	v_mfma_f32_16x16x128_f8f6f4 v[66:69], v[190:197], v[214:221], v[66:69]
	v_mfma_f32_16x16x128_f8f6f4 v[34:37], v[206:213], v[214:221], v[34:37]
	v_mfma_f32_16x16x128_f8f6f4 v[38:41], v[198:205], v[214:221], v[38:41]
	v_mfma_f32_16x16x128_f8f6f4 v[30:33], v[198:205], v[222:229], v[30:33]
	v_mfma_f32_16x16x128_f8f6f4 v[26:29], v[206:213], v[222:229], v[26:29]
	v_mfma_f32_16x16x128_f8f6f4 v[58:61], v[190:197], v[222:229], v[58:61]
	v_mfma_f32_16x16x128_f8f6f4 v[62:65], v[2:9], v[222:229], v[62:65]
	s_setprio 0
	s_setprio 1
	v_mfma_f32_16x16x128_f8f6f4 v[54:57], v[2:9], v[230:237], v[54:57]
	v_mfma_f32_16x16x128_f8f6f4 v[50:53], v[190:197], v[230:237], v[50:53]
	v_mfma_f32_16x16x128_f8f6f4 v[18:21], v[206:213], v[230:237], v[18:21]
	v_mfma_f32_16x16x128_f8f6f4 v[22:25], v[198:205], v[230:237], v[22:25]
	v_mfma_f32_16x16x128_f8f6f4 v[14:17], v[198:205], v[242:249], v[14:17]
	v_mfma_f32_16x16x128_f8f6f4 v[10:13], v[206:213], v[242:249], v[10:13]
	v_mfma_f32_16x16x128_f8f6f4 v[42:45], v[190:197], v[242:249], v[42:45]
	v_mfma_f32_16x16x128_f8f6f4 v[46:49], v[2:9], v[242:249], v[46:49]
	s_barrier
	s_setprio 0
	ds_read_b128 v[190:193], v187 offset:32768
	ds_read_b128 v[194:197], v187 offset:33792
	ds_read_b128 v[198:201], v187 offset:34816
	ds_read_b128 v[202:205], v187 offset:35840
	ds_read_b128 v[2:5], v187 offset:49152
	ds_read_b128 v[6:9], v187 offset:50176
	ds_read_b128 v[206:209], v187 offset:51200
	ds_read_b128 v[210:213], v187 offset:52224
	ds_read_b128 v[214:217], v188 offset:32768
	ds_read_b128 v[218:221], v188 offset:33792
	ds_read_b128 v[222:225], v188 offset:34816
	ds_read_b128 v[226:229], v188 offset:35840
	ds_read_b128 v[230:233], v188 offset:36864
	ds_read_b128 v[234:237], v188 offset:37888
	ds_read_b128 v[242:245], v188 offset:38912
	ds_read_b128 v[246:249], v188 offset:39936
	s_add_u32 s54, s54, 0x158000
	s_addc_u32 s55, s55, 0
	s_mov_b32 m0, s76
	v_lshl_add_u64 v[238:239], s[54:55], 0, v[154:155]
	global_load_lds_dwordx4 v[238:239], off
	v_lshl_add_u64 v[238:239], s[54:55], 0, v[158:159]
	s_mov_b32 m0, s77
	s_nop 0
	global_load_lds_dwordx4 v[238:239], off
	s_waitcnt vmcnt(8)
	s_waitcnt lgkmcnt(0)
	s_setprio 1
	s_barrier
	v_mfma_f32_16x16x128_f8f6f4 v[134:137], v[190:197], v[214:221], v[134:137]
	v_mfma_f32_16x16x128_f8f6f4 v[130:133], v[198:205], v[214:221], v[130:133]
	v_mfma_f32_16x16x128_f8f6f4 v[98:101], v[206:213], v[214:221], v[98:101]
	v_mfma_f32_16x16x128_f8f6f4 v[102:105], v[2:9], v[214:221], v[102:105]
	v_mfma_f32_16x16x128_f8f6f4 v[94:97], v[2:9], v[222:229], v[94:97]
	v_mfma_f32_16x16x128_f8f6f4 v[90:93], v[206:213], v[222:229], v[90:93]
	v_mfma_f32_16x16x128_f8f6f4 v[122:125], v[198:205], v[222:229], v[122:125]
	v_mfma_f32_16x16x128_f8f6f4 v[126:129], v[190:197], v[222:229], v[126:129]
	s_setprio 0
	s_setprio 1
	v_mfma_f32_16x16x128_f8f6f4 v[118:121], v[190:197], v[230:237], v[118:121]
	v_mfma_f32_16x16x128_f8f6f4 v[114:117], v[198:205], v[230:237], v[114:117]
	v_mfma_f32_16x16x128_f8f6f4 v[82:85], v[206:213], v[230:237], v[82:85]
	v_mfma_f32_16x16x128_f8f6f4 v[86:89], v[2:9], v[230:237], v[86:89]
	v_mfma_f32_16x16x128_f8f6f4 v[78:81], v[2:9], v[242:249], v[78:81]
	v_mfma_f32_16x16x128_f8f6f4 v[74:77], v[206:213], v[242:249], v[74:77]
	v_mfma_f32_16x16x128_f8f6f4 v[106:109], v[198:205], v[242:249], v[106:109]
	v_mfma_f32_16x16x128_f8f6f4 v[110:113], v[190:197], v[242:249], v[110:113]
	s_barrier
	s_setprio 0
	ds_read_b128 v[214:217], v188 offset:49152
	ds_read_b128 v[218:221], v188 offset:50176
	ds_read_b128 v[222:225], v188 offset:51200
	ds_read_b128 v[226:229], v188 offset:52224
	ds_read_b128 v[230:233], v188 offset:53248
	ds_read_b128 v[234:237], v188 offset:54272
	ds_read_b128 v[242:245], v188 offset:55296
	ds_read_b128 v[246:249], v188 offset:56320
	s_mov_b32 m0, s83
	v_lshl_add_u64 v[176:177], v[176:177], 0, s[26:27]
	s_add_u32 s50, s50, 0x158080
	global_load_lds_dwordx4 v[176:177], off
	v_lshl_add_u64 v[176:177], v[178:179], 0, s[26:27]
	s_mov_b32 m0, s84
	s_addc_u32 s51, s51, 0
	global_load_lds_dwordx4 v[176:177], off
	v_lshl_add_u64 v[176:177], s[50:51], 0, v[156:157]
	s_mov_b32 m0, s87
	s_nop 0
	global_load_lds_dwordx4 v[176:177], off
	v_lshl_add_u64 v[176:177], s[50:51], 0, v[160:161]
	s_mov_b32 m0, s88
	s_nop 0
	global_load_lds_dwordx4 v[176:177], off
	v_lshl_add_u64 v[176:177], v[180:181], 0, s[26:27]
	s_mov_b32 m0, s85
	s_nop 0
	global_load_lds_dwordx4 v[176:177], off
	v_lshl_add_u64 v[176:177], v[182:183], 0, s[26:27]
	s_mov_b32 m0, s86
	s_nop 0
	global_load_lds_dwordx4 v[176:177], off
	s_waitcnt vmcnt(8)
	s_waitcnt lgkmcnt(0)
	s_setprio 1
	s_barrier
	v_mfma_f32_16x16x128_f8f6f4 v[70:73], v[190:197], v[214:221], v[70:73]
	v_mfma_f32_16x16x128_f8f6f4 v[66:69], v[198:205], v[214:221], v[66:69]
	v_mfma_f32_16x16x128_f8f6f4 v[34:37], v[206:213], v[214:221], v[34:37]
	v_mfma_f32_16x16x128_f8f6f4 v[38:41], v[2:9], v[214:221], v[38:41]
	v_mfma_f32_16x16x128_f8f6f4 v[30:33], v[2:9], v[222:229], v[30:33]
	v_mfma_f32_16x16x128_f8f6f4 v[26:29], v[206:213], v[222:229], v[26:29]
	v_mfma_f32_16x16x128_f8f6f4 v[58:61], v[198:205], v[222:229], v[58:61]
	v_mfma_f32_16x16x128_f8f6f4 v[62:65], v[190:197], v[222:229], v[62:65]
	s_setprio 0
	s_setprio 1
	v_mfma_f32_16x16x128_f8f6f4 v[54:57], v[190:197], v[230:237], v[54:57]
	v_mfma_f32_16x16x128_f8f6f4 v[50:53], v[198:205], v[230:237], v[50:53]
	v_mfma_f32_16x16x128_f8f6f4 v[18:21], v[206:213], v[230:237], v[18:21]
	v_mfma_f32_16x16x128_f8f6f4 v[22:25], v[2:9], v[230:237], v[22:25]
	v_mfma_f32_16x16x128_f8f6f4 v[14:17], v[2:9], v[242:249], v[14:17]
	v_mfma_f32_16x16x128_f8f6f4 v[10:13], v[206:213], v[242:249], v[10:13]
	v_mfma_f32_16x16x128_f8f6f4 v[42:45], v[198:205], v[242:249], v[42:45]
	v_mfma_f32_16x16x128_f8f6f4 v[46:49], v[190:197], v[242:249], v[46:49]
	s_barrier
	s_setprio 0
	s_add_i32 s50, s72, 2
	s_add_u32 s52, s52, 0x100
	s_addc_u32 s53, s53, 0
	s_add_u32 s8, s8, 0x100
	s_addc_u32 s9, s9, 0
	s_cmp_ge_i32 s72, s95
	s_cbranch_scc1 .LBB0_287
	s_mov_b32 s72, s50
	s_cmp_eq_u32 s95, s72
	s_cselect_b64 s[50:51], -1, 0
	s_cmp_lg_u32 s95, s72
	s_cbranch_scc0 .LBB0_284
	s_branch .LBB0_285

.LBB0_437:
	ds_read_b128 v[18:21], v200
	ds_read_b128 v[22:25], v200 offset:1024
	ds_read_b128 v[26:29], v200 offset:2048
	ds_read_b128 v[30:33], v200 offset:3072
	ds_read_b128 v[2:5], v200 offset:16384
	ds_read_b128 v[6:9], v200 offset:17408
	ds_read_b128 v[10:13], v200 offset:18432
	ds_read_b128 v[14:17], v200 offset:19456
	ds_read_b128 v[180:183], v201
	ds_read_b128 v[184:187], v201 offset:1024
	ds_read_b128 v[202:205], v201 offset:2048
	ds_read_b128 v[206:209], v201 offset:3072
	ds_read_b128 v[210:213], v201 offset:4096
	ds_read_b128 v[214:217], v201 offset:5120
	ds_read_b128 v[218:221], v201 offset:6144
	ds_read_b128 v[222:225], v201 offset:7168
	s_ashr_i32 s47, s46, 31
	s_lshl_b64 s[8:9], s[46:47], 20
	s_add_u32 s48, s12, s8
	s_addc_u32 s49, s13, s9
	s_and_b64 s[8:9], s[2:3], exec
	s_cselect_b32 s47, s49, s73
	s_cselect_b32 s71, s48, s72
	s_ashr_i32 s45, s44, 31
	s_lshl_b64 s[8:9], s[44:45], 20
	s_add_u32 s50, s39, s8
	s_addc_u32 s51, s76, s9
	s_and_b64 s[8:9], s[2:3], exec
	s_cselect_b32 s45, s51, s55
	s_cselect_b32 s94, s50, s54
	s_add_u32 s8, s72, 0x80080
	s_addc_u32 s9, s73, 0
	s_mov_b32 m0, s33
	v_lshl_add_u64 v[226:227], s[8:9], 0, v[162:163]
	global_load_lds_dwordx4 v[226:227], off
	v_lshl_add_u64 v[226:227], s[8:9], 0, v[166:167]
	s_mov_b32 m0, s93
	s_nop 0
	global_load_lds_dwordx4 v[226:227], off
	s_waitcnt vmcnt(8)
	s_waitcnt lgkmcnt(0)
	s_setprio 1
	s_barrier
	v_mfma_f32_16x16x128_f8f6f4 v[158:161], v[18:25], v[180:187], 0
	v_mfma_f32_16x16x128_f8f6f4 v[154:157], v[26:33], v[180:187], 0
	v_mfma_f32_16x16x128_f8f6f4 v[122:125], v[10:17], v[180:187], 0
	v_mfma_f32_16x16x128_f8f6f4 v[126:129], v[2:9], v[180:187], 0
	v_mfma_f32_16x16x128_f8f6f4 v[118:121], v[2:9], v[202:209], 0
	v_mfma_f32_16x16x128_f8f6f4 v[114:117], v[10:17], v[202:209], 0
	v_mfma_f32_16x16x128_f8f6f4 v[146:149], v[26:33], v[202:209], 0
	v_mfma_f32_16x16x128_f8f6f4 v[150:153], v[18:25], v[202:209], 0
	s_setprio 0
	s_setprio 1
	v_mfma_f32_16x16x128_f8f6f4 v[142:145], v[18:25], v[210:217], 0
	v_mfma_f32_16x16x128_f8f6f4 v[138:141], v[26:33], v[210:217], 0
	v_mfma_f32_16x16x128_f8f6f4 v[106:109], v[10:17], v[210:217], 0
	v_mfma_f32_16x16x128_f8f6f4 v[110:113], v[2:9], v[210:217], 0
	v_mfma_f32_16x16x128_f8f6f4 v[102:105], v[2:9], v[218:225], 0
	v_mfma_f32_16x16x128_f8f6f4 v[98:101], v[10:17], v[218:225], 0
	v_mfma_f32_16x16x128_f8f6f4 v[130:133], v[26:33], v[218:225], 0
	v_mfma_f32_16x16x128_f8f6f4 v[134:137], v[18:25], v[218:225], 0
	s_barrier
	s_setprio 0
	ds_read_b128 v[202:205], v201 offset:16384
	ds_read_b128 v[206:209], v201 offset:17408
	ds_read_b128 v[210:213], v201 offset:18432
	ds_read_b128 v[214:217], v201 offset:19456
	ds_read_b128 v[218:221], v201 offset:20480
	ds_read_b128 v[222:225], v201 offset:21504
	ds_read_b128 v[226:229], v201 offset:22528
	ds_read_b128 v[230:233], v201 offset:23552
	v_lshl_add_u64 v[180:181], s[54:55], 0, v[164:165]
	s_mov_b32 m0, s78
	v_lshl_add_u64 v[182:183], v[180:181], 0, s[26:27]
	global_load_lds_dwordx4 v[182:183], off
	v_lshl_add_u64 v[182:183], s[54:55], 0, v[168:169]
	s_add_u32 s8, s54, 0x80100
	v_lshl_add_u64 v[184:185], v[182:183], 0, s[26:27]
	s_mov_b32 m0, s79
	s_addc_u32 s9, s55, 0
	global_load_lds_dwordx4 v[184:185], off
	v_lshl_add_u64 v[184:185], s[8:9], 0, v[164:165]
	s_mov_b32 m0, s80
	s_nop 0
	global_load_lds_dwordx4 v[184:185], off
	v_lshl_add_u64 v[184:185], s[8:9], 0, v[168:169]
	s_mov_b32 m0, s81
	s_nop 0
	global_load_lds_dwordx4 v[184:185], off
	v_lshl_add_u64 v[184:185], s[72:73], 0, v[162:163]
	v_lshl_add_u64 v[186:187], v[184:185], 0, s[26:27]
	s_mov_b32 m0, s53
	s_nop 0
	global_load_lds_dwordx4 v[186:187], off
	v_lshl_add_u64 v[186:187], s[72:73], 0, v[166:167]
	v_lshl_add_u64 v[234:235], v[186:187], 0, s[26:27]
	s_mov_b32 m0, s82
	s_nop 0
	global_load_lds_dwordx4 v[234:235], off
	s_waitcnt vmcnt(8)
	s_waitcnt lgkmcnt(0)
	s_setprio 1
	s_barrier
	v_mfma_f32_16x16x128_f8f6f4 v[94:97], v[18:25], v[202:209], 0
	v_mfma_f32_16x16x128_f8f6f4 v[90:93], v[26:33], v[202:209], 0
	v_mfma_f32_16x16x128_f8f6f4 v[58:61], v[10:17], v[202:209], 0
	v_mfma_f32_16x16x128_f8f6f4 v[62:65], v[2:9], v[202:209], 0
	v_mfma_f32_16x16x128_f8f6f4 v[54:57], v[2:9], v[210:217], 0
	v_mfma_f32_16x16x128_f8f6f4 v[50:53], v[10:17], v[210:217], 0
	v_mfma_f32_16x16x128_f8f6f4 v[82:85], v[26:33], v[210:217], 0
	v_mfma_f32_16x16x128_f8f6f4 v[86:89], v[18:25], v[210:217], 0
	s_setprio 0
	s_setprio 1
	v_mfma_f32_16x16x128_f8f6f4 v[78:81], v[18:25], v[218:225], 0
	v_mfma_f32_16x16x128_f8f6f4 v[74:77], v[26:33], v[218:225], 0
	v_mfma_f32_16x16x128_f8f6f4 v[42:45], v[10:17], v[218:225], 0
	v_mfma_f32_16x16x128_f8f6f4 v[46:49], v[2:9], v[218:225], 0
	v_mfma_f32_16x16x128_f8f6f4 v[38:41], v[2:9], v[226:233], 0
	v_mfma_f32_16x16x128_f8f6f4 v[34:37], v[10:17], v[226:233], 0
	v_mfma_f32_16x16x128_f8f6f4 v[66:69], v[26:33], v[226:233], 0
	v_mfma_f32_16x16x128_f8f6f4 v[70:73], v[18:25], v[226:233], 0
	s_barrier
	s_setprio 0
	ds_read_b128 v[18:21], v200 offset:32768
	ds_read_b128 v[22:25], v200 offset:33792
	ds_read_b128 v[26:29], v200 offset:34816
	ds_read_b128 v[30:33], v200 offset:35840
	ds_read_b128 v[2:5], v200 offset:49152
	ds_read_b128 v[6:9], v200 offset:50176
	ds_read_b128 v[10:13], v200 offset:51200
	ds_read_b128 v[14:17], v200 offset:52224
	ds_read_b128 v[202:205], v201 offset:32768
	ds_read_b128 v[206:209], v201 offset:33792
	ds_read_b128 v[210:213], v201 offset:34816
	ds_read_b128 v[214:217], v201 offset:35840
	ds_read_b128 v[218:221], v201 offset:36864
	ds_read_b128 v[222:225], v201 offset:37888
	ds_read_b128 v[226:229], v201 offset:38912
	ds_read_b128 v[230:233], v201 offset:39936
	s_add_u32 s8, s72, 0x80100
	s_addc_u32 s9, s73, 0
	s_mov_b32 m0, s83
	v_lshl_add_u64 v[234:235], s[8:9], 0, v[162:163]
	global_load_lds_dwordx4 v[234:235], off
	v_lshl_add_u64 v[234:235], s[8:9], 0, v[166:167]
	s_mov_b32 m0, s84
	s_nop 0
	global_load_lds_dwordx4 v[234:235], off
	s_waitcnt vmcnt(8)
	s_waitcnt lgkmcnt(0)
	s_setprio 1
	s_barrier
	v_mfma_f32_16x16x128_f8f6f4 v[158:161], v[18:25], v[202:209], v[158:161]
	v_mfma_f32_16x16x128_f8f6f4 v[154:157], v[26:33], v[202:209], v[154:157]
	v_mfma_f32_16x16x128_f8f6f4 v[122:125], v[10:17], v[202:209], v[122:125]
	v_mfma_f32_16x16x128_f8f6f4 v[126:129], v[2:9], v[202:209], v[126:129]
	v_mfma_f32_16x16x128_f8f6f4 v[118:121], v[2:9], v[210:217], v[118:121]
	v_mfma_f32_16x16x128_f8f6f4 v[114:117], v[10:17], v[210:217], v[114:117]
	v_mfma_f32_16x16x128_f8f6f4 v[146:149], v[26:33], v[210:217], v[146:149]
	v_mfma_f32_16x16x128_f8f6f4 v[150:153], v[18:25], v[210:217], v[150:153]
	s_setprio 0
	s_setprio 1
	v_mfma_f32_16x16x128_f8f6f4 v[142:145], v[18:25], v[218:225], v[142:145]
	v_mfma_f32_16x16x128_f8f6f4 v[138:141], v[26:33], v[218:225], v[138:141]
	v_mfma_f32_16x16x128_f8f6f4 v[106:109], v[10:17], v[218:225], v[106:109]
	v_mfma_f32_16x16x128_f8f6f4 v[110:113], v[2:9], v[218:225], v[110:113]
	v_mfma_f32_16x16x128_f8f6f4 v[102:105], v[2:9], v[226:233], v[102:105]
	v_mfma_f32_16x16x128_f8f6f4 v[98:101], v[10:17], v[226:233], v[98:101]
	v_mfma_f32_16x16x128_f8f6f4 v[130:133], v[26:33], v[226:233], v[130:133]
	v_mfma_f32_16x16x128_f8f6f4 v[134:137], v[18:25], v[226:233], v[134:137]
	s_barrier
	s_setprio 0
	ds_read_b128 v[202:205], v201 offset:49152
	ds_read_b128 v[206:209], v201 offset:50176
	ds_read_b128 v[210:213], v201 offset:51200
	ds_read_b128 v[214:217], v201 offset:52224
	ds_read_b128 v[218:221], v201 offset:53248
	ds_read_b128 v[222:225], v201 offset:54272
	ds_read_b128 v[226:229], v201 offset:55296
	ds_read_b128 v[230:233], v201 offset:56320
	s_mov_b32 m0, s87
	v_lshl_add_u64 v[180:181], v[180:181], 0, s[36:37]
	s_add_u32 s8, s54, 0x80180
	global_load_lds_dwordx4 v[180:181], off
	v_lshl_add_u64 v[180:181], v[182:183], 0, s[36:37]
	s_mov_b32 m0, s88
	s_addc_u32 s9, s55, 0
	global_load_lds_dwordx4 v[180:181], off
	v_lshl_add_u64 v[180:181], s[8:9], 0, v[164:165]
	s_mov_b32 m0, s91
	s_nop 0
	global_load_lds_dwordx4 v[180:181], off
	v_lshl_add_u64 v[180:181], s[8:9], 0, v[168:169]
	s_mov_b32 m0, s92
	s_nop 0
	global_load_lds_dwordx4 v[180:181], off
	v_lshl_add_u64 v[180:181], v[184:185], 0, s[36:37]
	s_mov_b32 m0, s89
	s_nop 0
	global_load_lds_dwordx4 v[180:181], off
	v_lshl_add_u64 v[180:181], v[186:187], 0, s[36:37]
	s_mov_b32 m0, s90
	s_nop 0
	global_load_lds_dwordx4 v[180:181], off
	s_waitcnt vmcnt(8)
	s_waitcnt lgkmcnt(0)
	s_setprio 1
	s_barrier
	v_mfma_f32_16x16x128_f8f6f4 v[94:97], v[18:25], v[202:209], v[94:97]
	v_mfma_f32_16x16x128_f8f6f4 v[90:93], v[26:33], v[202:209], v[90:93]
	v_mfma_f32_16x16x128_f8f6f4 v[58:61], v[10:17], v[202:209], v[58:61]
	v_mfma_f32_16x16x128_f8f6f4 v[62:65], v[2:9], v[202:209], v[62:65]
	v_mfma_f32_16x16x128_f8f6f4 v[54:57], v[2:9], v[210:217], v[54:57]
	v_mfma_f32_16x16x128_f8f6f4 v[50:53], v[10:17], v[210:217], v[50:53]
	v_mfma_f32_16x16x128_f8f6f4 v[82:85], v[26:33], v[210:217], v[82:85]
	v_mfma_f32_16x16x128_f8f6f4 v[86:89], v[18:25], v[210:217], v[86:89]
	s_setprio 0
	s_setprio 1
	v_mfma_f32_16x16x128_f8f6f4 v[78:81], v[18:25], v[218:225], v[78:81]
	v_mfma_f32_16x16x128_f8f6f4 v[74:77], v[26:33], v[218:225], v[74:77]
	v_mfma_f32_16x16x128_f8f6f4 v[42:45], v[10:17], v[218:225], v[42:45]
	v_mfma_f32_16x16x128_f8f6f4 v[46:49], v[2:9], v[218:225], v[46:49]
	v_mfma_f32_16x16x128_f8f6f4 v[38:41], v[2:9], v[226:233], v[38:41]
	v_mfma_f32_16x16x128_f8f6f4 v[34:37], v[10:17], v[226:233], v[34:37]
	v_mfma_f32_16x16x128_f8f6f4 v[66:69], v[26:33], v[226:233], v[66:69]
	v_mfma_f32_16x16x128_f8f6f4 v[70:73], v[18:25], v[226:233], v[70:73]
	s_barrier
	s_setprio 0
	s_add_u32 s72, s72, 0x80180
	s_addc_u32 s73, s73, 0
	s_add_u32 s8, s54, 0x200
	s_addc_u32 s9, s55, 0
	s_mov_b32 s62, 0
.LBB0_438:
	ds_read_b128 v[2:5], v200
	ds_read_b128 v[6:9], v200 offset:1024
	ds_read_b128 v[18:21], v200 offset:2048
	ds_read_b128 v[22:25], v200 offset:3072
	ds_read_b128 v[26:29], v200 offset:16384
	ds_read_b128 v[30:33], v200 offset:17408
	ds_read_b128 v[180:183], v200 offset:18432
	ds_read_b128 v[184:187], v200 offset:19456
	ds_read_b128 v[10:13], v201
	ds_read_b128 v[14:17], v201 offset:1024
	ds_read_b128 v[202:205], v201 offset:2048
	ds_read_b128 v[206:209], v201 offset:3072
	ds_read_b128 v[210:213], v201 offset:4096
	ds_read_b128 v[214:217], v201 offset:5120
	ds_read_b128 v[218:221], v201 offset:6144
	ds_read_b128 v[222:225], v201 offset:7168
	s_add_u32 s54, s72, 0xfff80080
	s_addc_u32 s55, s73, -1
	s_cmp_eq_u32 s62, 28
	s_cselect_b32 s75, s47, s55
	s_cselect_b32 s74, s71, s54
	s_cselect_b32 s55, s45, s9
	s_cselect_b32 s54, s94, s8
	s_mov_b32 m0, s33
	v_lshl_add_u64 v[226:227], s[72:73], 0, v[170:171]
	global_load_lds_dwordx4 v[226:227], off
	v_lshl_add_u64 v[226:227], s[72:73], 0, v[172:173]
	s_mov_b32 m0, s93
	s_nop 0
	global_load_lds_dwordx4 v[226:227], off
	s_waitcnt vmcnt(8)
	s_waitcnt lgkmcnt(0)
	s_setprio 1
	s_barrier
	v_mfma_f32_16x16x128_f8f6f4 v[158:161], v[2:9], v[10:17], v[158:161]
	v_mfma_f32_16x16x128_f8f6f4 v[154:157], v[18:25], v[10:17], v[154:157]
	v_mfma_f32_16x16x128_f8f6f4 v[122:125], v[180:187], v[10:17], v[122:125]
	v_mfma_f32_16x16x128_f8f6f4 v[126:129], v[26:33], v[10:17], v[126:129]
	v_mfma_f32_16x16x128_f8f6f4 v[118:121], v[26:33], v[202:209], v[118:121]
	v_mfma_f32_16x16x128_f8f6f4 v[114:117], v[180:187], v[202:209], v[114:117]
	v_mfma_f32_16x16x128_f8f6f4 v[146:149], v[18:25], v[202:209], v[146:149]
	v_mfma_f32_16x16x128_f8f6f4 v[150:153], v[2:9], v[202:209], v[150:153]
	s_setprio 0
	s_setprio 1
	v_mfma_f32_16x16x128_f8f6f4 v[142:145], v[2:9], v[210:217], v[142:145]
	v_mfma_f32_16x16x128_f8f6f4 v[138:141], v[18:25], v[210:217], v[138:141]
	v_mfma_f32_16x16x128_f8f6f4 v[106:109], v[180:187], v[210:217], v[106:109]
	v_mfma_f32_16x16x128_f8f6f4 v[110:113], v[26:33], v[210:217], v[110:113]
	v_mfma_f32_16x16x128_f8f6f4 v[102:105], v[26:33], v[218:225], v[102:105]
	v_mfma_f32_16x16x128_f8f6f4 v[98:101], v[180:187], v[218:225], v[98:101]
	v_mfma_f32_16x16x128_f8f6f4 v[130:133], v[18:25], v[218:225], v[130:133]
	v_mfma_f32_16x16x128_f8f6f4 v[134:137], v[2:9], v[218:225], v[134:137]
	s_barrier
	s_setprio 0
	ds_read_b128 v[202:205], v201 offset:16384
	ds_read_b128 v[206:209], v201 offset:17408
	ds_read_b128 v[210:213], v201 offset:18432
	ds_read_b128 v[214:217], v201 offset:19456
	ds_read_b128 v[218:221], v201 offset:20480
	ds_read_b128 v[222:225], v201 offset:21504
	ds_read_b128 v[226:229], v201 offset:22528
	ds_read_b128 v[230:233], v201 offset:23552
	s_mov_b32 m0, s78
	v_lshl_add_u64 v[10:11], s[54:55], 0, v[164:165]
	s_add_u32 s96, s54, 0x80000
	global_load_lds_dwordx4 v[10:11], off
	v_lshl_add_u64 v[12:13], s[54:55], 0, v[168:169]
	s_mov_b32 m0, s79
	s_addc_u32 s97, s55, 0
	global_load_lds_dwordx4 v[12:13], off
	v_lshl_add_u64 v[14:15], s[96:97], 0, v[164:165]
	s_mov_b32 m0, s80
	v_lshl_add_u64 v[16:17], s[74:75], 0, v[166:167]
	global_load_lds_dwordx4 v[14:15], off
	v_lshl_add_u64 v[14:15], s[96:97], 0, v[168:169]
	s_mov_b32 m0, s81
	s_nop 0
	global_load_lds_dwordx4 v[14:15], off
	v_lshl_add_u64 v[14:15], s[74:75], 0, v[162:163]
	s_mov_b32 m0, s53
	s_nop 0
	global_load_lds_dwordx4 v[14:15], off
	s_mov_b32 m0, s82
	s_nop 0
	global_load_lds_dwordx4 v[16:17], off
	s_waitcnt vmcnt(8)
	s_waitcnt lgkmcnt(0)
	s_setprio 1
	s_barrier
	v_mfma_f32_16x16x128_f8f6f4 v[94:97], v[2:9], v[202:209], v[94:97]
	v_mfma_f32_16x16x128_f8f6f4 v[90:93], v[18:25], v[202:209], v[90:93]
	v_mfma_f32_16x16x128_f8f6f4 v[58:61], v[180:187], v[202:209], v[58:61]
	v_mfma_f32_16x16x128_f8f6f4 v[62:65], v[26:33], v[202:209], v[62:65]
	v_mfma_f32_16x16x128_f8f6f4 v[54:57], v[26:33], v[210:217], v[54:57]
	v_mfma_f32_16x16x128_f8f6f4 v[50:53], v[180:187], v[210:217], v[50:53]
	v_mfma_f32_16x16x128_f8f6f4 v[82:85], v[18:25], v[210:217], v[82:85]
	v_mfma_f32_16x16x128_f8f6f4 v[86:89], v[2:9], v[210:217], v[86:89]
	s_setprio 0
	s_setprio 1
	v_mfma_f32_16x16x128_f8f6f4 v[78:81], v[2:9], v[218:225], v[78:81]
	v_mfma_f32_16x16x128_f8f6f4 v[74:77], v[18:25], v[218:225], v[74:77]
	v_mfma_f32_16x16x128_f8f6f4 v[42:45], v[180:187], v[218:225], v[42:45]
	v_mfma_f32_16x16x128_f8f6f4 v[46:49], v[26:33], v[218:225], v[46:49]
	v_mfma_f32_16x16x128_f8f6f4 v[38:41], v[26:33], v[226:233], v[38:41]
	v_mfma_f32_16x16x128_f8f6f4 v[34:37], v[180:187], v[226:233], v[34:37]
	v_mfma_f32_16x16x128_f8f6f4 v[66:69], v[18:25], v[226:233], v[66:69]
	v_mfma_f32_16x16x128_f8f6f4 v[70:73], v[2:9], v[226:233], v[70:73]
	s_barrier
	s_setprio 0
	ds_read_b128 v[18:21], v200 offset:32768
	ds_read_b128 v[22:25], v200 offset:33792
	ds_read_b128 v[26:29], v200 offset:34816
	ds_read_b128 v[30:33], v200 offset:35840
	ds_read_b128 v[2:5], v200 offset:49152
	ds_read_b128 v[6:9], v200 offset:50176
	ds_read_b128 v[180:183], v200 offset:51200
	ds_read_b128 v[184:187], v200 offset:52224
	ds_read_b128 v[202:205], v201 offset:32768
	ds_read_b128 v[206:209], v201 offset:33792
	ds_read_b128 v[210:213], v201 offset:34816
	ds_read_b128 v[214:217], v201 offset:35840
	ds_read_b128 v[218:221], v201 offset:36864
	ds_read_b128 v[222:225], v201 offset:37888
	ds_read_b128 v[226:229], v201 offset:38912
	ds_read_b128 v[230:233], v201 offset:39936
	s_add_u32 s74, s74, 0x80000
	s_addc_u32 s75, s75, 0
	s_mov_b32 m0, s83
	v_lshl_add_u64 v[234:235], s[74:75], 0, v[162:163]
	global_load_lds_dwordx4 v[234:235], off
	v_lshl_add_u64 v[234:235], s[74:75], 0, v[166:167]
	s_mov_b32 m0, s84
	s_nop 0
	global_load_lds_dwordx4 v[234:235], off
	s_waitcnt vmcnt(8)
	s_waitcnt lgkmcnt(0)
	s_setprio 1
	s_barrier
	v_mfma_f32_16x16x128_f8f6f4 v[158:161], v[18:25], v[202:209], v[158:161]
	v_mfma_f32_16x16x128_f8f6f4 v[154:157], v[26:33], v[202:209], v[154:157]
	v_mfma_f32_16x16x128_f8f6f4 v[122:125], v[180:187], v[202:209], v[122:125]
	v_mfma_f32_16x16x128_f8f6f4 v[126:129], v[2:9], v[202:209], v[126:129]
	v_mfma_f32_16x16x128_f8f6f4 v[118:121], v[2:9], v[210:217], v[118:121]
	v_mfma_f32_16x16x128_f8f6f4 v[114:117], v[180:187], v[210:217], v[114:117]
	v_mfma_f32_16x16x128_f8f6f4 v[146:149], v[26:33], v[210:217], v[146:149]
	v_mfma_f32_16x16x128_f8f6f4 v[150:153], v[18:25], v[210:217], v[150:153]
	s_setprio 0
	s_setprio 1
	v_mfma_f32_16x16x128_f8f6f4 v[142:145], v[18:25], v[218:225], v[142:145]
	v_mfma_f32_16x16x128_f8f6f4 v[138:141], v[26:33], v[218:225], v[138:141]
	v_mfma_f32_16x16x128_f8f6f4 v[106:109], v[180:187], v[218:225], v[106:109]
	v_mfma_f32_16x16x128_f8f6f4 v[110:113], v[2:9], v[218:225], v[110:113]
	v_mfma_f32_16x16x128_f8f6f4 v[102:105], v[2:9], v[226:233], v[102:105]
	v_mfma_f32_16x16x128_f8f6f4 v[98:101], v[180:187], v[226:233], v[98:101]
	v_mfma_f32_16x16x128_f8f6f4 v[130:133], v[26:33], v[226:233], v[130:133]
	v_mfma_f32_16x16x128_f8f6f4 v[134:137], v[18:25], v[226:233], v[134:137]
	s_barrier
	s_setprio 0
	ds_read_b128 v[202:205], v201 offset:49152
	ds_read_b128 v[206:209], v201 offset:50176
	ds_read_b128 v[210:213], v201 offset:51200
	ds_read_b128 v[214:217], v201 offset:52224
	ds_read_b128 v[218:221], v201 offset:53248
	ds_read_b128 v[222:225], v201 offset:54272
	ds_read_b128 v[226:229], v201 offset:55296
	ds_read_b128 v[230:233], v201 offset:56320
	s_mov_b32 m0, s87
	v_lshl_add_u64 v[10:11], v[10:11], 0, s[4:5]
	s_add_u32 s54, s54, 0x80080
	global_load_lds_dwordx4 v[10:11], off
	v_lshl_add_u64 v[10:11], v[12:13], 0, s[4:5]
	s_mov_b32 m0, s88
	s_addc_u32 s55, s55, 0
	global_load_lds_dwordx4 v[10:11], off
	v_lshl_add_u64 v[10:11], s[54:55], 0, v[164:165]
	s_mov_b32 m0, s91
	s_nop 0
	global_load_lds_dwordx4 v[10:11], off
	v_lshl_add_u64 v[10:11], s[54:55], 0, v[168:169]
	s_mov_b32 m0, s92
	s_nop 0
	global_load_lds_dwordx4 v[10:11], off
	v_lshl_add_u64 v[10:11], v[14:15], 0, s[4:5]
	s_mov_b32 m0, s89
	s_nop 0
	global_load_lds_dwordx4 v[10:11], off
	v_lshl_add_u64 v[10:11], v[16:17], 0, s[4:5]
	s_mov_b32 m0, s90
	s_nop 0
	global_load_lds_dwordx4 v[10:11], off
	s_waitcnt vmcnt(8)
	s_waitcnt lgkmcnt(0)
	s_setprio 1
	s_barrier
	v_mfma_f32_16x16x128_f8f6f4 v[94:97], v[18:25], v[202:209], v[94:97]
	v_mfma_f32_16x16x128_f8f6f4 v[90:93], v[26:33], v[202:209], v[90:93]
	v_mfma_f32_16x16x128_f8f6f4 v[58:61], v[180:187], v[202:209], v[58:61]
	v_mfma_f32_16x16x128_f8f6f4 v[62:65], v[2:9], v[202:209], v[62:65]
	v_mfma_f32_16x16x128_f8f6f4 v[54:57], v[2:9], v[210:217], v[54:57]
	v_mfma_f32_16x16x128_f8f6f4 v[50:53], v[180:187], v[210:217], v[50:53]
	v_mfma_f32_16x16x128_f8f6f4 v[82:85], v[26:33], v[210:217], v[82:85]
	v_mfma_f32_16x16x128_f8f6f4 v[86:89], v[18:25], v[210:217], v[86:89]
	s_setprio 0
	s_setprio 1
	v_mfma_f32_16x16x128_f8f6f4 v[78:81], v[18:25], v[218:225], v[78:81]
	v_mfma_f32_16x16x128_f8f6f4 v[74:77], v[26:33], v[218:225], v[74:77]
	v_mfma_f32_16x16x128_f8f6f4 v[42:45], v[180:187], v[218:225], v[42:45]
	v_mfma_f32_16x16x128_f8f6f4 v[46:49], v[2:9], v[218:225], v[46:49]
	v_mfma_f32_16x16x128_f8f6f4 v[38:41], v[2:9], v[226:233], v[38:41]
	v_mfma_f32_16x16x128_f8f6f4 v[34:37], v[180:187], v[226:233], v[34:37]
	v_mfma_f32_16x16x128_f8f6f4 v[66:69], v[26:33], v[226:233], v[66:69]
	v_mfma_f32_16x16x128_f8f6f4 v[70:73], v[18:25], v[226:233], v[70:73]
	s_barrier
	s_setprio 0
	s_add_i32 s62, s62, 2
	s_add_u32 s72, s72, 0x100
	s_addc_u32 s73, s73, 0
	s_add_u32 s8, s8, 0x100
	s_addc_u32 s9, s9, 0
	s_cmp_gt_u32 s62, 29
	s_cbranch_scc0 .LBB0_438
	s_and_b64 vcc, exec, s[6:7]
	s_cbranch_vccz .LBB0_441
	s_barrier

.LBB0_452:
	ds_read_b128 v[146:149], v143
	ds_read_b128 v[150:153], v143 offset:1024
	ds_read_b128 v[154:157], v143 offset:2048
	ds_read_b128 v[158:161], v143 offset:3072
	ds_read_b128 v[162:165], v143 offset:16384
	ds_read_b128 v[166:169], v143 offset:17408
	ds_read_b128 v[170:173], v143 offset:18432
	ds_read_b128 v[174:177], v143 offset:19456
	ds_read_b128 v[180:183], v144
	ds_read_b128 v[184:187], v144 offset:1024
	ds_read_b128 v[188:191], v144 offset:2048
	ds_read_b128 v[192:195], v144 offset:3072
	ds_read_b128 v[196:199], v144 offset:4096
	ds_read_b128 v[200:203], v144 offset:5120
	ds_read_b128 v[204:207], v144 offset:6144
	ds_read_b128 v[208:211], v144 offset:7168
	s_add_u32 s8, s52, 0xfff00080
	s_addc_u32 s9, s53, -1
	s_cmp_eq_u32 s91, 28
	s_cselect_b32 s73, s27, s9
	s_cselect_b32 s72, s37, s8
	s_cselect_b32 s55, s39, s90
	s_cselect_b32 s54, s45, s89
	v_lshl_add_u64 v[140:141], s[52:53], 0, v[136:137]
	s_add_i32 m0, s47, 0xc000
	global_load_lds_dwordx4 v[140:141], off
	v_lshl_add_u64 v[140:141], s[52:53], 0, v[138:139]
	s_add_i32 m0, s47, 0xe000
	s_nop 0
	global_load_lds_dwordx4 v[140:141], off
	s_waitcnt vmcnt(8)
	s_waitcnt lgkmcnt(0)
	s_setprio 1
	s_barrier
	v_mfma_f32_16x16x32_bf16 v[126:129], v[146:149], v[180:183], v[126:129]
	v_mfma_f32_16x16x32_bf16 v[122:125], v[154:157], v[180:183], v[122:125]
	v_mfma_f32_16x16x32_bf16 v[118:121], v[146:149], v[188:191], v[118:121]
	v_mfma_f32_16x16x32_bf16 v[114:117], v[154:157], v[188:191], v[114:117]
	v_mfma_f32_16x16x32_bf16 v[110:113], v[146:149], v[196:199], v[110:113]
	v_mfma_f32_16x16x32_bf16 v[106:109], v[154:157], v[196:199], v[106:109]
	v_mfma_f32_16x16x32_bf16 v[102:105], v[146:149], v[204:207], v[102:105]
	v_mfma_f32_16x16x32_bf16 v[98:101], v[154:157], v[204:207], v[98:101]
	v_mfma_f32_16x16x32_bf16 v[126:129], v[150:153], v[184:187], v[126:129]
	v_mfma_f32_16x16x32_bf16 v[122:125], v[158:161], v[184:187], v[122:125]
	v_mfma_f32_16x16x32_bf16 v[118:121], v[150:153], v[192:195], v[118:121]
	v_mfma_f32_16x16x32_bf16 v[114:117], v[158:161], v[192:195], v[114:117]
	v_mfma_f32_16x16x32_bf16 v[110:113], v[150:153], v[200:203], v[110:113]
	v_mfma_f32_16x16x32_bf16 v[106:109], v[158:161], v[200:203], v[106:109]
	v_mfma_f32_16x16x32_bf16 v[102:105], v[150:153], v[208:211], v[102:105]
	v_mfma_f32_16x16x32_bf16 v[98:101], v[158:161], v[208:211], v[98:101]
	s_setprio 0
	s_setprio 1
	v_mfma_f32_16x16x32_bf16 v[90:93], v[162:165], v[180:183], v[90:93]
	v_mfma_f32_16x16x32_bf16 v[82:85], v[170:173], v[180:183], v[82:85]
	v_mfma_f32_16x16x32_bf16 v[74:77], v[162:165], v[188:191], v[74:77]
	v_mfma_f32_16x16x32_bf16 v[66:69], v[170:173], v[188:191], v[66:69]
	v_mfma_f32_16x16x32_bf16 v[58:61], v[162:165], v[196:199], v[58:61]
	v_mfma_f32_16x16x32_bf16 v[50:53], v[170:173], v[196:199], v[50:53]
	v_mfma_f32_16x16x32_bf16 v[42:45], v[162:165], v[204:207], v[42:45]
	v_mfma_f32_16x16x32_bf16 v[34:37], v[170:173], v[204:207], v[34:37]
	v_mfma_f32_16x16x32_bf16 v[90:93], v[166:169], v[184:187], v[90:93]
	v_mfma_f32_16x16x32_bf16 v[82:85], v[174:177], v[184:187], v[82:85]
	v_mfma_f32_16x16x32_bf16 v[74:77], v[166:169], v[192:195], v[74:77]
	v_mfma_f32_16x16x32_bf16 v[66:69], v[174:177], v[192:195], v[66:69]
	v_mfma_f32_16x16x32_bf16 v[58:61], v[166:169], v[200:203], v[58:61]
	v_mfma_f32_16x16x32_bf16 v[50:53], v[174:177], v[200:203], v[50:53]
	v_mfma_f32_16x16x32_bf16 v[42:45], v[166:169], v[208:211], v[42:45]
	v_mfma_f32_16x16x32_bf16 v[34:37], v[174:177], v[208:211], v[34:37]
	s_barrier
	s_setprio 0
	ds_read_b128 v[180:183], v144 offset:16384
	ds_read_b128 v[184:187], v144 offset:17408
	ds_read_b128 v[188:191], v144 offset:18432
	ds_read_b128 v[192:195], v144 offset:19456
	ds_read_b128 v[196:199], v144 offset:20480
	ds_read_b128 v[200:203], v144 offset:21504
	ds_read_b128 v[204:207], v144 offset:22528
	ds_read_b128 v[208:211], v144 offset:23552
	s_mov_b32 m0, s74
	v_lshl_add_u64 v[140:141], s[54:55], 0, v[132:133]
	s_add_u32 s8, s54, 0x100000
	global_load_lds_dwordx4 v[140:141], off
	v_lshl_add_u64 v[212:213], s[54:55], 0, v[130:131]
	s_mov_b32 m0, s75
	s_addc_u32 s9, s55, 0
	global_load_lds_dwordx4 v[212:213], off
	v_lshl_add_u64 v[214:215], s[8:9], 0, v[132:133]
	s_mov_b32 m0, s76
	v_lshl_add_u64 v[216:217], s[72:73], 0, v[130:131]
	global_load_lds_dwordx4 v[214:215], off
	v_lshl_add_u64 v[214:215], s[8:9], 0, v[130:131]
	s_mov_b32 m0, s77
	s_nop 0
	global_load_lds_dwordx4 v[214:215], off
	v_lshl_add_u64 v[214:215], s[72:73], 0, v[132:133]
	s_mov_b32 m0, s47
	s_nop 0
	global_load_lds_dwordx4 v[214:215], off
	s_mov_b32 m0, s78
	s_nop 0
	global_load_lds_dwordx4 v[216:217], off
	s_waitcnt vmcnt(8)
	s_waitcnt lgkmcnt(0)
	s_setprio 1
	s_barrier
	v_mfma_f32_16x16x32_bf16 v[94:97], v[146:149], v[180:183], v[94:97]
	v_mfma_f32_16x16x32_bf16 v[86:89], v[154:157], v[180:183], v[86:89]
	v_mfma_f32_16x16x32_bf16 v[78:81], v[146:149], v[188:191], v[78:81]
	v_mfma_f32_16x16x32_bf16 v[70:73], v[154:157], v[188:191], v[70:73]
	v_mfma_f32_16x16x32_bf16 v[62:65], v[146:149], v[196:199], v[62:65]
	v_mfma_f32_16x16x32_bf16 v[54:57], v[154:157], v[196:199], v[54:57]
	v_mfma_f32_16x16x32_bf16 v[46:49], v[146:149], v[204:207], v[46:49]
	v_mfma_f32_16x16x32_bf16 v[38:41], v[154:157], v[204:207], v[38:41]
	v_mfma_f32_16x16x32_bf16 v[94:97], v[150:153], v[184:187], v[94:97]
	v_mfma_f32_16x16x32_bf16 v[86:89], v[158:161], v[184:187], v[86:89]
	v_mfma_f32_16x16x32_bf16 v[78:81], v[150:153], v[192:195], v[78:81]
	v_mfma_f32_16x16x32_bf16 v[70:73], v[158:161], v[192:195], v[70:73]
	v_mfma_f32_16x16x32_bf16 v[62:65], v[150:153], v[200:203], v[62:65]
	v_mfma_f32_16x16x32_bf16 v[54:57], v[158:161], v[200:203], v[54:57]
	v_mfma_f32_16x16x32_bf16 v[46:49], v[150:153], v[208:211], v[46:49]
	v_mfma_f32_16x16x32_bf16 v[38:41], v[158:161], v[208:211], v[38:41]
	s_setprio 0
	s_setprio 1
	v_mfma_f32_16x16x32_bf16 v[30:33], v[162:165], v[180:183], v[30:33]
	v_mfma_f32_16x16x32_bf16 v[26:29], v[170:173], v[180:183], v[26:29]
	v_mfma_f32_16x16x32_bf16 v[22:25], v[162:165], v[188:191], v[22:25]
	v_mfma_f32_16x16x32_bf16 v[18:21], v[170:173], v[188:191], v[18:21]
	v_mfma_f32_16x16x32_bf16 v[14:17], v[162:165], v[196:199], v[14:17]
	v_mfma_f32_16x16x32_bf16 v[10:13], v[170:173], v[196:199], v[10:13]
	v_mfma_f32_16x16x32_bf16 v[6:9], v[162:165], v[204:207], v[6:9]
	v_mfma_f32_16x16x32_bf16 v[2:5], v[170:173], v[204:207], v[2:5]
	v_mfma_f32_16x16x32_bf16 v[30:33], v[166:169], v[184:187], v[30:33]
	v_mfma_f32_16x16x32_bf16 v[26:29], v[174:177], v[184:187], v[26:29]
	v_mfma_f32_16x16x32_bf16 v[22:25], v[166:169], v[192:195], v[22:25]
	v_mfma_f32_16x16x32_bf16 v[18:21], v[174:177], v[192:195], v[18:21]
	v_mfma_f32_16x16x32_bf16 v[14:17], v[166:169], v[200:203], v[14:17]
	v_mfma_f32_16x16x32_bf16 v[10:13], v[174:177], v[200:203], v[10:13]
	v_mfma_f32_16x16x32_bf16 v[6:9], v[166:169], v[208:211], v[6:9]
	v_mfma_f32_16x16x32_bf16 v[2:5], v[174:177], v[208:211], v[2:5]
	s_barrier
	s_setprio 0
	ds_read_b128 v[146:149], v143 offset:32768
	ds_read_b128 v[150:153], v143 offset:33792
	ds_read_b128 v[154:157], v143 offset:34816
	ds_read_b128 v[158:161], v143 offset:35840
	ds_read_b128 v[162:165], v143 offset:49152
	ds_read_b128 v[166:169], v143 offset:50176
	ds_read_b128 v[170:173], v143 offset:51200
	ds_read_b128 v[174:177], v143 offset:52224
	ds_read_b128 v[180:183], v144 offset:32768
	ds_read_b128 v[184:187], v144 offset:33792
	ds_read_b128 v[188:191], v144 offset:34816
	ds_read_b128 v[192:195], v144 offset:35840
	ds_read_b128 v[196:199], v144 offset:36864
	ds_read_b128 v[200:203], v144 offset:37888
	ds_read_b128 v[204:207], v144 offset:38912
	ds_read_b128 v[208:211], v144 offset:39936
	s_add_u32 s8, s72, 0x100000
	s_addc_u32 s9, s73, 0
	s_mov_b32 m0, s79
	v_lshl_add_u64 v[218:219], s[8:9], 0, v[132:133]
	global_load_lds_dwordx4 v[218:219], off
	v_lshl_add_u64 v[218:219], s[8:9], 0, v[130:131]
	s_mov_b32 m0, s80
	s_nop 0
	global_load_lds_dwordx4 v[218:219], off
	s_waitcnt vmcnt(8)
	s_waitcnt lgkmcnt(0)
	s_setprio 1
	s_barrier
	v_mfma_f32_16x16x32_bf16 v[126:129], v[146:149], v[180:183], v[126:129]
	v_mfma_f32_16x16x32_bf16 v[122:125], v[154:157], v[180:183], v[122:125]
	v_mfma_f32_16x16x32_bf16 v[118:121], v[146:149], v[188:191], v[118:121]
	v_mfma_f32_16x16x32_bf16 v[114:117], v[154:157], v[188:191], v[114:117]
	v_mfma_f32_16x16x32_bf16 v[110:113], v[146:149], v[196:199], v[110:113]
	v_mfma_f32_16x16x32_bf16 v[106:109], v[154:157], v[196:199], v[106:109]
	v_mfma_f32_16x16x32_bf16 v[102:105], v[146:149], v[204:207], v[102:105]
	v_mfma_f32_16x16x32_bf16 v[98:101], v[154:157], v[204:207], v[98:101]
	v_mfma_f32_16x16x32_bf16 v[126:129], v[150:153], v[184:187], v[126:129]
	v_mfma_f32_16x16x32_bf16 v[122:125], v[158:161], v[184:187], v[122:125]
	v_mfma_f32_16x16x32_bf16 v[118:121], v[150:153], v[192:195], v[118:121]
	v_mfma_f32_16x16x32_bf16 v[114:117], v[158:161], v[192:195], v[114:117]
	v_mfma_f32_16x16x32_bf16 v[110:113], v[150:153], v[200:203], v[110:113]
	v_mfma_f32_16x16x32_bf16 v[106:109], v[158:161], v[200:203], v[106:109]
	v_mfma_f32_16x16x32_bf16 v[102:105], v[150:153], v[208:211], v[102:105]
	v_mfma_f32_16x16x32_bf16 v[98:101], v[158:161], v[208:211], v[98:101]
	s_setprio 0
	s_setprio 1
	v_mfma_f32_16x16x32_bf16 v[90:93], v[162:165], v[180:183], v[90:93]
	v_mfma_f32_16x16x32_bf16 v[82:85], v[170:173], v[180:183], v[82:85]
	v_mfma_f32_16x16x32_bf16 v[74:77], v[162:165], v[188:191], v[74:77]
	v_mfma_f32_16x16x32_bf16 v[66:69], v[170:173], v[188:191], v[66:69]
	v_mfma_f32_16x16x32_bf16 v[58:61], v[162:165], v[196:199], v[58:61]
	v_mfma_f32_16x16x32_bf16 v[50:53], v[170:173], v[196:199], v[50:53]
	v_mfma_f32_16x16x32_bf16 v[42:45], v[162:165], v[204:207], v[42:45]
	v_mfma_f32_16x16x32_bf16 v[34:37], v[170:173], v[204:207], v[34:37]
	v_mfma_f32_16x16x32_bf16 v[90:93], v[166:169], v[184:187], v[90:93]
	v_mfma_f32_16x16x32_bf16 v[82:85], v[174:177], v[184:187], v[82:85]
	v_mfma_f32_16x16x32_bf16 v[74:77], v[166:169], v[192:195], v[74:77]
	v_mfma_f32_16x16x32_bf16 v[66:69], v[174:177], v[192:195], v[66:69]
	v_mfma_f32_16x16x32_bf16 v[58:61], v[166:169], v[200:203], v[58:61]
	v_mfma_f32_16x16x32_bf16 v[50:53], v[174:177], v[200:203], v[50:53]
	v_mfma_f32_16x16x32_bf16 v[42:45], v[166:169], v[208:211], v[42:45]
	v_mfma_f32_16x16x32_bf16 v[34:37], v[174:177], v[208:211], v[34:37]
	s_barrier
	s_setprio 0
	ds_read_b128 v[180:183], v144 offset:49152
	ds_read_b128 v[184:187], v144 offset:50176
	ds_read_b128 v[188:191], v144 offset:51200
	ds_read_b128 v[192:195], v144 offset:52224
	ds_read_b128 v[196:199], v144 offset:53248
	ds_read_b128 v[200:203], v144 offset:54272
	ds_read_b128 v[204:207], v144 offset:55296
	ds_read_b128 v[208:211], v144 offset:56320
	s_mov_b32 m0, s81
	v_lshl_add_u64 v[140:141], v[140:141], 0, s[4:5]
	s_add_u32 s8, s54, 0x100080
	global_load_lds_dwordx4 v[140:141], off
	v_lshl_add_u64 v[140:141], v[212:213], 0, s[4:5]
	s_mov_b32 m0, s82
	s_addc_u32 s9, s55, 0
	global_load_lds_dwordx4 v[140:141], off
	v_lshl_add_u64 v[140:141], s[8:9], 0, v[132:133]
	s_mov_b32 m0, s85
	s_nop 0
	global_load_lds_dwordx4 v[140:141], off
	v_lshl_add_u64 v[140:141], s[8:9], 0, v[130:131]
	s_mov_b32 m0, s86
	s_nop 0
	global_load_lds_dwordx4 v[140:141], off
	v_lshl_add_u64 v[140:141], v[214:215], 0, s[4:5]
	s_mov_b32 m0, s83
	s_nop 0
	global_load_lds_dwordx4 v[140:141], off
	v_lshl_add_u64 v[140:141], v[216:217], 0, s[4:5]
	s_mov_b32 m0, s84
	s_nop 0
	global_load_lds_dwordx4 v[140:141], off
	s_waitcnt vmcnt(8)
	s_waitcnt lgkmcnt(0)
	s_setprio 1
	s_barrier
	v_mfma_f32_16x16x32_bf16 v[94:97], v[146:149], v[180:183], v[94:97]
	v_mfma_f32_16x16x32_bf16 v[86:89], v[154:157], v[180:183], v[86:89]
	v_mfma_f32_16x16x32_bf16 v[78:81], v[146:149], v[188:191], v[78:81]
	v_mfma_f32_16x16x32_bf16 v[70:73], v[154:157], v[188:191], v[70:73]
	v_mfma_f32_16x16x32_bf16 v[62:65], v[146:149], v[196:199], v[62:65]
	v_mfma_f32_16x16x32_bf16 v[54:57], v[154:157], v[196:199], v[54:57]
	v_mfma_f32_16x16x32_bf16 v[46:49], v[146:149], v[204:207], v[46:49]
	v_mfma_f32_16x16x32_bf16 v[38:41], v[154:157], v[204:207], v[38:41]
	v_mfma_f32_16x16x32_bf16 v[94:97], v[150:153], v[184:187], v[94:97]
	v_mfma_f32_16x16x32_bf16 v[86:89], v[158:161], v[184:187], v[86:89]
	v_mfma_f32_16x16x32_bf16 v[78:81], v[150:153], v[192:195], v[78:81]
	v_mfma_f32_16x16x32_bf16 v[70:73], v[158:161], v[192:195], v[70:73]
	v_mfma_f32_16x16x32_bf16 v[62:65], v[150:153], v[200:203], v[62:65]
	v_mfma_f32_16x16x32_bf16 v[54:57], v[158:161], v[200:203], v[54:57]
	v_mfma_f32_16x16x32_bf16 v[46:49], v[150:153], v[208:211], v[46:49]
	v_mfma_f32_16x16x32_bf16 v[38:41], v[158:161], v[208:211], v[38:41]
	s_setprio 0
	s_setprio 1
	v_mfma_f32_16x16x32_bf16 v[30:33], v[162:165], v[180:183], v[30:33]
	v_mfma_f32_16x16x32_bf16 v[26:29], v[170:173], v[180:183], v[26:29]
	v_mfma_f32_16x16x32_bf16 v[22:25], v[162:165], v[188:191], v[22:25]
	v_mfma_f32_16x16x32_bf16 v[18:21], v[170:173], v[188:191], v[18:21]
	v_mfma_f32_16x16x32_bf16 v[14:17], v[162:165], v[196:199], v[14:17]
	v_mfma_f32_16x16x32_bf16 v[10:13], v[170:173], v[196:199], v[10:13]
	v_mfma_f32_16x16x32_bf16 v[6:9], v[162:165], v[204:207], v[6:9]
	v_mfma_f32_16x16x32_bf16 v[2:5], v[170:173], v[204:207], v[2:5]
	v_mfma_f32_16x16x32_bf16 v[30:33], v[166:169], v[184:187], v[30:33]
	v_mfma_f32_16x16x32_bf16 v[26:29], v[174:177], v[184:187], v[26:29]
	v_mfma_f32_16x16x32_bf16 v[22:25], v[166:169], v[192:195], v[22:25]
	v_mfma_f32_16x16x32_bf16 v[18:21], v[174:177], v[192:195], v[18:21]
	v_mfma_f32_16x16x32_bf16 v[14:17], v[166:169], v[200:203], v[14:17]
	v_mfma_f32_16x16x32_bf16 v[10:13], v[174:177], v[200:203], v[10:13]
	v_mfma_f32_16x16x32_bf16 v[6:9], v[166:169], v[208:211], v[6:9]
	v_mfma_f32_16x16x32_bf16 v[2:5], v[174:177], v[208:211], v[2:5]
	s_barrier
	s_setprio 0
	s_add_i32 s91, s91, 2
	s_add_u32 s52, s52, 0x100
	s_addc_u32 s53, s53, 0
	s_add_u32 s89, s89, 0x100
	s_addc_u32 s90, s90, 0
	s_cmp_gt_u32 s91, 29
	s_cbranch_scc0 .LBB0_452
	s_and_b64 vcc, exec, s[6:7]
	s_cbranch_vccz .LBB0_455
	s_barrier

.LBB0_600:
	s_ashr_i32 s55, s54, 31
	ds_read_b128 v[18:21], v200
	ds_read_b128 v[22:25], v200 offset:1024
	ds_read_b128 v[26:29], v200 offset:2048
	ds_read_b128 v[30:33], v200 offset:3072
	ds_read_b128 v[2:5], v200 offset:16384
	ds_read_b128 v[6:9], v200 offset:17408
	ds_read_b128 v[10:13], v200 offset:18432
	ds_read_b128 v[14:17], v200 offset:19456
	s_lshl_b64 s[4:5], s[54:55], 18
	s_add_u32 s72, s38, s4
	s_addc_u32 s73, s39, s5
	s_and_b64 s[4:5], s[2:3], exec
	s_cselect_b32 s4, s73, s81
	s_cselect_b32 s5, s72, s80
	s_ashr_i32 s53, s52, 31
	s_lshl_b64 s[8:9], s[52:53], 18
	s_add_u32 s74, s94, s8
	v_readlane_b32 s8, v254, 6
	s_addc_u32 s75, s8, s9
	s_and_b64 s[8:9], s[2:3], exec
	s_cselect_b32 s53, s75, s79
	s_cselect_b32 s55, s74, s78
	s_add_u32 s8, s80, 0x20080
	s_addc_u32 s9, s81, 0
	s_mov_b32 m0, s96
	v_lshl_add_u64 v[226:227], s[8:9], 0, v[162:163]
	ds_read_b128 v[182:185], v201
	ds_read_b128 v[186:189], v201 offset:1024
	ds_read_b128 v[202:205], v201 offset:2048
	ds_read_b128 v[206:209], v201 offset:3072
	ds_read_b128 v[210:213], v201 offset:4096
	ds_read_b128 v[214:217], v201 offset:5120
	ds_read_b128 v[218:221], v201 offset:6144
	ds_read_b128 v[222:225], v201 offset:7168
	global_load_lds_dwordx4 v[226:227], off
	v_lshl_add_u64 v[226:227], s[8:9], 0, v[166:167]
	s_mov_b32 m0, s61
	s_nop 0
	global_load_lds_dwordx4 v[226:227], off
	s_waitcnt vmcnt(8)
	s_waitcnt lgkmcnt(0)
	s_setprio 1
	s_barrier
	v_mfma_f32_16x16x128_f8f6f4 v[158:161], v[18:25], v[182:189], 0
	v_mfma_f32_16x16x128_f8f6f4 v[154:157], v[26:33], v[182:189], 0
	v_mfma_f32_16x16x128_f8f6f4 v[122:125], v[10:17], v[182:189], 0
	v_mfma_f32_16x16x128_f8f6f4 v[126:129], v[2:9], v[182:189], 0
	v_mfma_f32_16x16x128_f8f6f4 v[118:121], v[2:9], v[202:209], 0
	v_mfma_f32_16x16x128_f8f6f4 v[114:117], v[10:17], v[202:209], 0
	v_mfma_f32_16x16x128_f8f6f4 v[146:149], v[26:33], v[202:209], 0
	v_mfma_f32_16x16x128_f8f6f4 v[150:153], v[18:25], v[202:209], 0
	s_setprio 0
	s_setprio 1
	v_mfma_f32_16x16x128_f8f6f4 v[142:145], v[18:25], v[210:217], 0
	v_mfma_f32_16x16x128_f8f6f4 v[138:141], v[26:33], v[210:217], 0
	v_mfma_f32_16x16x128_f8f6f4 v[106:109], v[10:17], v[210:217], 0
	v_mfma_f32_16x16x128_f8f6f4 v[110:113], v[2:9], v[210:217], 0
	v_mfma_f32_16x16x128_f8f6f4 v[102:105], v[2:9], v[218:225], 0
	v_mfma_f32_16x16x128_f8f6f4 v[98:101], v[10:17], v[218:225], 0
	v_mfma_f32_16x16x128_f8f6f4 v[130:133], v[26:33], v[218:225], 0
	v_mfma_f32_16x16x128_f8f6f4 v[134:137], v[18:25], v[218:225], 0
	s_barrier
	s_setprio 0
	ds_read_b128 v[202:205], v201 offset:16384
	ds_read_b128 v[206:209], v201 offset:17408
	ds_read_b128 v[210:213], v201 offset:18432
	ds_read_b128 v[214:217], v201 offset:19456
	ds_read_b128 v[218:221], v201 offset:20480
	ds_read_b128 v[222:225], v201 offset:21504
	ds_read_b128 v[226:229], v201 offset:22528
	ds_read_b128 v[230:233], v201 offset:23552
	v_lshl_add_u64 v[182:183], s[78:79], 0, v[164:165]
	s_mov_b32 m0, s68
	v_lshl_add_u64 v[184:185], v[182:183], 0, s[46:47]
	global_load_lds_dwordx4 v[184:185], off
	v_lshl_add_u64 v[184:185], s[78:79], 0, v[168:169]
	s_add_u32 s8, s78, 0x20100
	v_lshl_add_u64 v[186:187], v[184:185], 0, s[46:47]
	s_mov_b32 m0, s69
	s_addc_u32 s9, s79, 0
	global_load_lds_dwordx4 v[186:187], off
	v_lshl_add_u64 v[186:187], s[8:9], 0, v[164:165]
	s_mov_b32 m0, s77
	s_nop 0
	global_load_lds_dwordx4 v[186:187], off
	v_lshl_add_u64 v[186:187], s[8:9], 0, v[168:169]
	s_mov_b32 m0, s84
	s_nop 0
	global_load_lds_dwordx4 v[186:187], off
	v_lshl_add_u64 v[186:187], s[80:81], 0, v[162:163]
	v_lshl_add_u64 v[188:189], v[186:187], 0, s[46:47]
	s_mov_b32 m0, s33
	s_nop 0
	global_load_lds_dwordx4 v[188:189], off
	v_lshl_add_u64 v[188:189], s[80:81], 0, v[166:167]
	v_lshl_add_u64 v[234:235], v[188:189], 0, s[46:47]
	s_mov_b32 m0, s85
	s_nop 0
	global_load_lds_dwordx4 v[234:235], off
	s_waitcnt vmcnt(8)
	s_waitcnt lgkmcnt(0)
	s_setprio 1
	s_barrier
	v_mfma_f32_16x16x128_f8f6f4 v[94:97], v[18:25], v[202:209], 0
	v_mfma_f32_16x16x128_f8f6f4 v[90:93], v[26:33], v[202:209], 0
	v_mfma_f32_16x16x128_f8f6f4 v[58:61], v[10:17], v[202:209], 0
	v_mfma_f32_16x16x128_f8f6f4 v[62:65], v[2:9], v[202:209], 0
	v_mfma_f32_16x16x128_f8f6f4 v[54:57], v[2:9], v[210:217], 0
	v_mfma_f32_16x16x128_f8f6f4 v[50:53], v[10:17], v[210:217], 0
	v_mfma_f32_16x16x128_f8f6f4 v[82:85], v[26:33], v[210:217], 0
	v_mfma_f32_16x16x128_f8f6f4 v[86:89], v[18:25], v[210:217], 0
	s_setprio 0
	s_setprio 1
	v_mfma_f32_16x16x128_f8f6f4 v[78:81], v[18:25], v[218:225], 0
	v_mfma_f32_16x16x128_f8f6f4 v[74:77], v[26:33], v[218:225], 0
	v_mfma_f32_16x16x128_f8f6f4 v[42:45], v[10:17], v[218:225], 0
	v_mfma_f32_16x16x128_f8f6f4 v[46:49], v[2:9], v[218:225], 0
	v_mfma_f32_16x16x128_f8f6f4 v[38:41], v[2:9], v[226:233], 0
	v_mfma_f32_16x16x128_f8f6f4 v[34:37], v[10:17], v[226:233], 0
	v_mfma_f32_16x16x128_f8f6f4 v[66:69], v[26:33], v[226:233], 0
	v_mfma_f32_16x16x128_f8f6f4 v[70:73], v[18:25], v[226:233], 0
	s_barrier
	s_setprio 0
	ds_read_b128 v[18:21], v200 offset:32768
	ds_read_b128 v[22:25], v200 offset:33792
	ds_read_b128 v[26:29], v200 offset:34816
	ds_read_b128 v[30:33], v200 offset:35840
	ds_read_b128 v[2:5], v200 offset:49152
	ds_read_b128 v[6:9], v200 offset:50176
	ds_read_b128 v[10:13], v200 offset:51200
	ds_read_b128 v[14:17], v200 offset:52224
	ds_read_b128 v[202:205], v201 offset:32768
	ds_read_b128 v[206:209], v201 offset:33792
	ds_read_b128 v[210:213], v201 offset:34816
	ds_read_b128 v[214:217], v201 offset:35840
	ds_read_b128 v[218:221], v201 offset:36864
	ds_read_b128 v[222:225], v201 offset:37888
	ds_read_b128 v[226:229], v201 offset:38912
	ds_read_b128 v[230:233], v201 offset:39936
	s_add_u32 s8, s80, 0x20100
	s_addc_u32 s9, s81, 0
	s_mov_b32 m0, s86
	v_lshl_add_u64 v[234:235], s[8:9], 0, v[162:163]
	global_load_lds_dwordx4 v[234:235], off
	v_lshl_add_u64 v[234:235], s[8:9], 0, v[166:167]
	s_mov_b32 m0, s87
	s_nop 0
	global_load_lds_dwordx4 v[234:235], off
	s_waitcnt vmcnt(8)
	s_waitcnt lgkmcnt(0)
	s_setprio 1
	s_barrier
	v_mfma_f32_16x16x128_f8f6f4 v[158:161], v[18:25], v[202:209], v[158:161]
	v_mfma_f32_16x16x128_f8f6f4 v[154:157], v[26:33], v[202:209], v[154:157]
	v_mfma_f32_16x16x128_f8f6f4 v[122:125], v[10:17], v[202:209], v[122:125]
	v_mfma_f32_16x16x128_f8f6f4 v[126:129], v[2:9], v[202:209], v[126:129]
	v_mfma_f32_16x16x128_f8f6f4 v[118:121], v[2:9], v[210:217], v[118:121]
	v_mfma_f32_16x16x128_f8f6f4 v[114:117], v[10:17], v[210:217], v[114:117]
	v_mfma_f32_16x16x128_f8f6f4 v[146:149], v[26:33], v[210:217], v[146:149]
	v_mfma_f32_16x16x128_f8f6f4 v[150:153], v[18:25], v[210:217], v[150:153]
	s_setprio 0
	s_setprio 1
	v_mfma_f32_16x16x128_f8f6f4 v[142:145], v[18:25], v[218:225], v[142:145]
	v_mfma_f32_16x16x128_f8f6f4 v[138:141], v[26:33], v[218:225], v[138:141]
	v_mfma_f32_16x16x128_f8f6f4 v[106:109], v[10:17], v[218:225], v[106:109]
	v_mfma_f32_16x16x128_f8f6f4 v[110:113], v[2:9], v[218:225], v[110:113]
	v_mfma_f32_16x16x128_f8f6f4 v[102:105], v[2:9], v[226:233], v[102:105]
	v_mfma_f32_16x16x128_f8f6f4 v[98:101], v[10:17], v[226:233], v[98:101]
	v_mfma_f32_16x16x128_f8f6f4 v[130:133], v[26:33], v[226:233], v[130:133]
	v_mfma_f32_16x16x128_f8f6f4 v[134:137], v[18:25], v[226:233], v[134:137]
	s_barrier
	s_setprio 0
	ds_read_b128 v[202:205], v201 offset:49152
	ds_read_b128 v[206:209], v201 offset:50176
	ds_read_b128 v[210:213], v201 offset:51200
	ds_read_b128 v[214:217], v201 offset:52224
	ds_read_b128 v[218:221], v201 offset:53248
	ds_read_b128 v[222:225], v201 offset:54272
	ds_read_b128 v[226:229], v201 offset:55296
	ds_read_b128 v[230:233], v201 offset:56320
	s_mov_b32 m0, s89
	v_lshl_add_u64 v[182:183], v[182:183], 0, s[48:49]
	s_add_u32 s8, s78, 0x20180
	global_load_lds_dwordx4 v[182:183], off
	v_lshl_add_u64 v[182:183], v[184:185], 0, s[48:49]
	s_mov_b32 m0, s90
	s_addc_u32 s9, s79, 0
	global_load_lds_dwordx4 v[182:183], off
	v_lshl_add_u64 v[182:183], s[8:9], 0, v[164:165]
	s_mov_b32 m0, s93
	s_nop 0
	global_load_lds_dwordx4 v[182:183], off
	v_lshl_add_u64 v[182:183], s[8:9], 0, v[168:169]
	s_mov_b32 m0, s95
	s_nop 0
	global_load_lds_dwordx4 v[182:183], off
	v_lshl_add_u64 v[182:183], v[186:187], 0, s[48:49]
	s_mov_b32 m0, s91
	s_nop 0
	global_load_lds_dwordx4 v[182:183], off
	v_lshl_add_u64 v[182:183], v[188:189], 0, s[48:49]
	s_mov_b32 m0, s92
	s_nop 0
	global_load_lds_dwordx4 v[182:183], off
	s_waitcnt vmcnt(8)
	s_waitcnt lgkmcnt(0)
	s_setprio 1
	s_barrier
	v_mfma_f32_16x16x128_f8f6f4 v[94:97], v[18:25], v[202:209], v[94:97]
	v_mfma_f32_16x16x128_f8f6f4 v[90:93], v[26:33], v[202:209], v[90:93]
	v_mfma_f32_16x16x128_f8f6f4 v[58:61], v[10:17], v[202:209], v[58:61]
	v_mfma_f32_16x16x128_f8f6f4 v[62:65], v[2:9], v[202:209], v[62:65]
	v_mfma_f32_16x16x128_f8f6f4 v[54:57], v[2:9], v[210:217], v[54:57]
	v_mfma_f32_16x16x128_f8f6f4 v[50:53], v[10:17], v[210:217], v[50:53]
	v_mfma_f32_16x16x128_f8f6f4 v[82:85], v[26:33], v[210:217], v[82:85]
	v_mfma_f32_16x16x128_f8f6f4 v[86:89], v[18:25], v[210:217], v[86:89]
	s_setprio 0
	s_setprio 1
	v_mfma_f32_16x16x128_f8f6f4 v[78:81], v[18:25], v[218:225], v[78:81]
	v_mfma_f32_16x16x128_f8f6f4 v[74:77], v[26:33], v[218:225], v[74:77]
	v_mfma_f32_16x16x128_f8f6f4 v[42:45], v[10:17], v[218:225], v[42:45]
	v_mfma_f32_16x16x128_f8f6f4 v[46:49], v[2:9], v[218:225], v[46:49]
	v_mfma_f32_16x16x128_f8f6f4 v[38:41], v[2:9], v[226:233], v[38:41]
	v_mfma_f32_16x16x128_f8f6f4 v[34:37], v[10:17], v[226:233], v[34:37]
	v_mfma_f32_16x16x128_f8f6f4 v[66:69], v[26:33], v[226:233], v[66:69]
	v_mfma_f32_16x16x128_f8f6f4 v[70:73], v[18:25], v[226:233], v[70:73]
	s_barrier
	s_setprio 0
	s_add_u32 s80, s80, 0x20180
	s_addc_u32 s81, s81, 0
	s_add_u32 s8, s78, 0x200
	s_addc_u32 s9, s79, 0
	s_mov_b32 s62, 0
.LBB0_601:
	ds_read_b128 v[2:5], v200
	ds_read_b128 v[6:9], v200 offset:1024
	ds_read_b128 v[18:21], v200 offset:2048
	ds_read_b128 v[22:25], v200 offset:3072
	ds_read_b128 v[26:29], v200 offset:16384
	ds_read_b128 v[30:33], v200 offset:17408
	ds_read_b128 v[182:185], v200 offset:18432
	ds_read_b128 v[186:189], v200 offset:19456
	ds_read_b128 v[10:13], v201
	ds_read_b128 v[14:17], v201 offset:1024
	ds_read_b128 v[202:205], v201 offset:2048
	ds_read_b128 v[206:209], v201 offset:3072
	ds_read_b128 v[210:213], v201 offset:4096
	ds_read_b128 v[214:217], v201 offset:5120
	ds_read_b128 v[218:221], v201 offset:6144
	ds_read_b128 v[222:225], v201 offset:7168
	s_add_u32 s63, s80, 0xfffe0080
	s_addc_u32 s71, s81, -1
	s_cmp_eq_u32 s62, 4
	s_cselect_b32 s83, s4, s71
	s_cselect_b32 s82, s5, s63
	s_cselect_b32 s79, s53, s9
	s_cselect_b32 s78, s55, s8
	s_mov_b32 m0, s96
	v_lshl_add_u64 v[226:227], s[80:81], 0, v[170:171]
	global_load_lds_dwordx4 v[226:227], off
	v_lshl_add_u64 v[226:227], s[80:81], 0, v[172:173]
	s_mov_b32 m0, s61
	s_nop 0
	global_load_lds_dwordx4 v[226:227], off
	s_waitcnt vmcnt(8)
	s_waitcnt lgkmcnt(0)
	s_setprio 1
	s_barrier
	v_mfma_f32_16x16x128_f8f6f4 v[158:161], v[2:9], v[10:17], v[158:161]
	v_mfma_f32_16x16x128_f8f6f4 v[154:157], v[18:25], v[10:17], v[154:157]
	v_mfma_f32_16x16x128_f8f6f4 v[122:125], v[182:189], v[10:17], v[122:125]
	v_mfma_f32_16x16x128_f8f6f4 v[126:129], v[26:33], v[10:17], v[126:129]
	v_mfma_f32_16x16x128_f8f6f4 v[118:121], v[26:33], v[202:209], v[118:121]
	v_mfma_f32_16x16x128_f8f6f4 v[114:117], v[182:189], v[202:209], v[114:117]
	v_mfma_f32_16x16x128_f8f6f4 v[146:149], v[18:25], v[202:209], v[146:149]
	v_mfma_f32_16x16x128_f8f6f4 v[150:153], v[2:9], v[202:209], v[150:153]
	s_setprio 0
	s_setprio 1
	v_mfma_f32_16x16x128_f8f6f4 v[142:145], v[2:9], v[210:217], v[142:145]
	v_mfma_f32_16x16x128_f8f6f4 v[138:141], v[18:25], v[210:217], v[138:141]
	v_mfma_f32_16x16x128_f8f6f4 v[106:109], v[182:189], v[210:217], v[106:109]
	v_mfma_f32_16x16x128_f8f6f4 v[110:113], v[26:33], v[210:217], v[110:113]
	v_mfma_f32_16x16x128_f8f6f4 v[102:105], v[26:33], v[218:225], v[102:105]
	v_mfma_f32_16x16x128_f8f6f4 v[98:101], v[182:189], v[218:225], v[98:101]
	v_mfma_f32_16x16x128_f8f6f4 v[130:133], v[18:25], v[218:225], v[130:133]
	v_mfma_f32_16x16x128_f8f6f4 v[134:137], v[2:9], v[218:225], v[134:137]
	s_barrier
	s_setprio 0
	ds_read_b128 v[202:205], v201 offset:16384
	ds_read_b128 v[206:209], v201 offset:17408
	ds_read_b128 v[210:213], v201 offset:18432
	ds_read_b128 v[214:217], v201 offset:19456
	ds_read_b128 v[218:221], v201 offset:20480
	ds_read_b128 v[222:225], v201 offset:21504
	ds_read_b128 v[226:229], v201 offset:22528
	ds_read_b128 v[230:233], v201 offset:23552
	s_mov_b32 m0, s68
	v_lshl_add_u64 v[10:11], s[78:79], 0, v[164:165]
	s_add_u32 vcc_lo, s78, 0x20000
	global_load_lds_dwordx4 v[10:11], off
	v_lshl_add_u64 v[12:13], s[78:79], 0, v[168:169]
	s_mov_b32 m0, s69
	s_addc_u32 vcc_hi, s79, 0
	global_load_lds_dwordx4 v[12:13], off
	v_lshl_add_u64 v[14:15], vcc, 0, v[164:165]
	s_mov_b32 m0, s77
	v_lshl_add_u64 v[16:17], s[82:83], 0, v[166:167]
	global_load_lds_dwordx4 v[14:15], off
	v_lshl_add_u64 v[14:15], vcc, 0, v[168:169]
	s_mov_b32 m0, s84
	s_nop 0
	global_load_lds_dwordx4 v[14:15], off
	v_lshl_add_u64 v[14:15], s[82:83], 0, v[162:163]
	s_mov_b32 m0, s33
	s_nop 0
	global_load_lds_dwordx4 v[14:15], off
	s_mov_b32 m0, s85
	s_nop 0
	global_load_lds_dwordx4 v[16:17], off
	s_waitcnt vmcnt(8)
	s_waitcnt lgkmcnt(0)
	s_setprio 1
	s_barrier
	v_mfma_f32_16x16x128_f8f6f4 v[94:97], v[2:9], v[202:209], v[94:97]
	v_mfma_f32_16x16x128_f8f6f4 v[90:93], v[18:25], v[202:209], v[90:93]
	v_mfma_f32_16x16x128_f8f6f4 v[58:61], v[182:189], v[202:209], v[58:61]
	v_mfma_f32_16x16x128_f8f6f4 v[62:65], v[26:33], v[202:209], v[62:65]
	v_mfma_f32_16x16x128_f8f6f4 v[54:57], v[26:33], v[210:217], v[54:57]
	v_mfma_f32_16x16x128_f8f6f4 v[50:53], v[182:189], v[210:217], v[50:53]
	v_mfma_f32_16x16x128_f8f6f4 v[82:85], v[18:25], v[210:217], v[82:85]
	v_mfma_f32_16x16x128_f8f6f4 v[86:89], v[2:9], v[210:217], v[86:89]
	s_setprio 0
	s_setprio 1
	v_mfma_f32_16x16x128_f8f6f4 v[78:81], v[2:9], v[218:225], v[78:81]
	v_mfma_f32_16x16x128_f8f6f4 v[74:77], v[18:25], v[218:225], v[74:77]
	v_mfma_f32_16x16x128_f8f6f4 v[42:45], v[182:189], v[218:225], v[42:45]
	v_mfma_f32_16x16x128_f8f6f4 v[46:49], v[26:33], v[218:225], v[46:49]
	v_mfma_f32_16x16x128_f8f6f4 v[38:41], v[26:33], v[226:233], v[38:41]
	v_mfma_f32_16x16x128_f8f6f4 v[34:37], v[182:189], v[226:233], v[34:37]
	v_mfma_f32_16x16x128_f8f6f4 v[66:69], v[18:25], v[226:233], v[66:69]
	v_mfma_f32_16x16x128_f8f6f4 v[70:73], v[2:9], v[226:233], v[70:73]
	s_barrier
	s_setprio 0
	ds_read_b128 v[18:21], v200 offset:32768
	ds_read_b128 v[22:25], v200 offset:33792
	ds_read_b128 v[26:29], v200 offset:34816
	ds_read_b128 v[30:33], v200 offset:35840
	ds_read_b128 v[2:5], v200 offset:49152
	ds_read_b128 v[6:9], v200 offset:50176
	ds_read_b128 v[182:185], v200 offset:51200
	ds_read_b128 v[186:189], v200 offset:52224
	ds_read_b128 v[202:205], v201 offset:32768
	ds_read_b128 v[206:209], v201 offset:33792
	ds_read_b128 v[210:213], v201 offset:34816
	ds_read_b128 v[214:217], v201 offset:35840
	ds_read_b128 v[218:221], v201 offset:36864
	ds_read_b128 v[222:225], v201 offset:37888
	ds_read_b128 v[226:229], v201 offset:38912
	ds_read_b128 v[230:233], v201 offset:39936
	s_add_u32 s82, s82, 0x20000
	s_addc_u32 s83, s83, 0
	s_mov_b32 m0, s86
	v_lshl_add_u64 v[234:235], s[82:83], 0, v[162:163]
	global_load_lds_dwordx4 v[234:235], off
	v_lshl_add_u64 v[234:235], s[82:83], 0, v[166:167]
	s_mov_b32 m0, s87
	s_nop 0
	global_load_lds_dwordx4 v[234:235], off
	s_waitcnt vmcnt(8)
	s_waitcnt lgkmcnt(0)
	s_setprio 1
	s_barrier
	v_mfma_f32_16x16x128_f8f6f4 v[158:161], v[18:25], v[202:209], v[158:161]
	v_mfma_f32_16x16x128_f8f6f4 v[154:157], v[26:33], v[202:209], v[154:157]
	v_mfma_f32_16x16x128_f8f6f4 v[122:125], v[182:189], v[202:209], v[122:125]
	v_mfma_f32_16x16x128_f8f6f4 v[126:129], v[2:9], v[202:209], v[126:129]
	v_mfma_f32_16x16x128_f8f6f4 v[118:121], v[2:9], v[210:217], v[118:121]
	v_mfma_f32_16x16x128_f8f6f4 v[114:117], v[182:189], v[210:217], v[114:117]
	v_mfma_f32_16x16x128_f8f6f4 v[146:149], v[26:33], v[210:217], v[146:149]
	v_mfma_f32_16x16x128_f8f6f4 v[150:153], v[18:25], v[210:217], v[150:153]
	s_setprio 0
	s_setprio 1
	v_mfma_f32_16x16x128_f8f6f4 v[142:145], v[18:25], v[218:225], v[142:145]
	v_mfma_f32_16x16x128_f8f6f4 v[138:141], v[26:33], v[218:225], v[138:141]
	v_mfma_f32_16x16x128_f8f6f4 v[106:109], v[182:189], v[218:225], v[106:109]
	v_mfma_f32_16x16x128_f8f6f4 v[110:113], v[2:9], v[218:225], v[110:113]
	v_mfma_f32_16x16x128_f8f6f4 v[102:105], v[2:9], v[226:233], v[102:105]
	v_mfma_f32_16x16x128_f8f6f4 v[98:101], v[182:189], v[226:233], v[98:101]
	v_mfma_f32_16x16x128_f8f6f4 v[130:133], v[26:33], v[226:233], v[130:133]
	v_mfma_f32_16x16x128_f8f6f4 v[134:137], v[18:25], v[226:233], v[134:137]
	s_barrier
	s_setprio 0
	ds_read_b128 v[202:205], v201 offset:49152
	ds_read_b128 v[206:209], v201 offset:50176
	ds_read_b128 v[210:213], v201 offset:51200
	ds_read_b128 v[214:217], v201 offset:52224
	ds_read_b128 v[218:221], v201 offset:53248
	ds_read_b128 v[222:225], v201 offset:54272
	ds_read_b128 v[226:229], v201 offset:55296
	ds_read_b128 v[230:233], v201 offset:56320
	s_mov_b32 m0, s89
	v_lshl_add_u64 v[10:11], v[10:11], 0, s[42:43]
	s_add_u32 s78, s78, 0x20080
	global_load_lds_dwordx4 v[10:11], off
	v_lshl_add_u64 v[10:11], v[12:13], 0, s[42:43]
	s_mov_b32 m0, s90
	s_addc_u32 s79, s79, 0
	global_load_lds_dwordx4 v[10:11], off
	v_lshl_add_u64 v[10:11], s[78:79], 0, v[164:165]
	s_mov_b32 m0, s93
	s_nop 0
	global_load_lds_dwordx4 v[10:11], off
	v_lshl_add_u64 v[10:11], s[78:79], 0, v[168:169]
	s_mov_b32 m0, s95
	s_nop 0
	global_load_lds_dwordx4 v[10:11], off
	v_lshl_add_u64 v[10:11], v[14:15], 0, s[42:43]
	s_mov_b32 m0, s91
	s_nop 0
	global_load_lds_dwordx4 v[10:11], off
	v_lshl_add_u64 v[10:11], v[16:17], 0, s[42:43]
	s_mov_b32 m0, s92
	s_nop 0
	global_load_lds_dwordx4 v[10:11], off
	s_waitcnt vmcnt(8)
	s_waitcnt lgkmcnt(0)
	s_setprio 1
	s_barrier
	v_mfma_f32_16x16x128_f8f6f4 v[94:97], v[18:25], v[202:209], v[94:97]
	v_mfma_f32_16x16x128_f8f6f4 v[90:93], v[26:33], v[202:209], v[90:93]
	v_mfma_f32_16x16x128_f8f6f4 v[58:61], v[182:189], v[202:209], v[58:61]
	v_mfma_f32_16x16x128_f8f6f4 v[62:65], v[2:9], v[202:209], v[62:65]
	v_mfma_f32_16x16x128_f8f6f4 v[54:57], v[2:9], v[210:217], v[54:57]
	v_mfma_f32_16x16x128_f8f6f4 v[50:53], v[182:189], v[210:217], v[50:53]
	v_mfma_f32_16x16x128_f8f6f4 v[82:85], v[26:33], v[210:217], v[82:85]
	v_mfma_f32_16x16x128_f8f6f4 v[86:89], v[18:25], v[210:217], v[86:89]
	s_setprio 0
	s_setprio 1
	v_mfma_f32_16x16x128_f8f6f4 v[78:81], v[18:25], v[218:225], v[78:81]
	v_mfma_f32_16x16x128_f8f6f4 v[74:77], v[26:33], v[218:225], v[74:77]
	v_mfma_f32_16x16x128_f8f6f4 v[42:45], v[182:189], v[218:225], v[42:45]
	v_mfma_f32_16x16x128_f8f6f4 v[46:49], v[2:9], v[218:225], v[46:49]
	v_mfma_f32_16x16x128_f8f6f4 v[38:41], v[2:9], v[226:233], v[38:41]
	v_mfma_f32_16x16x128_f8f6f4 v[34:37], v[182:189], v[226:233], v[34:37]
	v_mfma_f32_16x16x128_f8f6f4 v[66:69], v[26:33], v[226:233], v[66:69]
	v_mfma_f32_16x16x128_f8f6f4 v[70:73], v[18:25], v[226:233], v[70:73]
	s_barrier
	s_setprio 0
	s_add_i32 s62, s62, 2
	s_add_u32 s80, s80, 0x100
	s_addc_u32 s81, s81, 0
	s_add_u32 s8, s8, 0x100
	s_addc_u32 s9, s9, 0
	s_cmp_gt_u32 s62, 5
	s_cbranch_scc0 .LBB0_601
	s_and_b64 vcc, exec, s[44:45]
	s_cbranch_vccz .LBB0_604
	s_barrier

.LBB0_616:
	ds_read_b128 v[18:21], v188
	ds_read_b128 v[22:25], v188 offset:1024
	ds_read_b128 v[26:29], v188 offset:2048
	ds_read_b128 v[30:33], v188 offset:3072
	ds_read_b128 v[2:5], v188 offset:16384
	ds_read_b128 v[6:9], v188 offset:17408
	ds_read_b128 v[10:13], v188 offset:18432
	ds_read_b128 v[14:17], v188 offset:19456
	s_ashr_i32 s55, s54, 31
	s_lshl_b64 s[62:63], s[54:55], 17
	s_add_u32 s72, s36, s62
	s_addc_u32 s73, s37, s63
	s_and_b64 s[62:63], s[2:3], exec
	s_cselect_b32 s85, s73, s79
	s_cselect_b32 s84, s72, s78
	s_ashr_i32 s53, s52, 31
	s_lshl_b64 s[62:63], s[52:53], 17
	s_add_u32 s74, s94, s62
	v_readlane_b32 s5, v254, 8
	s_addc_u32 s75, s5, s63
	s_and_b64 s[62:63], s[2:3], exec
	s_cselect_b32 s83, s75, s81
	s_cselect_b32 s82, s74, s80
	s_add_u32 s62, s78, 0x10080
	s_addc_u32 s63, s79, 0
	s_mov_b32 m0, s96
	v_lshl_add_u64 v[174:175], s[62:63], 0, v[166:167]
	ds_read_b128 v[196:199], v189
	ds_read_b128 v[200:203], v189 offset:1024
	ds_read_b128 v[204:207], v189 offset:2048
	ds_read_b128 v[208:211], v189 offset:3072
	ds_read_b128 v[212:215], v189 offset:4096
	ds_read_b128 v[216:219], v189 offset:5120
	ds_read_b128 v[220:223], v189 offset:6144
	ds_read_b128 v[224:227], v189 offset:7168
	global_load_lds_dwordx4 v[174:175], off
	v_lshl_add_u64 v[174:175], s[62:63], 0, v[168:169]
	s_mov_b32 m0, s97
	s_nop 0
	global_load_lds_dwordx4 v[174:175], off
	s_waitcnt vmcnt(8)
	s_waitcnt lgkmcnt(0)
	s_setprio 1
	s_barrier
	v_mfma_f32_16x16x128_f8f6f4 v[158:161], v[18:25], v[196:203], 0
	v_mfma_f32_16x16x128_f8f6f4 v[154:157], v[26:33], v[196:203], 0
	v_mfma_f32_16x16x128_f8f6f4 v[122:125], v[10:17], v[196:203], 0
	v_mfma_f32_16x16x128_f8f6f4 v[126:129], v[2:9], v[196:203], 0
	v_mfma_f32_16x16x128_f8f6f4 v[118:121], v[2:9], v[204:211], 0
	v_mfma_f32_16x16x128_f8f6f4 v[114:117], v[10:17], v[204:211], 0
	v_mfma_f32_16x16x128_f8f6f4 v[146:149], v[26:33], v[204:211], 0
	v_mfma_f32_16x16x128_f8f6f4 v[150:153], v[18:25], v[204:211], 0
	s_setprio 0
	s_setprio 1
	v_mfma_f32_16x16x128_f8f6f4 v[142:145], v[18:25], v[212:219], 0
	v_mfma_f32_16x16x128_f8f6f4 v[138:141], v[26:33], v[212:219], 0
	v_mfma_f32_16x16x128_f8f6f4 v[106:109], v[10:17], v[212:219], 0
	v_mfma_f32_16x16x128_f8f6f4 v[110:113], v[2:9], v[212:219], 0
	v_mfma_f32_16x16x128_f8f6f4 v[102:105], v[2:9], v[220:227], 0
	v_mfma_f32_16x16x128_f8f6f4 v[98:101], v[10:17], v[220:227], 0
	v_mfma_f32_16x16x128_f8f6f4 v[130:133], v[26:33], v[220:227], 0
	v_mfma_f32_16x16x128_f8f6f4 v[134:137], v[18:25], v[220:227], 0
	s_barrier
	s_setprio 0
	ds_read_b128 v[196:199], v189 offset:16384
	ds_read_b128 v[200:203], v189 offset:17408
	ds_read_b128 v[204:207], v189 offset:18432
	ds_read_b128 v[208:211], v189 offset:19456
	ds_read_b128 v[212:215], v189 offset:20480
	ds_read_b128 v[216:219], v189 offset:21504
	ds_read_b128 v[220:223], v189 offset:22528
	ds_read_b128 v[224:227], v189 offset:23552
	v_lshl_add_u64 v[174:175], s[80:81], 0, v[162:163]
	s_mov_b32 m0, s61
	v_lshl_add_u64 v[176:177], v[174:175], 0, s[46:47]
	global_load_lds_dwordx4 v[176:177], off
	v_lshl_add_u64 v[176:177], s[80:81], 0, v[164:165]
	s_add_u32 s62, s80, 0x10100
	v_lshl_add_u64 v[182:183], v[176:177], 0, s[46:47]
	s_mov_b32 m0, s68
	s_addc_u32 s63, s81, 0
	global_load_lds_dwordx4 v[182:183], off
	v_lshl_add_u64 v[182:183], s[62:63], 0, v[162:163]
	s_mov_b32 m0, s69
	s_nop 0
	global_load_lds_dwordx4 v[182:183], off
	v_lshl_add_u64 v[182:183], s[62:63], 0, v[164:165]
	s_mov_b32 m0, s77
	s_nop 0
	global_load_lds_dwordx4 v[182:183], off
	v_lshl_add_u64 v[182:183], s[78:79], 0, v[166:167]
	v_lshl_add_u64 v[184:185], v[182:183], 0, s[46:47]
	s_mov_b32 m0, s51
	s_nop 0
	global_load_lds_dwordx4 v[184:185], off
	v_lshl_add_u64 v[184:185], s[78:79], 0, v[168:169]
	v_lshl_add_u64 v[228:229], v[184:185], 0, s[46:47]
	s_mov_b32 m0, s86
	s_nop 0
	global_load_lds_dwordx4 v[228:229], off
	s_waitcnt vmcnt(8)
	s_waitcnt lgkmcnt(0)
	s_setprio 1
	s_barrier
	v_mfma_f32_16x16x128_f8f6f4 v[94:97], v[18:25], v[196:203], 0
	v_mfma_f32_16x16x128_f8f6f4 v[90:93], v[26:33], v[196:203], 0
	v_mfma_f32_16x16x128_f8f6f4 v[58:61], v[10:17], v[196:203], 0
	v_mfma_f32_16x16x128_f8f6f4 v[62:65], v[2:9], v[196:203], 0
	v_mfma_f32_16x16x128_f8f6f4 v[54:57], v[2:9], v[204:211], 0
	v_mfma_f32_16x16x128_f8f6f4 v[50:53], v[10:17], v[204:211], 0
	v_mfma_f32_16x16x128_f8f6f4 v[82:85], v[26:33], v[204:211], 0
	v_mfma_f32_16x16x128_f8f6f4 v[86:89], v[18:25], v[204:211], 0
	s_setprio 0
	s_setprio 1
	v_mfma_f32_16x16x128_f8f6f4 v[78:81], v[18:25], v[212:219], 0
	v_mfma_f32_16x16x128_f8f6f4 v[74:77], v[26:33], v[212:219], 0
	v_mfma_f32_16x16x128_f8f6f4 v[42:45], v[10:17], v[212:219], 0
	v_mfma_f32_16x16x128_f8f6f4 v[46:49], v[2:9], v[212:219], 0
	v_mfma_f32_16x16x128_f8f6f4 v[38:41], v[2:9], v[220:227], 0
	v_mfma_f32_16x16x128_f8f6f4 v[34:37], v[10:17], v[220:227], 0
	v_mfma_f32_16x16x128_f8f6f4 v[66:69], v[26:33], v[220:227], 0
	v_mfma_f32_16x16x128_f8f6f4 v[70:73], v[18:25], v[220:227], 0
	s_barrier
	s_setprio 0
	ds_read_b128 v[2:5], v188 offset:32768
	ds_read_b128 v[6:9], v188 offset:33792
	ds_read_b128 v[10:13], v188 offset:34816
	ds_read_b128 v[14:17], v188 offset:35840
	ds_read_b128 v[18:21], v188 offset:49152
	ds_read_b128 v[22:25], v188 offset:50176
	ds_read_b128 v[26:29], v188 offset:51200
	ds_read_b128 v[30:33], v188 offset:52224
	ds_read_b128 v[196:199], v189 offset:32768
	ds_read_b128 v[200:203], v189 offset:33792
	ds_read_b128 v[204:207], v189 offset:34816
	ds_read_b128 v[208:211], v189 offset:35840
	ds_read_b128 v[212:215], v189 offset:36864
	ds_read_b128 v[216:219], v189 offset:37888
	ds_read_b128 v[220:223], v189 offset:38912
	ds_read_b128 v[224:227], v189 offset:39936
	s_add_u32 s62, s78, 0x10100
	s_addc_u32 s63, s79, 0
	s_mov_b32 m0, s87
	v_lshl_add_u64 v[228:229], s[62:63], 0, v[166:167]
	global_load_lds_dwordx4 v[228:229], off
	v_lshl_add_u64 v[228:229], s[62:63], 0, v[168:169]
	s_mov_b32 m0, s88
	s_nop 0
	global_load_lds_dwordx4 v[228:229], off
	s_waitcnt vmcnt(8)
	s_waitcnt lgkmcnt(0)
	s_setprio 1
	s_barrier
	v_mfma_f32_16x16x128_f8f6f4 v[158:161], v[2:9], v[196:203], v[158:161]
	v_mfma_f32_16x16x128_f8f6f4 v[154:157], v[10:17], v[196:203], v[154:157]
	v_mfma_f32_16x16x128_f8f6f4 v[122:125], v[26:33], v[196:203], v[122:125]
	v_mfma_f32_16x16x128_f8f6f4 v[126:129], v[18:25], v[196:203], v[126:129]
	v_mfma_f32_16x16x128_f8f6f4 v[118:121], v[18:25], v[204:211], v[118:121]
	v_mfma_f32_16x16x128_f8f6f4 v[114:117], v[26:33], v[204:211], v[114:117]
	v_mfma_f32_16x16x128_f8f6f4 v[146:149], v[10:17], v[204:211], v[146:149]
	v_mfma_f32_16x16x128_f8f6f4 v[150:153], v[2:9], v[204:211], v[150:153]
	s_setprio 0
	s_setprio 1
	v_mfma_f32_16x16x128_f8f6f4 v[142:145], v[2:9], v[212:219], v[142:145]
	v_mfma_f32_16x16x128_f8f6f4 v[138:141], v[10:17], v[212:219], v[138:141]
	v_mfma_f32_16x16x128_f8f6f4 v[106:109], v[26:33], v[212:219], v[106:109]
	v_mfma_f32_16x16x128_f8f6f4 v[110:113], v[18:25], v[212:219], v[110:113]
	v_mfma_f32_16x16x128_f8f6f4 v[102:105], v[18:25], v[220:227], v[102:105]
	v_mfma_f32_16x16x128_f8f6f4 v[98:101], v[26:33], v[220:227], v[98:101]
	v_mfma_f32_16x16x128_f8f6f4 v[130:133], v[10:17], v[220:227], v[130:133]
	v_mfma_f32_16x16x128_f8f6f4 v[134:137], v[2:9], v[220:227], v[134:137]
	s_barrier
	s_setprio 0
	ds_read_b128 v[196:199], v189 offset:49152
	ds_read_b128 v[200:203], v189 offset:50176
	ds_read_b128 v[204:207], v189 offset:51200
	ds_read_b128 v[208:211], v189 offset:52224
	ds_read_b128 v[212:215], v189 offset:53248
	ds_read_b128 v[216:219], v189 offset:54272
	ds_read_b128 v[220:223], v189 offset:55296
	ds_read_b128 v[224:227], v189 offset:56320
	s_mov_b32 m0, s89
	v_lshl_add_u64 v[174:175], v[174:175], 0, s[48:49]
	s_add_u32 s62, s80, 0x10180
	global_load_lds_dwordx4 v[174:175], off
	v_lshl_add_u64 v[174:175], v[176:177], 0, s[48:49]
	s_mov_b32 m0, s90
	s_addc_u32 s63, s81, 0
	global_load_lds_dwordx4 v[174:175], off
	v_lshl_add_u64 v[174:175], s[62:63], 0, v[162:163]
	s_mov_b32 m0, s93
	s_nop 0
	global_load_lds_dwordx4 v[174:175], off
	v_lshl_add_u64 v[174:175], s[62:63], 0, v[164:165]
	s_mov_b32 m0, s95
	s_nop 0
	global_load_lds_dwordx4 v[174:175], off
	v_lshl_add_u64 v[174:175], v[182:183], 0, s[48:49]
	s_mov_b32 m0, s91
	s_nop 0
	global_load_lds_dwordx4 v[174:175], off
	v_lshl_add_u64 v[174:175], v[184:185], 0, s[48:49]
	s_mov_b32 m0, s92
	s_nop 0
	global_load_lds_dwordx4 v[174:175], off
	s_waitcnt vmcnt(8)
	s_waitcnt lgkmcnt(0)
	s_setprio 1
	s_barrier
	v_mfma_f32_16x16x128_f8f6f4 v[94:97], v[2:9], v[196:203], v[94:97]
	v_mfma_f32_16x16x128_f8f6f4 v[90:93], v[10:17], v[196:203], v[90:93]
	v_mfma_f32_16x16x128_f8f6f4 v[58:61], v[26:33], v[196:203], v[58:61]
	v_mfma_f32_16x16x128_f8f6f4 v[62:65], v[18:25], v[196:203], v[62:65]
	v_mfma_f32_16x16x128_f8f6f4 v[54:57], v[18:25], v[204:211], v[54:57]
	v_mfma_f32_16x16x128_f8f6f4 v[50:53], v[26:33], v[204:211], v[50:53]
	v_mfma_f32_16x16x128_f8f6f4 v[82:85], v[10:17], v[204:211], v[82:85]
	v_mfma_f32_16x16x128_f8f6f4 v[86:89], v[2:9], v[204:211], v[86:89]
	s_setprio 0
	s_setprio 1
	v_mfma_f32_16x16x128_f8f6f4 v[78:81], v[2:9], v[212:219], v[78:81]
	v_mfma_f32_16x16x128_f8f6f4 v[74:77], v[10:17], v[212:219], v[74:77]
	v_mfma_f32_16x16x128_f8f6f4 v[42:45], v[26:33], v[212:219], v[42:45]
	v_mfma_f32_16x16x128_f8f6f4 v[46:49], v[18:25], v[212:219], v[46:49]
	v_mfma_f32_16x16x128_f8f6f4 v[38:41], v[18:25], v[220:227], v[38:41]
	v_mfma_f32_16x16x128_f8f6f4 v[34:37], v[26:33], v[220:227], v[34:37]
	v_mfma_f32_16x16x128_f8f6f4 v[66:69], v[10:17], v[220:227], v[66:69]
	v_mfma_f32_16x16x128_f8f6f4 v[70:73], v[2:9], v[220:227], v[70:73]
	s_barrier
	s_setprio 0
	ds_read_b128 v[2:5], v188
	ds_read_b128 v[6:9], v188 offset:1024
	ds_read_b128 v[10:13], v188 offset:2048
	ds_read_b128 v[14:17], v188 offset:3072
	ds_read_b128 v[18:21], v188 offset:16384
	ds_read_b128 v[22:25], v188 offset:17408
	ds_read_b128 v[26:29], v188 offset:18432
	ds_read_b128 v[30:33], v188 offset:19456
	ds_read_b128 v[196:199], v189
	ds_read_b128 v[200:203], v189 offset:1024
	ds_read_b128 v[204:207], v189 offset:2048
	ds_read_b128 v[208:211], v189 offset:3072
	ds_read_b128 v[212:215], v189 offset:4096
	ds_read_b128 v[216:219], v189 offset:5120
	ds_read_b128 v[220:223], v189 offset:6144
	ds_read_b128 v[224:227], v189 offset:7168
	s_add_u32 s62, s78, 0x10180
	s_addc_u32 s63, s79, 0
	s_mov_b32 m0, s96
	v_lshl_add_u64 v[174:175], s[62:63], 0, v[166:167]
	global_load_lds_dwordx4 v[174:175], off
	v_lshl_add_u64 v[174:175], s[62:63], 0, v[168:169]
	s_mov_b32 m0, s97
	s_nop 0
	global_load_lds_dwordx4 v[174:175], off
	s_waitcnt vmcnt(8)
	s_waitcnt lgkmcnt(0)
	s_setprio 1
	s_barrier
	v_mfma_f32_16x16x128_f8f6f4 v[158:161], v[2:9], v[196:203], v[158:161]
	v_mfma_f32_16x16x128_f8f6f4 v[154:157], v[10:17], v[196:203], v[154:157]
	v_mfma_f32_16x16x128_f8f6f4 v[122:125], v[26:33], v[196:203], v[122:125]
	v_mfma_f32_16x16x128_f8f6f4 v[126:129], v[18:25], v[196:203], v[126:129]
	v_mfma_f32_16x16x128_f8f6f4 v[118:121], v[18:25], v[204:211], v[118:121]
	v_mfma_f32_16x16x128_f8f6f4 v[114:117], v[26:33], v[204:211], v[114:117]
	v_mfma_f32_16x16x128_f8f6f4 v[146:149], v[10:17], v[204:211], v[146:149]
	v_mfma_f32_16x16x128_f8f6f4 v[150:153], v[2:9], v[204:211], v[150:153]
	s_setprio 0
	s_setprio 1
	v_mfma_f32_16x16x128_f8f6f4 v[142:145], v[2:9], v[212:219], v[142:145]
	v_mfma_f32_16x16x128_f8f6f4 v[138:141], v[10:17], v[212:219], v[138:141]
	v_mfma_f32_16x16x128_f8f6f4 v[106:109], v[26:33], v[212:219], v[106:109]
	v_mfma_f32_16x16x128_f8f6f4 v[110:113], v[18:25], v[212:219], v[110:113]
	v_mfma_f32_16x16x128_f8f6f4 v[102:105], v[18:25], v[220:227], v[102:105]
	v_mfma_f32_16x16x128_f8f6f4 v[98:101], v[26:33], v[220:227], v[98:101]
	v_mfma_f32_16x16x128_f8f6f4 v[130:133], v[10:17], v[220:227], v[130:133]
	v_mfma_f32_16x16x128_f8f6f4 v[134:137], v[2:9], v[220:227], v[134:137]
	s_barrier
	s_setprio 0
	ds_read_b128 v[196:199], v189 offset:16384
	ds_read_b128 v[200:203], v189 offset:17408
	ds_read_b128 v[204:207], v189 offset:18432
	ds_read_b128 v[208:211], v189 offset:19456
	ds_read_b128 v[212:215], v189 offset:20480
	ds_read_b128 v[216:219], v189 offset:21504
	ds_read_b128 v[220:223], v189 offset:22528
	ds_read_b128 v[224:227], v189 offset:23552
	s_mov_b32 m0, s61
	v_lshl_add_u64 v[174:175], s[82:83], 0, v[162:163]
	s_add_u32 s62, s82, 0x10000
	global_load_lds_dwordx4 v[174:175], off
	v_lshl_add_u64 v[176:177], s[82:83], 0, v[164:165]
	s_mov_b32 m0, s68
	s_addc_u32 s63, s83, 0
	global_load_lds_dwordx4 v[176:177], off
	v_lshl_add_u64 v[182:183], s[62:63], 0, v[162:163]
	s_mov_b32 m0, s69
	v_lshl_add_u64 v[184:185], s[84:85], 0, v[168:169]
	global_load_lds_dwordx4 v[182:183], off
	v_lshl_add_u64 v[182:183], s[62:63], 0, v[164:165]
	s_mov_b32 m0, s77
	s_nop 0
	global_load_lds_dwordx4 v[182:183], off
	v_lshl_add_u64 v[182:183], s[84:85], 0, v[166:167]
	s_mov_b32 m0, s51
	s_nop 0
	global_load_lds_dwordx4 v[182:183], off
	s_mov_b32 m0, s86
	s_nop 0
	global_load_lds_dwordx4 v[184:185], off
	s_waitcnt vmcnt(8)
	s_waitcnt lgkmcnt(0)
	s_setprio 1
	s_barrier
	v_mfma_f32_16x16x128_f8f6f4 v[94:97], v[2:9], v[196:203], v[94:97]
	v_mfma_f32_16x16x128_f8f6f4 v[90:93], v[10:17], v[196:203], v[90:93]
	v_mfma_f32_16x16x128_f8f6f4 v[58:61], v[26:33], v[196:203], v[58:61]
	v_mfma_f32_16x16x128_f8f6f4 v[62:65], v[18:25], v[196:203], v[62:65]
	v_mfma_f32_16x16x128_f8f6f4 v[54:57], v[18:25], v[204:211], v[54:57]
	v_mfma_f32_16x16x128_f8f6f4 v[50:53], v[26:33], v[204:211], v[50:53]
	v_mfma_f32_16x16x128_f8f6f4 v[82:85], v[10:17], v[204:211], v[82:85]
	v_mfma_f32_16x16x128_f8f6f4 v[86:89], v[2:9], v[204:211], v[86:89]
	s_setprio 0
	s_setprio 1
	v_mfma_f32_16x16x128_f8f6f4 v[78:81], v[2:9], v[212:219], v[78:81]
	v_mfma_f32_16x16x128_f8f6f4 v[74:77], v[10:17], v[212:219], v[74:77]
	v_mfma_f32_16x16x128_f8f6f4 v[42:45], v[26:33], v[212:219], v[42:45]
	v_mfma_f32_16x16x128_f8f6f4 v[46:49], v[18:25], v[212:219], v[46:49]
	v_mfma_f32_16x16x128_f8f6f4 v[38:41], v[18:25], v[220:227], v[38:41]
	v_mfma_f32_16x16x128_f8f6f4 v[34:37], v[26:33], v[220:227], v[34:37]
	v_mfma_f32_16x16x128_f8f6f4 v[66:69], v[10:17], v[220:227], v[66:69]
	v_mfma_f32_16x16x128_f8f6f4 v[70:73], v[2:9], v[220:227], v[70:73]
	s_barrier
	s_setprio 0
	ds_read_b128 v[2:5], v188 offset:32768
	ds_read_b128 v[6:9], v188 offset:33792
	ds_read_b128 v[10:13], v188 offset:34816
	ds_read_b128 v[14:17], v188 offset:35840
	ds_read_b128 v[18:21], v188 offset:49152
	ds_read_b128 v[22:25], v188 offset:50176
	ds_read_b128 v[26:29], v188 offset:51200
	ds_read_b128 v[30:33], v188 offset:52224
	ds_read_b128 v[196:199], v189 offset:32768
	ds_read_b128 v[200:203], v189 offset:33792
	ds_read_b128 v[204:207], v189 offset:34816
	ds_read_b128 v[208:211], v189 offset:35840
	ds_read_b128 v[212:215], v189 offset:36864
	ds_read_b128 v[216:219], v189 offset:37888
	ds_read_b128 v[220:223], v189 offset:38912
	ds_read_b128 v[224:227], v189 offset:39936
	s_add_u32 s62, s84, 0x10000
	s_addc_u32 s63, s85, 0
	s_mov_b32 m0, s87
	v_lshl_add_u64 v[228:229], s[62:63], 0, v[166:167]
	global_load_lds_dwordx4 v[228:229], off
	v_lshl_add_u64 v[228:229], s[62:63], 0, v[168:169]
	s_mov_b32 m0, s88
	s_nop 0
	global_load_lds_dwordx4 v[228:229], off
	s_waitcnt vmcnt(8)
	s_waitcnt lgkmcnt(0)
	s_setprio 1
	s_barrier
	v_mfma_f32_16x16x128_f8f6f4 v[158:161], v[2:9], v[196:203], v[158:161]
	v_mfma_f32_16x16x128_f8f6f4 v[154:157], v[10:17], v[196:203], v[154:157]
	v_mfma_f32_16x16x128_f8f6f4 v[122:125], v[26:33], v[196:203], v[122:125]
	v_mfma_f32_16x16x128_f8f6f4 v[126:129], v[18:25], v[196:203], v[126:129]
	v_mfma_f32_16x16x128_f8f6f4 v[118:121], v[18:25], v[204:211], v[118:121]
	v_mfma_f32_16x16x128_f8f6f4 v[114:117], v[26:33], v[204:211], v[114:117]
	v_mfma_f32_16x16x128_f8f6f4 v[146:149], v[10:17], v[204:211], v[146:149]
	v_mfma_f32_16x16x128_f8f6f4 v[150:153], v[2:9], v[204:211], v[150:153]
	s_setprio 0
	s_setprio 1
	v_mfma_f32_16x16x128_f8f6f4 v[142:145], v[2:9], v[212:219], v[142:145]
	v_mfma_f32_16x16x128_f8f6f4 v[138:141], v[10:17], v[212:219], v[138:141]
	v_mfma_f32_16x16x128_f8f6f4 v[106:109], v[26:33], v[212:219], v[106:109]
	v_mfma_f32_16x16x128_f8f6f4 v[110:113], v[18:25], v[212:219], v[110:113]
	v_mfma_f32_16x16x128_f8f6f4 v[102:105], v[18:25], v[220:227], v[102:105]
	v_mfma_f32_16x16x128_f8f6f4 v[98:101], v[26:33], v[220:227], v[98:101]
	v_mfma_f32_16x16x128_f8f6f4 v[130:133], v[10:17], v[220:227], v[130:133]
	v_mfma_f32_16x16x128_f8f6f4 v[134:137], v[2:9], v[220:227], v[134:137]
	s_barrier
	s_setprio 0
	ds_read_b128 v[196:199], v189 offset:49152
	ds_read_b128 v[200:203], v189 offset:50176
	ds_read_b128 v[204:207], v189 offset:51200
	ds_read_b128 v[208:211], v189 offset:52224
	ds_read_b128 v[212:215], v189 offset:53248
	ds_read_b128 v[216:219], v189 offset:54272
	ds_read_b128 v[220:223], v189 offset:55296
	ds_read_b128 v[224:227], v189 offset:56320
	s_mov_b32 m0, s89
	v_lshl_add_u64 v[174:175], v[174:175], 0, s[40:41]
	s_add_u32 s62, s82, 0x10080
	global_load_lds_dwordx4 v[174:175], off
	v_lshl_add_u64 v[174:175], v[176:177], 0, s[40:41]
	s_mov_b32 m0, s90
	s_addc_u32 s63, s83, 0
	global_load_lds_dwordx4 v[174:175], off
	v_lshl_add_u64 v[174:175], s[62:63], 0, v[162:163]
	s_mov_b32 m0, s93
	s_nop 0
	global_load_lds_dwordx4 v[174:175], off
	v_lshl_add_u64 v[174:175], s[62:63], 0, v[164:165]
	s_mov_b32 m0, s95
	s_nop 0
	global_load_lds_dwordx4 v[174:175], off
	v_lshl_add_u64 v[174:175], v[182:183], 0, s[40:41]
	s_mov_b32 m0, s91
	s_nop 0
	global_load_lds_dwordx4 v[174:175], off
	v_lshl_add_u64 v[174:175], v[184:185], 0, s[40:41]
	s_mov_b32 m0, s92
	s_nop 0
	global_load_lds_dwordx4 v[174:175], off
	s_waitcnt vmcnt(8)
	s_waitcnt lgkmcnt(0)
	s_setprio 1
	s_barrier
	v_mfma_f32_16x16x128_f8f6f4 v[94:97], v[2:9], v[196:203], v[94:97]
	v_mfma_f32_16x16x128_f8f6f4 v[90:93], v[10:17], v[196:203], v[90:93]
	v_mfma_f32_16x16x128_f8f6f4 v[58:61], v[26:33], v[196:203], v[58:61]
	v_mfma_f32_16x16x128_f8f6f4 v[62:65], v[18:25], v[196:203], v[62:65]
	v_mfma_f32_16x16x128_f8f6f4 v[54:57], v[18:25], v[204:211], v[54:57]
	v_mfma_f32_16x16x128_f8f6f4 v[50:53], v[26:33], v[204:211], v[50:53]
	v_mfma_f32_16x16x128_f8f6f4 v[82:85], v[10:17], v[204:211], v[82:85]
	v_mfma_f32_16x16x128_f8f6f4 v[86:89], v[2:9], v[204:211], v[86:89]
	s_setprio 0
	s_setprio 1
	v_mfma_f32_16x16x128_f8f6f4 v[78:81], v[2:9], v[212:219], v[78:81]
	v_mfma_f32_16x16x128_f8f6f4 v[74:77], v[10:17], v[212:219], v[74:77]
	v_mfma_f32_16x16x128_f8f6f4 v[42:45], v[26:33], v[212:219], v[42:45]
	v_mfma_f32_16x16x128_f8f6f4 v[46:49], v[18:25], v[212:219], v[46:49]
	v_mfma_f32_16x16x128_f8f6f4 v[38:41], v[18:25], v[220:227], v[38:41]
	v_mfma_f32_16x16x128_f8f6f4 v[34:37], v[26:33], v[220:227], v[34:37]
	v_mfma_f32_16x16x128_f8f6f4 v[66:69], v[10:17], v[220:227], v[66:69]
	v_mfma_f32_16x16x128_f8f6f4 v[70:73], v[2:9], v[220:227], v[70:73]
	s_barrier
	s_setprio 0
	s_andn2_b64 vcc, exec, s[42:43]
	s_cbranch_vccnz .LBB0_618
	s_barrier

.LBB0_630:
	s_ashr_i32 s54, s48, 1
	s_ashr_i32 s51, s50, 31
	s_ashr_i32 s55, s54, 31
	s_lshl_b64 s[52:53], s[50:51], 19
	s_lshl_b64 s[54:55], s[54:55], 9
	s_waitcnt vmcnt(0)
	ds_read_b128 v[18:21], v181
	ds_read_b128 v[22:25], v181 offset:1024
	ds_read_b128 v[26:29], v181 offset:2048
	ds_read_b128 v[30:33], v181 offset:3072
	ds_read_b128 v[2:5], v181 offset:16384
	ds_read_b128 v[6:9], v181 offset:17408
	ds_read_b128 v[10:13], v181 offset:18432
	ds_read_b128 v[14:17], v181 offset:19456
	s_add_u32 s5, s26, s52
	s_addc_u32 s33, s27, s53
	s_add_u32 s52, s5, s54
	s_addc_u32 s53, s33, s55
	s_and_b64 s[54:55], s[2:3], exec
	s_cselect_b32 s81, s53, s75
	s_cselect_b32 s80, s52, s74
	s_ashr_i32 s49, s48, 31
	s_lshl_b64 s[54:55], s[48:49], 17
	v_readlane_b32 s5, v254, 9
	s_add_u32 s54, s5, s54
	v_readlane_b32 s5, v254, 10
	s_addc_u32 s55, s5, s55
	s_and_b64 s[62:63], s[2:3], exec
	s_cselect_b32 s79, s55, s77
	s_cselect_b32 s78, s54, s76
	s_add_u32 s62, s74, 0x40080
	s_addc_u32 s63, s75, 0
	s_add_i32 s33, s8, 0xc000
	v_lshl_add_u64 v[174:175], s[62:63], 0, v[166:167]
	s_mov_b32 m0, s33
	s_add_i32 s5, s8, 0xe000
	ds_read_b128 v[190:193], v187
	ds_read_b128 v[194:197], v187 offset:1024
	ds_read_b128 v[198:201], v187 offset:2048
	ds_read_b128 v[202:205], v187 offset:3072
	ds_read_b128 v[206:209], v187 offset:4096
	ds_read_b128 v[210:213], v187 offset:5120
	ds_read_b128 v[214:217], v187 offset:6144
	ds_read_b128 v[218:221], v187 offset:7168
	global_load_lds_dwordx4 v[174:175], off
	v_lshl_add_u64 v[174:175], s[62:63], 0, v[168:169]
	s_mov_b32 m0, s5
	s_nop 0
	global_load_lds_dwordx4 v[174:175], off
	s_waitcnt vmcnt(8)
	s_waitcnt lgkmcnt(0)
	s_setprio 1
	s_barrier
	v_mfma_f32_16x16x128_f8f6f4 v[158:161], v[18:25], v[190:197], 0
	v_mfma_f32_16x16x128_f8f6f4 v[154:157], v[26:33], v[190:197], 0
	v_mfma_f32_16x16x128_f8f6f4 v[122:125], v[10:17], v[190:197], 0
	v_mfma_f32_16x16x128_f8f6f4 v[126:129], v[2:9], v[190:197], 0
	v_mfma_f32_16x16x128_f8f6f4 v[118:121], v[2:9], v[198:205], 0
	v_mfma_f32_16x16x128_f8f6f4 v[114:117], v[10:17], v[198:205], 0
	v_mfma_f32_16x16x128_f8f6f4 v[146:149], v[26:33], v[198:205], 0
	v_mfma_f32_16x16x128_f8f6f4 v[150:153], v[18:25], v[198:205], 0
	s_setprio 0
	s_setprio 1
	v_mfma_f32_16x16x128_f8f6f4 v[142:145], v[18:25], v[206:213], 0
	v_mfma_f32_16x16x128_f8f6f4 v[138:141], v[26:33], v[206:213], 0
	v_mfma_f32_16x16x128_f8f6f4 v[106:109], v[10:17], v[206:213], 0
	v_mfma_f32_16x16x128_f8f6f4 v[110:113], v[2:9], v[206:213], 0
	v_mfma_f32_16x16x128_f8f6f4 v[102:105], v[2:9], v[214:221], 0
	v_mfma_f32_16x16x128_f8f6f4 v[98:101], v[10:17], v[214:221], 0
	v_mfma_f32_16x16x128_f8f6f4 v[130:133], v[26:33], v[214:221], 0
	v_mfma_f32_16x16x128_f8f6f4 v[134:137], v[18:25], v[214:221], 0
	s_barrier
	s_setprio 0
	ds_read_b128 v[190:193], v187 offset:16384
	ds_read_b128 v[194:197], v187 offset:17408
	ds_read_b128 v[198:201], v187 offset:18432
	ds_read_b128 v[202:205], v187 offset:19456
	ds_read_b128 v[206:209], v187 offset:20480
	ds_read_b128 v[210:213], v187 offset:21504
	ds_read_b128 v[214:217], v187 offset:22528
	ds_read_b128 v[218:221], v187 offset:23552
	v_lshl_add_u64 v[174:175], s[76:77], 0, v[162:163]
	s_mov_b32 m0, s9
	v_lshl_add_u64 v[176:177], v[174:175], 0, s[44:45]
	global_load_lds_dwordx4 v[176:177], off
	v_lshl_add_u64 v[176:177], s[76:77], 0, v[164:165]
	s_add_u32 s62, s76, 0x10100
	v_lshl_add_u64 v[182:183], v[176:177], 0, s[44:45]
	s_mov_b32 m0, s61
	s_addc_u32 s63, s77, 0
	global_load_lds_dwordx4 v[182:183], off
	v_lshl_add_u64 v[182:183], s[62:63], 0, v[162:163]
	s_mov_b32 m0, s68
	s_nop 0
	global_load_lds_dwordx4 v[182:183], off
	v_lshl_add_u64 v[182:183], s[62:63], 0, v[164:165]
	s_mov_b32 m0, s69
	s_nop 0
	global_load_lds_dwordx4 v[182:183], off
	v_lshl_add_u64 v[182:183], s[74:75], 0, v[166:167]
	v_lshl_add_u64 v[184:185], v[182:183], 0, s[44:45]
	s_mov_b32 m0, s8
	s_nop 0
	global_load_lds_dwordx4 v[184:185], off
	v_lshl_add_u64 v[184:185], s[74:75], 0, v[168:169]
	v_lshl_add_u64 v[222:223], v[184:185], 0, s[44:45]
	s_mov_b32 m0, s71
	s_nop 0
	global_load_lds_dwordx4 v[222:223], off
	s_waitcnt vmcnt(8)
	s_waitcnt lgkmcnt(0)
	s_setprio 1
	s_barrier
	v_mfma_f32_16x16x128_f8f6f4 v[94:97], v[18:25], v[190:197], 0
	v_mfma_f32_16x16x128_f8f6f4 v[90:93], v[26:33], v[190:197], 0
	v_mfma_f32_16x16x128_f8f6f4 v[58:61], v[10:17], v[190:197], 0
	v_mfma_f32_16x16x128_f8f6f4 v[62:65], v[2:9], v[190:197], 0
	v_mfma_f32_16x16x128_f8f6f4 v[54:57], v[2:9], v[198:205], 0
	v_mfma_f32_16x16x128_f8f6f4 v[50:53], v[10:17], v[198:205], 0
	v_mfma_f32_16x16x128_f8f6f4 v[82:85], v[26:33], v[198:205], 0
	v_mfma_f32_16x16x128_f8f6f4 v[86:89], v[18:25], v[198:205], 0
	s_setprio 0
	s_setprio 1
	v_mfma_f32_16x16x128_f8f6f4 v[78:81], v[18:25], v[206:213], 0
	v_mfma_f32_16x16x128_f8f6f4 v[74:77], v[26:33], v[206:213], 0
	v_mfma_f32_16x16x128_f8f6f4 v[42:45], v[10:17], v[206:213], 0
	v_mfma_f32_16x16x128_f8f6f4 v[46:49], v[2:9], v[206:213], 0
	v_mfma_f32_16x16x128_f8f6f4 v[38:41], v[2:9], v[214:221], 0
	v_mfma_f32_16x16x128_f8f6f4 v[34:37], v[10:17], v[214:221], 0
	v_mfma_f32_16x16x128_f8f6f4 v[66:69], v[26:33], v[214:221], 0
	v_mfma_f32_16x16x128_f8f6f4 v[70:73], v[18:25], v[214:221], 0
	s_barrier
	s_setprio 0
	ds_read_b128 v[2:5], v181 offset:32768
	ds_read_b128 v[6:9], v181 offset:33792
	ds_read_b128 v[10:13], v181 offset:34816
	ds_read_b128 v[14:17], v181 offset:35840
	ds_read_b128 v[18:21], v181 offset:49152
	ds_read_b128 v[22:25], v181 offset:50176
	ds_read_b128 v[26:29], v181 offset:51200
	ds_read_b128 v[30:33], v181 offset:52224
	ds_read_b128 v[190:193], v187 offset:32768
	ds_read_b128 v[194:197], v187 offset:33792
	ds_read_b128 v[198:201], v187 offset:34816
	ds_read_b128 v[202:205], v187 offset:35840
	ds_read_b128 v[206:209], v187 offset:36864
	ds_read_b128 v[210:213], v187 offset:37888
	ds_read_b128 v[214:217], v187 offset:38912
	ds_read_b128 v[218:221], v187 offset:39936
	s_add_u32 s62, s74, 0x40100
	s_addc_u32 s63, s75, 0
	s_mov_b32 m0, s73
	v_lshl_add_u64 v[222:223], s[62:63], 0, v[166:167]
	global_load_lds_dwordx4 v[222:223], off
	v_lshl_add_u64 v[222:223], s[62:63], 0, v[168:169]
	s_mov_b32 m0, s82
	s_nop 0
	global_load_lds_dwordx4 v[222:223], off
	s_waitcnt vmcnt(8)
	s_waitcnt lgkmcnt(0)
	s_setprio 1
	s_barrier
	v_mfma_f32_16x16x128_f8f6f4 v[158:161], v[2:9], v[190:197], v[158:161]
	v_mfma_f32_16x16x128_f8f6f4 v[154:157], v[10:17], v[190:197], v[154:157]
	v_mfma_f32_16x16x128_f8f6f4 v[122:125], v[26:33], v[190:197], v[122:125]
	v_mfma_f32_16x16x128_f8f6f4 v[126:129], v[18:25], v[190:197], v[126:129]
	v_mfma_f32_16x16x128_f8f6f4 v[118:121], v[18:25], v[198:205], v[118:121]
	v_mfma_f32_16x16x128_f8f6f4 v[114:117], v[26:33], v[198:205], v[114:117]
	v_mfma_f32_16x16x128_f8f6f4 v[146:149], v[10:17], v[198:205], v[146:149]
	v_mfma_f32_16x16x128_f8f6f4 v[150:153], v[2:9], v[198:205], v[150:153]
	s_setprio 0
	s_setprio 1
	v_mfma_f32_16x16x128_f8f6f4 v[142:145], v[2:9], v[206:213], v[142:145]
	v_mfma_f32_16x16x128_f8f6f4 v[138:141], v[10:17], v[206:213], v[138:141]
	v_mfma_f32_16x16x128_f8f6f4 v[106:109], v[26:33], v[206:213], v[106:109]
	v_mfma_f32_16x16x128_f8f6f4 v[110:113], v[18:25], v[206:213], v[110:113]
	v_mfma_f32_16x16x128_f8f6f4 v[102:105], v[18:25], v[214:221], v[102:105]
	v_mfma_f32_16x16x128_f8f6f4 v[98:101], v[26:33], v[214:221], v[98:101]
	v_mfma_f32_16x16x128_f8f6f4 v[130:133], v[10:17], v[214:221], v[130:133]
	v_mfma_f32_16x16x128_f8f6f4 v[134:137], v[2:9], v[214:221], v[134:137]
	s_barrier
	s_setprio 0
	ds_read_b128 v[190:193], v187 offset:49152
	ds_read_b128 v[194:197], v187 offset:50176
	ds_read_b128 v[198:201], v187 offset:51200
	ds_read_b128 v[202:205], v187 offset:52224
	ds_read_b128 v[206:209], v187 offset:53248
	ds_read_b128 v[210:213], v187 offset:54272
	ds_read_b128 v[214:217], v187 offset:55296
	ds_read_b128 v[218:221], v187 offset:56320
	s_mov_b32 m0, s83
	v_lshl_add_u64 v[174:175], v[174:175], 0, s[46:47]
	s_add_u32 s62, s76, 0x10180
	global_load_lds_dwordx4 v[174:175], off
	v_lshl_add_u64 v[174:175], v[176:177], 0, s[46:47]
	s_mov_b32 m0, s84
	s_addc_u32 s63, s77, 0
	global_load_lds_dwordx4 v[174:175], off
	v_lshl_add_u64 v[174:175], s[62:63], 0, v[162:163]
	s_mov_b32 m0, s87
	s_nop 0
	global_load_lds_dwordx4 v[174:175], off
	v_lshl_add_u64 v[174:175], s[62:63], 0, v[164:165]
	s_mov_b32 m0, s88
	s_nop 0
	global_load_lds_dwordx4 v[174:175], off
	v_lshl_add_u64 v[174:175], v[182:183], 0, s[46:47]
	s_mov_b32 m0, s85
	s_nop 0
	global_load_lds_dwordx4 v[174:175], off
	v_lshl_add_u64 v[174:175], v[184:185], 0, s[46:47]
	s_mov_b32 m0, s86
	s_nop 0
	global_load_lds_dwordx4 v[174:175], off
	s_waitcnt vmcnt(8)
	s_waitcnt lgkmcnt(0)
	s_setprio 1
	s_barrier
	v_mfma_f32_16x16x128_f8f6f4 v[94:97], v[2:9], v[190:197], v[94:97]
	v_mfma_f32_16x16x128_f8f6f4 v[90:93], v[10:17], v[190:197], v[90:93]
	v_mfma_f32_16x16x128_f8f6f4 v[58:61], v[26:33], v[190:197], v[58:61]
	v_mfma_f32_16x16x128_f8f6f4 v[62:65], v[18:25], v[190:197], v[62:65]
	v_mfma_f32_16x16x128_f8f6f4 v[54:57], v[18:25], v[198:205], v[54:57]
	v_mfma_f32_16x16x128_f8f6f4 v[50:53], v[26:33], v[198:205], v[50:53]
	v_mfma_f32_16x16x128_f8f6f4 v[82:85], v[10:17], v[198:205], v[82:85]
	v_mfma_f32_16x16x128_f8f6f4 v[86:89], v[2:9], v[198:205], v[86:89]
	s_setprio 0
	s_setprio 1
	v_mfma_f32_16x16x128_f8f6f4 v[78:81], v[2:9], v[206:213], v[78:81]
	v_mfma_f32_16x16x128_f8f6f4 v[74:77], v[10:17], v[206:213], v[74:77]
	v_mfma_f32_16x16x128_f8f6f4 v[42:45], v[26:33], v[206:213], v[42:45]
	v_mfma_f32_16x16x128_f8f6f4 v[46:49], v[18:25], v[206:213], v[46:49]
	v_mfma_f32_16x16x128_f8f6f4 v[38:41], v[18:25], v[214:221], v[38:41]
	v_mfma_f32_16x16x128_f8f6f4 v[34:37], v[26:33], v[214:221], v[34:37]
	v_mfma_f32_16x16x128_f8f6f4 v[66:69], v[10:17], v[214:221], v[66:69]
	v_mfma_f32_16x16x128_f8f6f4 v[70:73], v[2:9], v[214:221], v[70:73]
	s_barrier
	s_setprio 0
	ds_read_b128 v[2:5], v181
	ds_read_b128 v[6:9], v181 offset:1024
	ds_read_b128 v[10:13], v181 offset:2048
	ds_read_b128 v[14:17], v181 offset:3072
	ds_read_b128 v[18:21], v181 offset:16384
	ds_read_b128 v[22:25], v181 offset:17408
	ds_read_b128 v[26:29], v181 offset:18432
	ds_read_b128 v[30:33], v181 offset:19456
	ds_read_b128 v[190:193], v187
	ds_read_b128 v[194:197], v187 offset:1024
	ds_read_b128 v[198:201], v187 offset:2048
	ds_read_b128 v[202:205], v187 offset:3072
	ds_read_b128 v[206:209], v187 offset:4096
	ds_read_b128 v[210:213], v187 offset:5120
	ds_read_b128 v[214:217], v187 offset:6144
	ds_read_b128 v[218:221], v187 offset:7168
	s_add_u32 s62, s74, 0x40180
	s_addc_u32 s63, s75, 0
	s_mov_b32 m0, s33
	v_lshl_add_u64 v[174:175], s[62:63], 0, v[166:167]
	global_load_lds_dwordx4 v[174:175], off
	v_lshl_add_u64 v[174:175], s[62:63], 0, v[168:169]
	s_mov_b32 m0, s5
	s_nop 0
	global_load_lds_dwordx4 v[174:175], off
	s_waitcnt vmcnt(8)
	s_waitcnt lgkmcnt(0)
	s_setprio 1
	s_barrier
	v_mfma_f32_16x16x128_f8f6f4 v[158:161], v[2:9], v[190:197], v[158:161]
	v_mfma_f32_16x16x128_f8f6f4 v[154:157], v[10:17], v[190:197], v[154:157]
	v_mfma_f32_16x16x128_f8f6f4 v[122:125], v[26:33], v[190:197], v[122:125]
	v_mfma_f32_16x16x128_f8f6f4 v[126:129], v[18:25], v[190:197], v[126:129]
	v_mfma_f32_16x16x128_f8f6f4 v[118:121], v[18:25], v[198:205], v[118:121]
	v_mfma_f32_16x16x128_f8f6f4 v[114:117], v[26:33], v[198:205], v[114:117]
	v_mfma_f32_16x16x128_f8f6f4 v[146:149], v[10:17], v[198:205], v[146:149]
	v_mfma_f32_16x16x128_f8f6f4 v[150:153], v[2:9], v[198:205], v[150:153]
	s_setprio 0
	s_setprio 1
	v_mfma_f32_16x16x128_f8f6f4 v[142:145], v[2:9], v[206:213], v[142:145]
	v_mfma_f32_16x16x128_f8f6f4 v[138:141], v[10:17], v[206:213], v[138:141]
	v_mfma_f32_16x16x128_f8f6f4 v[106:109], v[26:33], v[206:213], v[106:109]
	v_mfma_f32_16x16x128_f8f6f4 v[110:113], v[18:25], v[206:213], v[110:113]
	v_mfma_f32_16x16x128_f8f6f4 v[102:105], v[18:25], v[214:221], v[102:105]
	v_mfma_f32_16x16x128_f8f6f4 v[98:101], v[26:33], v[214:221], v[98:101]
	v_mfma_f32_16x16x128_f8f6f4 v[130:133], v[10:17], v[214:221], v[130:133]
	v_mfma_f32_16x16x128_f8f6f4 v[134:137], v[2:9], v[214:221], v[134:137]
	s_barrier
	s_setprio 0
	ds_read_b128 v[190:193], v187 offset:16384
	ds_read_b128 v[194:197], v187 offset:17408
	ds_read_b128 v[198:201], v187 offset:18432
	ds_read_b128 v[202:205], v187 offset:19456
	ds_read_b128 v[206:209], v187 offset:20480
	ds_read_b128 v[210:213], v187 offset:21504
	ds_read_b128 v[214:217], v187 offset:22528
	ds_read_b128 v[218:221], v187 offset:23552
	s_mov_b32 m0, s9
	v_lshl_add_u64 v[174:175], s[78:79], 0, v[162:163]
	s_add_u32 s62, s78, 0x10000
	global_load_lds_dwordx4 v[174:175], off
	v_lshl_add_u64 v[176:177], s[78:79], 0, v[164:165]
	s_mov_b32 m0, s61
	s_addc_u32 s63, s79, 0
	global_load_lds_dwordx4 v[176:177], off
	v_lshl_add_u64 v[182:183], s[62:63], 0, v[162:163]
	s_mov_b32 m0, s68
	v_lshl_add_u64 v[184:185], s[80:81], 0, v[168:169]
	global_load_lds_dwordx4 v[182:183], off
	v_lshl_add_u64 v[182:183], s[62:63], 0, v[164:165]
	s_mov_b32 m0, s69
	s_nop 0
	global_load_lds_dwordx4 v[182:183], off
	v_lshl_add_u64 v[182:183], s[80:81], 0, v[166:167]
	s_mov_b32 m0, s8
	s_nop 0
	global_load_lds_dwordx4 v[182:183], off
	s_mov_b32 m0, s71
	s_nop 0
	global_load_lds_dwordx4 v[184:185], off
	s_waitcnt vmcnt(8)
	s_waitcnt lgkmcnt(0)
	s_setprio 1
	s_barrier
	v_mfma_f32_16x16x128_f8f6f4 v[94:97], v[2:9], v[190:197], v[94:97]
	v_mfma_f32_16x16x128_f8f6f4 v[90:93], v[10:17], v[190:197], v[90:93]
	v_mfma_f32_16x16x128_f8f6f4 v[58:61], v[26:33], v[190:197], v[58:61]
	v_mfma_f32_16x16x128_f8f6f4 v[62:65], v[18:25], v[190:197], v[62:65]
	v_mfma_f32_16x16x128_f8f6f4 v[54:57], v[18:25], v[198:205], v[54:57]
	v_mfma_f32_16x16x128_f8f6f4 v[50:53], v[26:33], v[198:205], v[50:53]
	v_mfma_f32_16x16x128_f8f6f4 v[82:85], v[10:17], v[198:205], v[82:85]
	v_mfma_f32_16x16x128_f8f6f4 v[86:89], v[2:9], v[198:205], v[86:89]
	s_setprio 0
	s_setprio 1
	v_mfma_f32_16x16x128_f8f6f4 v[78:81], v[2:9], v[206:213], v[78:81]
	v_mfma_f32_16x16x128_f8f6f4 v[74:77], v[10:17], v[206:213], v[74:77]
	v_mfma_f32_16x16x128_f8f6f4 v[42:45], v[26:33], v[206:213], v[42:45]
	v_mfma_f32_16x16x128_f8f6f4 v[46:49], v[18:25], v[206:213], v[46:49]
	v_mfma_f32_16x16x128_f8f6f4 v[38:41], v[18:25], v[214:221], v[38:41]
	v_mfma_f32_16x16x128_f8f6f4 v[34:37], v[26:33], v[214:221], v[34:37]
	v_mfma_f32_16x16x128_f8f6f4 v[66:69], v[10:17], v[214:221], v[66:69]
	v_mfma_f32_16x16x128_f8f6f4 v[70:73], v[2:9], v[214:221], v[70:73]
	s_barrier
	s_setprio 0
	ds_read_b128 v[2:5], v181 offset:32768
	ds_read_b128 v[6:9], v181 offset:33792
	ds_read_b128 v[10:13], v181 offset:34816
	ds_read_b128 v[14:17], v181 offset:35840
	ds_read_b128 v[18:21], v181 offset:49152
	ds_read_b128 v[22:25], v181 offset:50176
	ds_read_b128 v[26:29], v181 offset:51200
	ds_read_b128 v[30:33], v181 offset:52224
	ds_read_b128 v[190:193], v187 offset:32768
	ds_read_b128 v[194:197], v187 offset:33792
	ds_read_b128 v[198:201], v187 offset:34816
	ds_read_b128 v[202:205], v187 offset:35840
	ds_read_b128 v[206:209], v187 offset:36864
	ds_read_b128 v[210:213], v187 offset:37888
	ds_read_b128 v[214:217], v187 offset:38912
	ds_read_b128 v[218:221], v187 offset:39936
	s_add_u32 s62, s80, 0x40000
	s_addc_u32 s63, s81, 0
	s_mov_b32 m0, s73
	v_lshl_add_u64 v[222:223], s[62:63], 0, v[166:167]
	global_load_lds_dwordx4 v[222:223], off
	v_lshl_add_u64 v[222:223], s[62:63], 0, v[168:169]
	s_mov_b32 m0, s82
	s_nop 0
	global_load_lds_dwordx4 v[222:223], off
	s_waitcnt vmcnt(8)
	s_waitcnt lgkmcnt(0)
	s_setprio 1
	s_barrier
	v_mfma_f32_16x16x128_f8f6f4 v[158:161], v[2:9], v[190:197], v[158:161]
	v_mfma_f32_16x16x128_f8f6f4 v[154:157], v[10:17], v[190:197], v[154:157]
	v_mfma_f32_16x16x128_f8f6f4 v[122:125], v[26:33], v[190:197], v[122:125]
	v_mfma_f32_16x16x128_f8f6f4 v[126:129], v[18:25], v[190:197], v[126:129]
	v_mfma_f32_16x16x128_f8f6f4 v[118:121], v[18:25], v[198:205], v[118:121]
	v_mfma_f32_16x16x128_f8f6f4 v[114:117], v[26:33], v[198:205], v[114:117]
	v_mfma_f32_16x16x128_f8f6f4 v[146:149], v[10:17], v[198:205], v[146:149]
	v_mfma_f32_16x16x128_f8f6f4 v[150:153], v[2:9], v[198:205], v[150:153]
	s_setprio 0
	s_setprio 1
	v_mfma_f32_16x16x128_f8f6f4 v[142:145], v[2:9], v[206:213], v[142:145]
	v_mfma_f32_16x16x128_f8f6f4 v[138:141], v[10:17], v[206:213], v[138:141]
	v_mfma_f32_16x16x128_f8f6f4 v[106:109], v[26:33], v[206:213], v[106:109]
	v_mfma_f32_16x16x128_f8f6f4 v[110:113], v[18:25], v[206:213], v[110:113]
	v_mfma_f32_16x16x128_f8f6f4 v[102:105], v[18:25], v[214:221], v[102:105]
	v_mfma_f32_16x16x128_f8f6f4 v[98:101], v[26:33], v[214:221], v[98:101]
	v_mfma_f32_16x16x128_f8f6f4 v[130:133], v[10:17], v[214:221], v[130:133]
	v_mfma_f32_16x16x128_f8f6f4 v[134:137], v[2:9], v[214:221], v[134:137]
	s_barrier
	s_setprio 0
	ds_read_b128 v[190:193], v187 offset:49152
	ds_read_b128 v[194:197], v187 offset:50176
	ds_read_b128 v[198:201], v187 offset:51200
	ds_read_b128 v[202:205], v187 offset:52224
	ds_read_b128 v[206:209], v187 offset:53248
	ds_read_b128 v[210:213], v187 offset:54272
	ds_read_b128 v[214:217], v187 offset:55296
	ds_read_b128 v[218:221], v187 offset:56320
	s_mov_b32 m0, s83
	v_lshl_add_u64 v[174:175], v[174:175], 0, s[38:39]
	s_add_u32 s62, s78, 0x10080
	global_load_lds_dwordx4 v[174:175], off
	v_lshl_add_u64 v[174:175], v[176:177], 0, s[38:39]
	s_mov_b32 m0, s84
	s_addc_u32 s63, s79, 0
	global_load_lds_dwordx4 v[174:175], off
	v_lshl_add_u64 v[174:175], s[62:63], 0, v[162:163]
	s_mov_b32 m0, s87
	s_nop 0
	global_load_lds_dwordx4 v[174:175], off
	v_lshl_add_u64 v[174:175], s[62:63], 0, v[164:165]
	s_mov_b32 m0, s88
	s_nop 0
	global_load_lds_dwordx4 v[174:175], off
	v_lshl_add_u64 v[174:175], v[182:183], 0, s[38:39]
	s_mov_b32 m0, s85
	s_nop 0
	global_load_lds_dwordx4 v[174:175], off
	v_lshl_add_u64 v[174:175], v[184:185], 0, s[38:39]
	s_mov_b32 m0, s86
	s_nop 0
	global_load_lds_dwordx4 v[174:175], off
	s_waitcnt vmcnt(8)
	s_waitcnt lgkmcnt(0)
	s_setprio 1
	s_barrier
	v_mfma_f32_16x16x128_f8f6f4 v[94:97], v[2:9], v[190:197], v[94:97]
	v_mfma_f32_16x16x128_f8f6f4 v[90:93], v[10:17], v[190:197], v[90:93]
	v_mfma_f32_16x16x128_f8f6f4 v[58:61], v[26:33], v[190:197], v[58:61]
	v_mfma_f32_16x16x128_f8f6f4 v[62:65], v[18:25], v[190:197], v[62:65]
	v_mfma_f32_16x16x128_f8f6f4 v[54:57], v[18:25], v[198:205], v[54:57]
	v_mfma_f32_16x16x128_f8f6f4 v[50:53], v[26:33], v[198:205], v[50:53]
	v_mfma_f32_16x16x128_f8f6f4 v[82:85], v[10:17], v[198:205], v[82:85]
	v_mfma_f32_16x16x128_f8f6f4 v[86:89], v[2:9], v[198:205], v[86:89]
	s_setprio 0
	s_setprio 1
	v_mfma_f32_16x16x128_f8f6f4 v[78:81], v[2:9], v[206:213], v[78:81]
	v_mfma_f32_16x16x128_f8f6f4 v[74:77], v[10:17], v[206:213], v[74:77]
	v_mfma_f32_16x16x128_f8f6f4 v[42:45], v[26:33], v[206:213], v[42:45]
	v_mfma_f32_16x16x128_f8f6f4 v[46:49], v[18:25], v[206:213], v[46:49]
	v_mfma_f32_16x16x128_f8f6f4 v[38:41], v[18:25], v[214:221], v[38:41]
	v_mfma_f32_16x16x128_f8f6f4 v[34:37], v[26:33], v[214:221], v[34:37]
	v_mfma_f32_16x16x128_f8f6f4 v[66:69], v[10:17], v[214:221], v[66:69]
	v_mfma_f32_16x16x128_f8f6f4 v[70:73], v[2:9], v[214:221], v[70:73]
	s_barrier
	s_setprio 0
	s_andn2_b64 vcc, exec, s[40:41]
	s_cbranch_vccnz .LBB0_632
	s_barrier

.LBB0_791:
	ds_read_b128 v[2:5], v189
	ds_read_b128 v[6:9], v189 offset:1024
	ds_read_b128 v[192:195], v189 offset:2048
	ds_read_b128 v[196:199], v189 offset:3072
	ds_read_b128 v[200:203], v189 offset:16384
	ds_read_b128 v[204:207], v189 offset:17408
	ds_read_b128 v[208:211], v189 offset:18432
	ds_read_b128 v[212:215], v189 offset:19456
	ds_read_b128 v[216:219], v190
	ds_read_b128 v[220:223], v190 offset:1024
	ds_read_b128 v[224:227], v190 offset:2048
	ds_read_b128 v[228:231], v190 offset:3072
	ds_read_b128 v[242:245], v190 offset:4096
	ds_read_b128 v[246:249], v190 offset:5120
	ds_read_b128 v[232:235], v190 offset:6144
	ds_read_b128 v[236:239], v190 offset:7168
	s_add_u32 s37, s46, 0x100
	s_addc_u32 s39, s47, 0
	s_and_b64 s[50:51], s[48:49], exec
	s_cselect_b32 s51, s1, s39
	s_cselect_b32 s50, s0, s37
	s_add_u32 s37, s44, 0x100
	s_addc_u32 s39, s45, 0
	s_and_b64 s[48:49], s[48:49], exec
	s_cselect_b32 s49, s5, s39
	s_cselect_b32 s48, s4, s37
	s_add_u32 s88, s46, 0x80080
	s_addc_u32 s89, s47, 0
	s_add_i32 s37, s8, 0xc000
	v_lshl_add_u64 v[174:175], s[88:89], 0, v[154:155]
	s_mov_b32 m0, s37
	s_add_i32 s39, s8, 0xe000
	global_load_lds_dwordx4 v[174:175], off
	v_lshl_add_u64 v[174:175], s[88:89], 0, v[158:159]
	s_mov_b32 m0, s39
	s_nop 0
	global_load_lds_dwordx4 v[174:175], off
	s_waitcnt vmcnt(8)
	s_waitcnt lgkmcnt(0)
	s_setprio 1
	s_barrier
	v_mfma_f32_16x16x128_f8f6f4 v[134:137], v[2:9], v[216:223], 0
	v_mfma_f32_16x16x128_f8f6f4 v[130:133], v[192:199], v[216:223], 0
	v_mfma_f32_16x16x128_f8f6f4 v[98:101], v[208:215], v[216:223], 0
	v_mfma_f32_16x16x128_f8f6f4 v[102:105], v[200:207], v[216:223], 0
	v_mfma_f32_16x16x128_f8f6f4 v[94:97], v[200:207], v[224:231], 0
	v_mfma_f32_16x16x128_f8f6f4 v[90:93], v[208:215], v[224:231], 0
	v_mfma_f32_16x16x128_f8f6f4 v[122:125], v[192:199], v[224:231], 0
	v_mfma_f32_16x16x128_f8f6f4 v[126:129], v[2:9], v[224:231], 0
	s_setprio 0
	s_setprio 1
	v_mfma_f32_16x16x128_f8f6f4 v[118:121], v[2:9], v[242:249], 0
	v_mfma_f32_16x16x128_f8f6f4 v[114:117], v[192:199], v[242:249], 0
	v_mfma_f32_16x16x128_f8f6f4 v[82:85], v[208:215], v[242:249], 0
	v_mfma_f32_16x16x128_f8f6f4 v[86:89], v[200:207], v[242:249], 0
	v_mfma_f32_16x16x128_f8f6f4 v[78:81], v[200:207], v[232:239], 0
	v_mfma_f32_16x16x128_f8f6f4 v[74:77], v[208:215], v[232:239], 0
	v_mfma_f32_16x16x128_f8f6f4 v[106:109], v[192:199], v[232:239], 0
	v_mfma_f32_16x16x128_f8f6f4 v[110:113], v[2:9], v[232:239], 0
	s_barrier
	s_setprio 0
	ds_read_b128 v[216:219], v190 offset:16384
	ds_read_b128 v[220:223], v190 offset:17408
	ds_read_b128 v[224:227], v190 offset:18432
	ds_read_b128 v[228:231], v190 offset:19456
	ds_read_b128 v[232:235], v190 offset:20480
	ds_read_b128 v[236:239], v190 offset:21504
	ds_read_b128 v[242:245], v190 offset:22528
	ds_read_b128 v[246:249], v190 offset:23552
	s_mov_b32 m0, s9
	v_lshl_add_u64 v[174:175], s[48:49], 0, v[156:157]
	s_add_u32 s88, s48, 0x80000
	global_load_lds_dwordx4 v[174:175], off
	v_lshl_add_u64 v[176:177], s[48:49], 0, v[160:161]
	s_mov_b32 m0, s27
	s_addc_u32 s89, s49, 0
	global_load_lds_dwordx4 v[176:177], off
	v_lshl_add_u64 v[182:183], s[88:89], 0, v[156:157]
	s_mov_b32 m0, s33
	v_lshl_add_u64 v[184:185], s[50:51], 0, v[158:159]
	global_load_lds_dwordx4 v[182:183], off
	v_lshl_add_u64 v[182:183], s[88:89], 0, v[160:161]
	s_mov_b32 m0, s35
	s_nop 0
	global_load_lds_dwordx4 v[182:183], off
	v_lshl_add_u64 v[182:183], s[50:51], 0, v[154:155]
	s_mov_b32 m0, s8
	s_nop 0
	global_load_lds_dwordx4 v[182:183], off
	s_mov_b32 m0, s43
	s_nop 0
	global_load_lds_dwordx4 v[184:185], off
	s_waitcnt vmcnt(8)
	s_waitcnt lgkmcnt(0)
	s_setprio 1
	s_barrier
	v_mfma_f32_16x16x128_f8f6f4 v[70:73], v[2:9], v[216:223], 0
	v_mfma_f32_16x16x128_f8f6f4 v[66:69], v[192:199], v[216:223], 0
	v_mfma_f32_16x16x128_f8f6f4 v[34:37], v[208:215], v[216:223], 0
	v_mfma_f32_16x16x128_f8f6f4 v[38:41], v[200:207], v[216:223], 0
	v_mfma_f32_16x16x128_f8f6f4 v[30:33], v[200:207], v[224:231], 0
	v_mfma_f32_16x16x128_f8f6f4 v[26:29], v[208:215], v[224:231], 0
	v_mfma_f32_16x16x128_f8f6f4 v[58:61], v[192:199], v[224:231], 0
	v_mfma_f32_16x16x128_f8f6f4 v[62:65], v[2:9], v[224:231], 0
	s_setprio 0
	s_setprio 1
	v_mfma_f32_16x16x128_f8f6f4 v[54:57], v[2:9], v[232:239], 0
	v_mfma_f32_16x16x128_f8f6f4 v[50:53], v[192:199], v[232:239], 0
	v_mfma_f32_16x16x128_f8f6f4 v[18:21], v[208:215], v[232:239], 0
	v_mfma_f32_16x16x128_f8f6f4 v[22:25], v[200:207], v[232:239], 0
	v_mfma_f32_16x16x128_f8f6f4 v[14:17], v[200:207], v[242:249], 0
	v_mfma_f32_16x16x128_f8f6f4 v[10:13], v[208:215], v[242:249], 0
	v_mfma_f32_16x16x128_f8f6f4 v[42:45], v[192:199], v[242:249], 0
	v_mfma_f32_16x16x128_f8f6f4 v[46:49], v[2:9], v[242:249], 0
	s_barrier
	s_setprio 0
	ds_read_b128 v[2:5], v189 offset:32768
	ds_read_b128 v[6:9], v189 offset:33792
	ds_read_b128 v[192:195], v189 offset:34816
	ds_read_b128 v[196:199], v189 offset:35840
	ds_read_b128 v[200:203], v189 offset:49152
	ds_read_b128 v[204:207], v189 offset:50176
	ds_read_b128 v[208:211], v189 offset:51200
	ds_read_b128 v[212:215], v189 offset:52224
	ds_read_b128 v[216:219], v190 offset:32768
	ds_read_b128 v[220:223], v190 offset:33792
	ds_read_b128 v[224:227], v190 offset:34816
	ds_read_b128 v[228:231], v190 offset:35840
	ds_read_b128 v[232:235], v190 offset:36864
	ds_read_b128 v[236:239], v190 offset:37888
	ds_read_b128 v[242:245], v190 offset:38912
	ds_read_b128 v[246:249], v190 offset:39936
	s_add_u32 s50, s50, 0x80000
	s_addc_u32 s51, s51, 0
	s_mov_b32 m0, s52
	v_lshl_add_u64 v[186:187], s[50:51], 0, v[154:155]
	global_load_lds_dwordx4 v[186:187], off
	v_lshl_add_u64 v[186:187], s[50:51], 0, v[158:159]
	s_mov_b32 m0, s53
	s_nop 0
	global_load_lds_dwordx4 v[186:187], off
	s_waitcnt vmcnt(8)
	s_waitcnt lgkmcnt(0)
	s_setprio 1
	s_barrier
	v_mfma_f32_16x16x128_f8f6f4 v[134:137], v[2:9], v[216:223], v[134:137]
	v_mfma_f32_16x16x128_f8f6f4 v[130:133], v[192:199], v[216:223], v[130:133]
	v_mfma_f32_16x16x128_f8f6f4 v[98:101], v[208:215], v[216:223], v[98:101]
	v_mfma_f32_16x16x128_f8f6f4 v[102:105], v[200:207], v[216:223], v[102:105]
	v_mfma_f32_16x16x128_f8f6f4 v[94:97], v[200:207], v[224:231], v[94:97]
	v_mfma_f32_16x16x128_f8f6f4 v[90:93], v[208:215], v[224:231], v[90:93]
	v_mfma_f32_16x16x128_f8f6f4 v[122:125], v[192:199], v[224:231], v[122:125]
	v_mfma_f32_16x16x128_f8f6f4 v[126:129], v[2:9], v[224:231], v[126:129]
	s_setprio 0
	s_setprio 1
	v_mfma_f32_16x16x128_f8f6f4 v[118:121], v[2:9], v[232:239], v[118:121]
	v_mfma_f32_16x16x128_f8f6f4 v[114:117], v[192:199], v[232:239], v[114:117]
	v_mfma_f32_16x16x128_f8f6f4 v[82:85], v[208:215], v[232:239], v[82:85]
	v_mfma_f32_16x16x128_f8f6f4 v[86:89], v[200:207], v[232:239], v[86:89]
	v_mfma_f32_16x16x128_f8f6f4 v[78:81], v[200:207], v[242:249], v[78:81]
	v_mfma_f32_16x16x128_f8f6f4 v[74:77], v[208:215], v[242:249], v[74:77]
	v_mfma_f32_16x16x128_f8f6f4 v[106:109], v[192:199], v[242:249], v[106:109]
	v_mfma_f32_16x16x128_f8f6f4 v[110:113], v[2:9], v[242:249], v[110:113]
	s_barrier
	s_setprio 0
	ds_read_b128 v[216:219], v190 offset:49152
	ds_read_b128 v[220:223], v190 offset:50176
	ds_read_b128 v[224:227], v190 offset:51200
	ds_read_b128 v[228:231], v190 offset:52224
	ds_read_b128 v[232:235], v190 offset:53248
	ds_read_b128 v[236:239], v190 offset:54272
	ds_read_b128 v[242:245], v190 offset:55296
	ds_read_b128 v[246:249], v190 offset:56320
	s_mov_b32 m0, s70
	v_lshl_add_u64 v[174:175], v[174:175], 0, s[18:19]
	s_add_u32 s48, s48, 0x80080
	global_load_lds_dwordx4 v[174:175], off
	v_lshl_add_u64 v[174:175], v[176:177], 0, s[18:19]
	s_mov_b32 m0, s71
	s_addc_u32 s49, s49, 0
	global_load_lds_dwordx4 v[174:175], off
	v_lshl_add_u64 v[174:175], s[48:49], 0, v[156:157]
	s_mov_b32 m0, s74
	s_nop 0
	global_load_lds_dwordx4 v[174:175], off
	v_lshl_add_u64 v[174:175], s[48:49], 0, v[160:161]
	s_mov_b32 m0, s75
	s_nop 0
	global_load_lds_dwordx4 v[174:175], off
	v_lshl_add_u64 v[174:175], v[182:183], 0, s[18:19]
	s_mov_b32 m0, s72
	s_nop 0
	global_load_lds_dwordx4 v[174:175], off
	v_lshl_add_u64 v[174:175], v[184:185], 0, s[18:19]
	s_mov_b32 m0, s73
	s_nop 0
	global_load_lds_dwordx4 v[174:175], off
	s_waitcnt vmcnt(8)
	s_waitcnt lgkmcnt(0)
	s_setprio 1
	s_barrier
	v_mfma_f32_16x16x128_f8f6f4 v[70:73], v[2:9], v[216:223], v[70:73]
	v_mfma_f32_16x16x128_f8f6f4 v[66:69], v[192:199], v[216:223], v[66:69]
	v_mfma_f32_16x16x128_f8f6f4 v[34:37], v[208:215], v[216:223], v[34:37]
	v_mfma_f32_16x16x128_f8f6f4 v[38:41], v[200:207], v[216:223], v[38:41]
	v_mfma_f32_16x16x128_f8f6f4 v[30:33], v[200:207], v[224:231], v[30:33]
	v_mfma_f32_16x16x128_f8f6f4 v[26:29], v[208:215], v[224:231], v[26:29]
	v_mfma_f32_16x16x128_f8f6f4 v[58:61], v[192:199], v[224:231], v[58:61]
	v_mfma_f32_16x16x128_f8f6f4 v[62:65], v[2:9], v[224:231], v[62:65]
	s_setprio 0
	s_setprio 1
	v_mfma_f32_16x16x128_f8f6f4 v[54:57], v[2:9], v[232:239], v[54:57]
	v_mfma_f32_16x16x128_f8f6f4 v[50:53], v[192:199], v[232:239], v[50:53]
	v_mfma_f32_16x16x128_f8f6f4 v[18:21], v[208:215], v[232:239], v[18:21]
	v_mfma_f32_16x16x128_f8f6f4 v[22:25], v[200:207], v[232:239], v[22:25]
	v_mfma_f32_16x16x128_f8f6f4 v[14:17], v[200:207], v[242:249], v[14:17]
	v_mfma_f32_16x16x128_f8f6f4 v[10:13], v[208:215], v[242:249], v[10:13]
	v_mfma_f32_16x16x128_f8f6f4 v[42:45], v[192:199], v[242:249], v[42:45]
	v_mfma_f32_16x16x128_f8f6f4 v[46:49], v[2:9], v[242:249], v[46:49]
	s_barrier
	s_setprio 0
	s_cmp_lt_u32 s86, 3
	s_cbranch_scc1 .LBB0_796
	s_add_u32 s48, s55, s62
	s_addc_u32 s49, s61, s41
	s_add_u32 s46, s46, 0x80180
	s_addc_u32 s47, s47, 0
	s_add_u32 s41, s44, 0x200
	v_lshl_add_u64 v[174:175], v[172:173], 2, s[48:49]
	s_addc_u32 s50, s45, 0
	s_mov_b32 s51, 4
	s_cmp_eq_u32 s86, s51
	s_cselect_b64 s[44:45], -1, 0
	s_cmp_lg_u32 s86, s51
	s_cbranch_scc1 .LBB0_794

.LBB0_794:
	ds_read_b128 v[2:5], v189
	ds_read_b128 v[6:9], v189 offset:1024
	ds_read_b128 v[192:195], v189 offset:2048
	ds_read_b128 v[196:199], v189 offset:3072
	ds_read_b128 v[200:203], v189 offset:16384
	ds_read_b128 v[204:207], v189 offset:17408
	ds_read_b128 v[208:211], v189 offset:18432
	ds_read_b128 v[212:215], v189 offset:19456
	ds_read_b128 v[216:219], v190
	ds_read_b128 v[220:223], v190 offset:1024
	ds_read_b128 v[224:227], v190 offset:2048
	ds_read_b128 v[228:231], v190 offset:3072
	ds_read_b128 v[232:235], v190 offset:4096
	ds_read_b128 v[236:239], v190 offset:5120
	ds_read_b128 v[242:245], v190 offset:6144
	ds_read_b128 v[246:249], v190 offset:7168
	s_add_u32 s48, s46, 0xfff80080
	s_addc_u32 s49, s47, -1
	s_and_b64 s[44:45], s[44:45], exec
	s_cselect_b32 s44, s4, s41
	s_cselect_b32 s49, s1, s49
	s_cselect_b32 s48, s0, s48
	s_cselect_b32 s45, s5, s50
	s_mov_b32 m0, s37
	v_lshl_add_u64 v[176:177], s[46:47], 0, v[162:163]
	global_load_lds_dwordx4 v[176:177], off
	v_lshl_add_u64 v[176:177], s[46:47], 0, v[164:165]
	s_mov_b32 m0, s39
	s_nop 0
	global_load_lds_dwordx4 v[176:177], off
	s_waitcnt vmcnt(8)
	s_waitcnt lgkmcnt(0)
	s_setprio 1
	s_barrier
	v_mfma_f32_16x16x128_f8f6f4 v[134:137], v[2:9], v[216:223], v[134:137]
	v_mfma_f32_16x16x128_f8f6f4 v[130:133], v[192:199], v[216:223], v[130:133]
	v_mfma_f32_16x16x128_f8f6f4 v[98:101], v[208:215], v[216:223], v[98:101]
	v_mfma_f32_16x16x128_f8f6f4 v[102:105], v[200:207], v[216:223], v[102:105]
	v_mfma_f32_16x16x128_f8f6f4 v[94:97], v[200:207], v[224:231], v[94:97]
	v_mfma_f32_16x16x128_f8f6f4 v[90:93], v[208:215], v[224:231], v[90:93]
	v_mfma_f32_16x16x128_f8f6f4 v[122:125], v[192:199], v[224:231], v[122:125]
	v_mfma_f32_16x16x128_f8f6f4 v[126:129], v[2:9], v[224:231], v[126:129]
	s_setprio 0
	s_setprio 1
	v_mfma_f32_16x16x128_f8f6f4 v[118:121], v[2:9], v[232:239], v[118:121]
	v_mfma_f32_16x16x128_f8f6f4 v[114:117], v[192:199], v[232:239], v[114:117]
	v_mfma_f32_16x16x128_f8f6f4 v[82:85], v[208:215], v[232:239], v[82:85]
	v_mfma_f32_16x16x128_f8f6f4 v[86:89], v[200:207], v[232:239], v[86:89]
	v_mfma_f32_16x16x128_f8f6f4 v[78:81], v[200:207], v[242:249], v[78:81]
	v_mfma_f32_16x16x128_f8f6f4 v[74:77], v[208:215], v[242:249], v[74:77]
	v_mfma_f32_16x16x128_f8f6f4 v[106:109], v[192:199], v[242:249], v[106:109]
	v_mfma_f32_16x16x128_f8f6f4 v[110:113], v[2:9], v[242:249], v[110:113]
	s_barrier
	s_setprio 0
	ds_read_b128 v[216:219], v190 offset:16384
	ds_read_b128 v[220:223], v190 offset:17408
	ds_read_b128 v[224:227], v190 offset:18432
	ds_read_b128 v[228:231], v190 offset:19456
	ds_read_b128 v[232:235], v190 offset:20480
	ds_read_b128 v[236:239], v190 offset:21504
	ds_read_b128 v[242:245], v190 offset:22528
	ds_read_b128 v[246:249], v190 offset:23552
	s_mov_b32 m0, s9
	v_lshl_add_u64 v[176:177], s[44:45], 0, v[156:157]
	s_add_u32 s62, s44, 0x80000
	global_load_lds_dwordx4 v[176:177], off
	v_lshl_add_u64 v[182:183], s[44:45], 0, v[160:161]
	s_mov_b32 m0, s27
	s_addc_u32 s63, s45, 0
	global_load_lds_dwordx4 v[182:183], off
	v_lshl_add_u64 v[184:185], s[62:63], 0, v[156:157]
	s_mov_b32 m0, s33
	v_lshl_add_u64 v[186:187], s[48:49], 0, v[158:159]
	global_load_lds_dwordx4 v[184:185], off
	v_lshl_add_u64 v[184:185], s[62:63], 0, v[160:161]
	s_mov_b32 m0, s35
	s_nop 0
	global_load_lds_dwordx4 v[184:185], off
	v_lshl_add_u64 v[184:185], s[48:49], 0, v[154:155]
	s_mov_b32 m0, s8
	s_nop 0
	global_load_lds_dwordx4 v[184:185], off
	s_mov_b32 m0, s43
	s_nop 0
	global_load_lds_dwordx4 v[186:187], off
	s_waitcnt vmcnt(8)
	s_waitcnt lgkmcnt(0)
	s_setprio 1
	s_barrier
	v_mfma_f32_16x16x128_f8f6f4 v[70:73], v[2:9], v[216:223], v[70:73]
	v_mfma_f32_16x16x128_f8f6f4 v[66:69], v[192:199], v[216:223], v[66:69]
	v_mfma_f32_16x16x128_f8f6f4 v[34:37], v[208:215], v[216:223], v[34:37]
	v_mfma_f32_16x16x128_f8f6f4 v[38:41], v[200:207], v[216:223], v[38:41]
	v_mfma_f32_16x16x128_f8f6f4 v[30:33], v[200:207], v[224:231], v[30:33]
	v_mfma_f32_16x16x128_f8f6f4 v[26:29], v[208:215], v[224:231], v[26:29]
	v_mfma_f32_16x16x128_f8f6f4 v[58:61], v[192:199], v[224:231], v[58:61]
	v_mfma_f32_16x16x128_f8f6f4 v[62:65], v[2:9], v[224:231], v[62:65]
	s_setprio 0
	s_setprio 1
	v_mfma_f32_16x16x128_f8f6f4 v[54:57], v[2:9], v[232:239], v[54:57]
	v_mfma_f32_16x16x128_f8f6f4 v[50:53], v[192:199], v[232:239], v[50:53]
	v_mfma_f32_16x16x128_f8f6f4 v[18:21], v[208:215], v[232:239], v[18:21]
	v_mfma_f32_16x16x128_f8f6f4 v[22:25], v[200:207], v[232:239], v[22:25]
	v_mfma_f32_16x16x128_f8f6f4 v[14:17], v[200:207], v[242:249], v[14:17]
	v_mfma_f32_16x16x128_f8f6f4 v[10:13], v[208:215], v[242:249], v[10:13]
	v_mfma_f32_16x16x128_f8f6f4 v[42:45], v[192:199], v[242:249], v[42:45]
	v_mfma_f32_16x16x128_f8f6f4 v[46:49], v[2:9], v[242:249], v[46:49]
	s_barrier
	s_setprio 0
	ds_read_b128 v[192:195], v189 offset:32768
	ds_read_b128 v[196:199], v189 offset:33792
	ds_read_b128 v[200:203], v189 offset:34816
	ds_read_b128 v[204:207], v189 offset:35840
	ds_read_b128 v[2:5], v189 offset:49152
	ds_read_b128 v[6:9], v189 offset:50176
	ds_read_b128 v[208:211], v189 offset:51200
	ds_read_b128 v[212:215], v189 offset:52224
	ds_read_b128 v[216:219], v190 offset:32768
	ds_read_b128 v[220:223], v190 offset:33792
	ds_read_b128 v[224:227], v190 offset:34816
	ds_read_b128 v[228:231], v190 offset:35840
	ds_read_b128 v[232:235], v190 offset:36864
	ds_read_b128 v[236:239], v190 offset:37888
	ds_read_b128 v[242:245], v190 offset:38912
	ds_read_b128 v[246:249], v190 offset:39936
	s_add_u32 s48, s48, 0x80000
	s_addc_u32 s49, s49, 0
	s_mov_b32 m0, s52
	v_lshl_add_u64 v[252:253], s[48:49], 0, v[154:155]
	global_load_lds_dwordx4 v[252:253], off
	v_lshl_add_u64 v[252:253], s[48:49], 0, v[158:159]
	s_mov_b32 m0, s53
	s_nop 0
	global_load_lds_dwordx4 v[252:253], off
	s_waitcnt vmcnt(8)
	s_waitcnt lgkmcnt(0)
	s_setprio 1
	s_barrier
	v_mfma_f32_16x16x128_f8f6f4 v[134:137], v[192:199], v[216:223], v[134:137]
	v_mfma_f32_16x16x128_f8f6f4 v[130:133], v[200:207], v[216:223], v[130:133]
	v_mfma_f32_16x16x128_f8f6f4 v[98:101], v[208:215], v[216:223], v[98:101]
	v_mfma_f32_16x16x128_f8f6f4 v[102:105], v[2:9], v[216:223], v[102:105]
	v_mfma_f32_16x16x128_f8f6f4 v[94:97], v[2:9], v[224:231], v[94:97]
	v_mfma_f32_16x16x128_f8f6f4 v[90:93], v[208:215], v[224:231], v[90:93]
	v_mfma_f32_16x16x128_f8f6f4 v[122:125], v[200:207], v[224:231], v[122:125]
	v_mfma_f32_16x16x128_f8f6f4 v[126:129], v[192:199], v[224:231], v[126:129]
	s_setprio 0
	s_setprio 1
	v_mfma_f32_16x16x128_f8f6f4 v[118:121], v[192:199], v[232:239], v[118:121]
	v_mfma_f32_16x16x128_f8f6f4 v[114:117], v[200:207], v[232:239], v[114:117]
	v_mfma_f32_16x16x128_f8f6f4 v[82:85], v[208:215], v[232:239], v[82:85]
	v_mfma_f32_16x16x128_f8f6f4 v[86:89], v[2:9], v[232:239], v[86:89]
	v_mfma_f32_16x16x128_f8f6f4 v[78:81], v[2:9], v[242:249], v[78:81]
	v_mfma_f32_16x16x128_f8f6f4 v[74:77], v[208:215], v[242:249], v[74:77]
	v_mfma_f32_16x16x128_f8f6f4 v[106:109], v[200:207], v[242:249], v[106:109]
	v_mfma_f32_16x16x128_f8f6f4 v[110:113], v[192:199], v[242:249], v[110:113]
	s_barrier
	s_setprio 0
	ds_read_b128 v[216:219], v190 offset:49152
	ds_read_b128 v[220:223], v190 offset:50176
	ds_read_b128 v[224:227], v190 offset:51200
	ds_read_b128 v[228:231], v190 offset:52224
	ds_read_b128 v[232:235], v190 offset:53248
	ds_read_b128 v[236:239], v190 offset:54272
	ds_read_b128 v[242:245], v190 offset:55296
	ds_read_b128 v[246:249], v190 offset:56320
	s_mov_b32 m0, s70
	v_lshl_add_u64 v[176:177], v[176:177], 0, s[18:19]
	s_add_u32 s44, s44, 0x80080
	global_load_lds_dwordx4 v[176:177], off
	v_lshl_add_u64 v[176:177], v[182:183], 0, s[18:19]
	s_mov_b32 m0, s71
	s_addc_u32 s45, s45, 0
	global_load_lds_dwordx4 v[176:177], off
	v_lshl_add_u64 v[176:177], s[44:45], 0, v[156:157]
	s_mov_b32 m0, s74
	s_nop 0
	global_load_lds_dwordx4 v[176:177], off
	v_lshl_add_u64 v[176:177], s[44:45], 0, v[160:161]
	s_mov_b32 m0, s75
	s_nop 0
	global_load_lds_dwordx4 v[176:177], off
	v_lshl_add_u64 v[176:177], v[184:185], 0, s[18:19]
	s_mov_b32 m0, s72
	s_nop 0
	global_load_lds_dwordx4 v[176:177], off
	v_lshl_add_u64 v[176:177], v[186:187], 0, s[18:19]
	s_mov_b32 m0, s73
	s_nop 0
	global_load_lds_dwordx4 v[176:177], off
	s_waitcnt vmcnt(8)
	s_waitcnt lgkmcnt(0)
	s_setprio 1
	s_barrier
	v_mfma_f32_16x16x128_f8f6f4 v[70:73], v[192:199], v[216:223], v[70:73]
	v_mfma_f32_16x16x128_f8f6f4 v[66:69], v[200:207], v[216:223], v[66:69]
	v_mfma_f32_16x16x128_f8f6f4 v[34:37], v[208:215], v[216:223], v[34:37]
	v_mfma_f32_16x16x128_f8f6f4 v[38:41], v[2:9], v[216:223], v[38:41]
	v_mfma_f32_16x16x128_f8f6f4 v[30:33], v[2:9], v[224:231], v[30:33]
	v_mfma_f32_16x16x128_f8f6f4 v[26:29], v[208:215], v[224:231], v[26:29]
	v_mfma_f32_16x16x128_f8f6f4 v[58:61], v[200:207], v[224:231], v[58:61]
	v_mfma_f32_16x16x128_f8f6f4 v[62:65], v[192:199], v[224:231], v[62:65]
	s_setprio 0
	s_setprio 1
	v_mfma_f32_16x16x128_f8f6f4 v[54:57], v[192:199], v[232:239], v[54:57]
	v_mfma_f32_16x16x128_f8f6f4 v[50:53], v[200:207], v[232:239], v[50:53]
	v_mfma_f32_16x16x128_f8f6f4 v[18:21], v[208:215], v[232:239], v[18:21]
	v_mfma_f32_16x16x128_f8f6f4 v[22:25], v[2:9], v[232:239], v[22:25]
	v_mfma_f32_16x16x128_f8f6f4 v[14:17], v[2:9], v[242:249], v[14:17]
	v_mfma_f32_16x16x128_f8f6f4 v[10:13], v[208:215], v[242:249], v[10:13]
	v_mfma_f32_16x16x128_f8f6f4 v[42:45], v[200:207], v[242:249], v[42:45]
	v_mfma_f32_16x16x128_f8f6f4 v[46:49], v[192:199], v[242:249], v[46:49]
	s_barrier
	s_setprio 0
	s_add_i32 s44, s51, 2
	s_add_u32 s46, s46, 0x100
	s_addc_u32 s47, s47, 0
	s_add_u32 s41, s41, 0x100
	s_addc_u32 s50, s50, 0
	s_cmp_ge_i32 s51, s86
	s_cbranch_scc1 .LBB0_796
	s_mov_b32 s51, s44
	s_cmp_eq_u32 s86, s51
	s_cselect_b64 s[44:45], -1, 0
	s_cmp_lg_u32 s86, s51
	s_cbranch_scc0 .LBB0_793
	s_branch .LBB0_794

.LBB0_946:
	ds_read_b128 v[18:21], v192
	ds_read_b128 v[22:25], v192 offset:1024
	ds_read_b128 v[26:29], v192 offset:2048
	ds_read_b128 v[30:33], v192 offset:3072
	ds_read_b128 v[2:5], v192 offset:16384
	ds_read_b128 v[6:9], v192 offset:17408
	ds_read_b128 v[10:13], v192 offset:18432
	ds_read_b128 v[14:17], v192 offset:19456
	ds_read_b128 v[184:187], v193
	ds_read_b128 v[188:191], v193 offset:1024
	ds_read_b128 v[194:197], v193 offset:2048
	ds_read_b128 v[198:201], v193 offset:3072
	ds_read_b128 v[202:205], v193 offset:4096
	ds_read_b128 v[206:209], v193 offset:5120
	ds_read_b128 v[210:213], v193 offset:6144
	ds_read_b128 v[214:217], v193 offset:7168
	s_ashr_i32 s37, s36, 31
	s_lshl_b64 s[38:39], s[36:37], 20
	s_add_u32 s38, s22, s38
	s_addc_u32 s39, s23, s39
	s_and_b64 s[40:41], s[2:3], exec
	s_cselect_b32 s37, s39, s47
	s_cselect_b32 s84, s38, s46
	s_ashr_i32 s27, s26, 31
	s_lshl_b64 s[40:41], s[26:27], 20
	s_add_u32 s40, s25, s40
	s_addc_u32 s41, s35, s41
	s_and_b64 s[48:49], s[2:3], exec
	s_cselect_b32 s27, s41, s45
	s_cselect_b32 s85, s40, s44
	s_add_u32 s48, s46, 0x80080
	s_addc_u32 s49, s47, 0
	s_mov_b32 m0, s80
	v_lshl_add_u64 v[218:219], s[48:49], 0, v[164:165]
	global_load_lds_dwordx4 v[218:219], off
	v_lshl_add_u64 v[218:219], s[48:49], 0, v[168:169]
	s_mov_b32 m0, s81
	s_nop 0
	global_load_lds_dwordx4 v[218:219], off
	s_waitcnt vmcnt(8)
	s_waitcnt lgkmcnt(0)
	s_setprio 1
	s_barrier
	v_mfma_f32_16x16x128_f8f6f4 v[158:161], v[18:25], v[184:191], 0
	v_mfma_f32_16x16x128_f8f6f4 v[154:157], v[26:33], v[184:191], 0
	v_mfma_f32_16x16x128_f8f6f4 v[122:125], v[10:17], v[184:191], 0
	v_mfma_f32_16x16x128_f8f6f4 v[126:129], v[2:9], v[184:191], 0
	v_mfma_f32_16x16x128_f8f6f4 v[118:121], v[2:9], v[194:201], 0
	v_mfma_f32_16x16x128_f8f6f4 v[114:117], v[10:17], v[194:201], 0
	v_mfma_f32_16x16x128_f8f6f4 v[146:149], v[26:33], v[194:201], 0
	v_mfma_f32_16x16x128_f8f6f4 v[150:153], v[18:25], v[194:201], 0
	s_setprio 0
	s_setprio 1
	v_mfma_f32_16x16x128_f8f6f4 v[142:145], v[18:25], v[202:209], 0
	v_mfma_f32_16x16x128_f8f6f4 v[138:141], v[26:33], v[202:209], 0
	v_mfma_f32_16x16x128_f8f6f4 v[106:109], v[10:17], v[202:209], 0
	v_mfma_f32_16x16x128_f8f6f4 v[110:113], v[2:9], v[202:209], 0
	v_mfma_f32_16x16x128_f8f6f4 v[102:105], v[2:9], v[210:217], 0
	v_mfma_f32_16x16x128_f8f6f4 v[98:101], v[10:17], v[210:217], 0
	v_mfma_f32_16x16x128_f8f6f4 v[130:133], v[26:33], v[210:217], 0
	v_mfma_f32_16x16x128_f8f6f4 v[134:137], v[18:25], v[210:217], 0
	s_barrier
	s_setprio 0
	ds_read_b128 v[194:197], v193 offset:16384
	ds_read_b128 v[198:201], v193 offset:17408
	ds_read_b128 v[202:205], v193 offset:18432
	ds_read_b128 v[206:209], v193 offset:19456
	ds_read_b128 v[210:213], v193 offset:20480
	ds_read_b128 v[214:217], v193 offset:21504
	ds_read_b128 v[218:221], v193 offset:22528
	ds_read_b128 v[222:225], v193 offset:23552
	v_lshl_add_u64 v[184:185], s[44:45], 0, v[166:167]
	s_mov_b32 m0, s52
	v_lshl_add_u64 v[186:187], v[184:185], 0, s[14:15]
	global_load_lds_dwordx4 v[186:187], off
	v_lshl_add_u64 v[186:187], s[44:45], 0, v[170:171]
	s_add_u32 s48, s44, 0x80100
	v_lshl_add_u64 v[188:189], v[186:187], 0, s[14:15]
	s_mov_b32 m0, s53
	s_addc_u32 s49, s45, 0
	global_load_lds_dwordx4 v[188:189], off
	v_lshl_add_u64 v[188:189], s[48:49], 0, v[166:167]
	s_mov_b32 m0, s54
	s_nop 0
	global_load_lds_dwordx4 v[188:189], off
	v_lshl_add_u64 v[188:189], s[48:49], 0, v[170:171]
	s_mov_b32 m0, s55
	s_nop 0
	global_load_lds_dwordx4 v[188:189], off
	v_lshl_add_u64 v[188:189], s[46:47], 0, v[164:165]
	v_lshl_add_u64 v[190:191], v[188:189], 0, s[14:15]
	s_mov_b32 m0, s43
	s_nop 0
	global_load_lds_dwordx4 v[190:191], off
	v_lshl_add_u64 v[190:191], s[46:47], 0, v[168:169]
	v_lshl_add_u64 v[226:227], v[190:191], 0, s[14:15]
	s_mov_b32 m0, s61
	s_nop 0
	global_load_lds_dwordx4 v[226:227], off
	s_waitcnt vmcnt(8)
	s_waitcnt lgkmcnt(0)
	s_setprio 1
	s_barrier
	v_mfma_f32_16x16x128_f8f6f4 v[94:97], v[18:25], v[194:201], 0
	v_mfma_f32_16x16x128_f8f6f4 v[90:93], v[26:33], v[194:201], 0
	v_mfma_f32_16x16x128_f8f6f4 v[58:61], v[10:17], v[194:201], 0
	v_mfma_f32_16x16x128_f8f6f4 v[62:65], v[2:9], v[194:201], 0
	v_mfma_f32_16x16x128_f8f6f4 v[54:57], v[2:9], v[202:209], 0
	v_mfma_f32_16x16x128_f8f6f4 v[50:53], v[10:17], v[202:209], 0
	v_mfma_f32_16x16x128_f8f6f4 v[82:85], v[26:33], v[202:209], 0
	v_mfma_f32_16x16x128_f8f6f4 v[86:89], v[18:25], v[202:209], 0
	s_setprio 0
	s_setprio 1
	v_mfma_f32_16x16x128_f8f6f4 v[78:81], v[18:25], v[210:217], 0
	v_mfma_f32_16x16x128_f8f6f4 v[74:77], v[26:33], v[210:217], 0
	v_mfma_f32_16x16x128_f8f6f4 v[42:45], v[10:17], v[210:217], 0
	v_mfma_f32_16x16x128_f8f6f4 v[46:49], v[2:9], v[210:217], 0
	v_mfma_f32_16x16x128_f8f6f4 v[38:41], v[2:9], v[218:225], 0
	v_mfma_f32_16x16x128_f8f6f4 v[34:37], v[10:17], v[218:225], 0
	v_mfma_f32_16x16x128_f8f6f4 v[66:69], v[26:33], v[218:225], 0
	v_mfma_f32_16x16x128_f8f6f4 v[70:73], v[18:25], v[218:225], 0
	s_barrier
	s_setprio 0
	ds_read_b128 v[18:21], v192 offset:32768
	ds_read_b128 v[22:25], v192 offset:33792
	ds_read_b128 v[26:29], v192 offset:34816
	ds_read_b128 v[30:33], v192 offset:35840
	ds_read_b128 v[2:5], v192 offset:49152
	ds_read_b128 v[6:9], v192 offset:50176
	ds_read_b128 v[10:13], v192 offset:51200
	ds_read_b128 v[14:17], v192 offset:52224
	ds_read_b128 v[194:197], v193 offset:32768
	ds_read_b128 v[198:201], v193 offset:33792
	ds_read_b128 v[202:205], v193 offset:34816
	ds_read_b128 v[206:209], v193 offset:35840
	ds_read_b128 v[210:213], v193 offset:36864
	ds_read_b128 v[214:217], v193 offset:37888
	ds_read_b128 v[218:221], v193 offset:38912
	ds_read_b128 v[222:225], v193 offset:39936
	s_add_u32 s48, s46, 0x80100
	s_addc_u32 s49, s47, 0
	s_mov_b32 m0, s68
	v_lshl_add_u64 v[226:227], s[48:49], 0, v[164:165]
	global_load_lds_dwordx4 v[226:227], off
	v_lshl_add_u64 v[226:227], s[48:49], 0, v[168:169]
	s_mov_b32 m0, s69
	s_nop 0
	global_load_lds_dwordx4 v[226:227], off
	s_waitcnt vmcnt(8)
	s_waitcnt lgkmcnt(0)
	s_setprio 1
	s_barrier
	v_mfma_f32_16x16x128_f8f6f4 v[158:161], v[18:25], v[194:201], v[158:161]
	v_mfma_f32_16x16x128_f8f6f4 v[154:157], v[26:33], v[194:201], v[154:157]
	v_mfma_f32_16x16x128_f8f6f4 v[122:125], v[10:17], v[194:201], v[122:125]
	v_mfma_f32_16x16x128_f8f6f4 v[126:129], v[2:9], v[194:201], v[126:129]
	v_mfma_f32_16x16x128_f8f6f4 v[118:121], v[2:9], v[202:209], v[118:121]
	v_mfma_f32_16x16x128_f8f6f4 v[114:117], v[10:17], v[202:209], v[114:117]
	v_mfma_f32_16x16x128_f8f6f4 v[146:149], v[26:33], v[202:209], v[146:149]
	v_mfma_f32_16x16x128_f8f6f4 v[150:153], v[18:25], v[202:209], v[150:153]
	s_setprio 0
	s_setprio 1
	v_mfma_f32_16x16x128_f8f6f4 v[142:145], v[18:25], v[210:217], v[142:145]
	v_mfma_f32_16x16x128_f8f6f4 v[138:141], v[26:33], v[210:217], v[138:141]
	v_mfma_f32_16x16x128_f8f6f4 v[106:109], v[10:17], v[210:217], v[106:109]
	v_mfma_f32_16x16x128_f8f6f4 v[110:113], v[2:9], v[210:217], v[110:113]
	v_mfma_f32_16x16x128_f8f6f4 v[102:105], v[2:9], v[218:225], v[102:105]
	v_mfma_f32_16x16x128_f8f6f4 v[98:101], v[10:17], v[218:225], v[98:101]
	v_mfma_f32_16x16x128_f8f6f4 v[130:133], v[26:33], v[218:225], v[130:133]
	v_mfma_f32_16x16x128_f8f6f4 v[134:137], v[18:25], v[218:225], v[134:137]
	s_barrier
	s_setprio 0
	ds_read_b128 v[194:197], v193 offset:49152
	ds_read_b128 v[198:201], v193 offset:50176
	ds_read_b128 v[202:205], v193 offset:51200
	ds_read_b128 v[206:209], v193 offset:52224
	ds_read_b128 v[210:213], v193 offset:53248
	ds_read_b128 v[214:217], v193 offset:54272
	ds_read_b128 v[218:221], v193 offset:55296
	ds_read_b128 v[222:225], v193 offset:56320
	s_mov_b32 m0, s74
	v_lshl_add_u64 v[184:185], v[184:185], 0, s[18:19]
	s_add_u32 s48, s44, 0x80180
	global_load_lds_dwordx4 v[184:185], off
	v_lshl_add_u64 v[184:185], v[186:187], 0, s[18:19]
	s_mov_b32 m0, s75
	s_addc_u32 s49, s45, 0
	global_load_lds_dwordx4 v[184:185], off
	v_lshl_add_u64 v[184:185], s[48:49], 0, v[166:167]
	s_mov_b32 m0, s78
	s_nop 0
	global_load_lds_dwordx4 v[184:185], off
	v_lshl_add_u64 v[184:185], s[48:49], 0, v[170:171]
	s_mov_b32 m0, s79
	s_nop 0
	global_load_lds_dwordx4 v[184:185], off
	v_lshl_add_u64 v[184:185], v[188:189], 0, s[18:19]
	s_mov_b32 m0, s76
	s_nop 0
	global_load_lds_dwordx4 v[184:185], off
	v_lshl_add_u64 v[184:185], v[190:191], 0, s[18:19]
	s_mov_b32 m0, s77
	s_nop 0
	global_load_lds_dwordx4 v[184:185], off
	s_waitcnt vmcnt(8)
	s_waitcnt lgkmcnt(0)
	s_setprio 1
	s_barrier
	v_mfma_f32_16x16x128_f8f6f4 v[94:97], v[18:25], v[194:201], v[94:97]
	v_mfma_f32_16x16x128_f8f6f4 v[90:93], v[26:33], v[194:201], v[90:93]
	v_mfma_f32_16x16x128_f8f6f4 v[58:61], v[10:17], v[194:201], v[58:61]
	v_mfma_f32_16x16x128_f8f6f4 v[62:65], v[2:9], v[194:201], v[62:65]
	v_mfma_f32_16x16x128_f8f6f4 v[54:57], v[2:9], v[202:209], v[54:57]
	v_mfma_f32_16x16x128_f8f6f4 v[50:53], v[10:17], v[202:209], v[50:53]
	v_mfma_f32_16x16x128_f8f6f4 v[82:85], v[26:33], v[202:209], v[82:85]
	v_mfma_f32_16x16x128_f8f6f4 v[86:89], v[18:25], v[202:209], v[86:89]
	s_setprio 0
	s_setprio 1
	v_mfma_f32_16x16x128_f8f6f4 v[78:81], v[18:25], v[210:217], v[78:81]
	v_mfma_f32_16x16x128_f8f6f4 v[74:77], v[26:33], v[210:217], v[74:77]
	v_mfma_f32_16x16x128_f8f6f4 v[42:45], v[10:17], v[210:217], v[42:45]
	v_mfma_f32_16x16x128_f8f6f4 v[46:49], v[2:9], v[210:217], v[46:49]
	v_mfma_f32_16x16x128_f8f6f4 v[38:41], v[2:9], v[218:225], v[38:41]
	v_mfma_f32_16x16x128_f8f6f4 v[34:37], v[10:17], v[218:225], v[34:37]
	v_mfma_f32_16x16x128_f8f6f4 v[66:69], v[26:33], v[218:225], v[66:69]
	v_mfma_f32_16x16x128_f8f6f4 v[70:73], v[18:25], v[218:225], v[70:73]
	s_barrier
	s_setprio 0
	s_add_u32 s46, s46, 0x80180
	s_addc_u32 s47, s47, 0
	s_add_u32 s62, s44, 0x200
	s_addc_u32 s63, s45, 0
	s_mov_b32 s86, 0
.LBB0_947:
	ds_read_b128 v[2:5], v192
	ds_read_b128 v[6:9], v192 offset:1024
	ds_read_b128 v[18:21], v192 offset:2048
	ds_read_b128 v[22:25], v192 offset:3072
	ds_read_b128 v[26:29], v192 offset:16384
	ds_read_b128 v[30:33], v192 offset:17408
	ds_read_b128 v[184:187], v192 offset:18432
	ds_read_b128 v[188:191], v192 offset:19456
	ds_read_b128 v[10:13], v193
	ds_read_b128 v[14:17], v193 offset:1024
	ds_read_b128 v[194:197], v193 offset:2048
	ds_read_b128 v[198:201], v193 offset:3072
	ds_read_b128 v[202:205], v193 offset:4096
	ds_read_b128 v[206:209], v193 offset:5120
	ds_read_b128 v[210:213], v193 offset:6144
	ds_read_b128 v[214:217], v193 offset:7168
	s_add_u32 s44, s46, 0xfff80080
	s_addc_u32 s45, s47, -1
	s_cmp_eq_u32 s86, 28
	s_cselect_b32 s49, s37, s45
	s_cselect_b32 s48, s84, s44
	s_cselect_b32 s45, s27, s63
	s_cselect_b32 s44, s85, s62
	s_mov_b32 m0, s80
	v_lshl_add_u64 v[218:219], s[46:47], 0, v[172:173]
	global_load_lds_dwordx4 v[218:219], off
	v_lshl_add_u64 v[218:219], s[46:47], 0, v[174:175]
	s_mov_b32 m0, s81
	s_nop 0
	global_load_lds_dwordx4 v[218:219], off
	s_waitcnt vmcnt(8)
	s_waitcnt lgkmcnt(0)
	s_setprio 1
	s_barrier
	v_mfma_f32_16x16x128_f8f6f4 v[158:161], v[2:9], v[10:17], v[158:161]
	v_mfma_f32_16x16x128_f8f6f4 v[154:157], v[18:25], v[10:17], v[154:157]
	v_mfma_f32_16x16x128_f8f6f4 v[122:125], v[184:191], v[10:17], v[122:125]
	v_mfma_f32_16x16x128_f8f6f4 v[126:129], v[26:33], v[10:17], v[126:129]
	v_mfma_f32_16x16x128_f8f6f4 v[118:121], v[26:33], v[194:201], v[118:121]
	v_mfma_f32_16x16x128_f8f6f4 v[114:117], v[184:191], v[194:201], v[114:117]
	v_mfma_f32_16x16x128_f8f6f4 v[146:149], v[18:25], v[194:201], v[146:149]
	v_mfma_f32_16x16x128_f8f6f4 v[150:153], v[2:9], v[194:201], v[150:153]
	s_setprio 0
	s_setprio 1
	v_mfma_f32_16x16x128_f8f6f4 v[142:145], v[2:9], v[202:209], v[142:145]
	v_mfma_f32_16x16x128_f8f6f4 v[138:141], v[18:25], v[202:209], v[138:141]
	v_mfma_f32_16x16x128_f8f6f4 v[106:109], v[184:191], v[202:209], v[106:109]
	v_mfma_f32_16x16x128_f8f6f4 v[110:113], v[26:33], v[202:209], v[110:113]
	v_mfma_f32_16x16x128_f8f6f4 v[102:105], v[26:33], v[210:217], v[102:105]
	v_mfma_f32_16x16x128_f8f6f4 v[98:101], v[184:191], v[210:217], v[98:101]
	v_mfma_f32_16x16x128_f8f6f4 v[130:133], v[18:25], v[210:217], v[130:133]
	v_mfma_f32_16x16x128_f8f6f4 v[134:137], v[2:9], v[210:217], v[134:137]
	s_barrier
	s_setprio 0
	ds_read_b128 v[194:197], v193 offset:16384
	ds_read_b128 v[198:201], v193 offset:17408
	ds_read_b128 v[202:205], v193 offset:18432
	ds_read_b128 v[206:209], v193 offset:19456
	ds_read_b128 v[210:213], v193 offset:20480
	ds_read_b128 v[214:217], v193 offset:21504
	ds_read_b128 v[218:221], v193 offset:22528
	ds_read_b128 v[222:225], v193 offset:23552
	s_mov_b32 m0, s52
	v_lshl_add_u64 v[10:11], s[44:45], 0, v[166:167]
	s_add_u32 s88, s44, 0x80000
	global_load_lds_dwordx4 v[10:11], off
	v_lshl_add_u64 v[12:13], s[44:45], 0, v[170:171]
	s_mov_b32 m0, s53
	s_addc_u32 s89, s45, 0
	global_load_lds_dwordx4 v[12:13], off
	v_lshl_add_u64 v[14:15], s[88:89], 0, v[166:167]
	s_mov_b32 m0, s54
	v_lshl_add_u64 v[16:17], s[48:49], 0, v[168:169]
	global_load_lds_dwordx4 v[14:15], off
	v_lshl_add_u64 v[14:15], s[88:89], 0, v[170:171]
	s_mov_b32 m0, s55
	s_nop 0
	global_load_lds_dwordx4 v[14:15], off
	v_lshl_add_u64 v[14:15], s[48:49], 0, v[164:165]
	s_mov_b32 m0, s43
	s_nop 0
	global_load_lds_dwordx4 v[14:15], off
	s_mov_b32 m0, s61
	s_nop 0
	global_load_lds_dwordx4 v[16:17], off
	s_waitcnt vmcnt(8)
	s_waitcnt lgkmcnt(0)
	s_setprio 1
	s_barrier
	v_mfma_f32_16x16x128_f8f6f4 v[94:97], v[2:9], v[194:201], v[94:97]
	v_mfma_f32_16x16x128_f8f6f4 v[90:93], v[18:25], v[194:201], v[90:93]
	v_mfma_f32_16x16x128_f8f6f4 v[58:61], v[184:191], v[194:201], v[58:61]
	v_mfma_f32_16x16x128_f8f6f4 v[62:65], v[26:33], v[194:201], v[62:65]
	v_mfma_f32_16x16x128_f8f6f4 v[54:57], v[26:33], v[202:209], v[54:57]
	v_mfma_f32_16x16x128_f8f6f4 v[50:53], v[184:191], v[202:209], v[50:53]
	v_mfma_f32_16x16x128_f8f6f4 v[82:85], v[18:25], v[202:209], v[82:85]
	v_mfma_f32_16x16x128_f8f6f4 v[86:89], v[2:9], v[202:209], v[86:89]
	s_setprio 0
	s_setprio 1
	v_mfma_f32_16x16x128_f8f6f4 v[78:81], v[2:9], v[210:217], v[78:81]
	v_mfma_f32_16x16x128_f8f6f4 v[74:77], v[18:25], v[210:217], v[74:77]
	v_mfma_f32_16x16x128_f8f6f4 v[42:45], v[184:191], v[210:217], v[42:45]
	v_mfma_f32_16x16x128_f8f6f4 v[46:49], v[26:33], v[210:217], v[46:49]
	v_mfma_f32_16x16x128_f8f6f4 v[38:41], v[26:33], v[218:225], v[38:41]
	v_mfma_f32_16x16x128_f8f6f4 v[34:37], v[184:191], v[218:225], v[34:37]
	v_mfma_f32_16x16x128_f8f6f4 v[66:69], v[18:25], v[218:225], v[66:69]
	v_mfma_f32_16x16x128_f8f6f4 v[70:73], v[2:9], v[218:225], v[70:73]
	s_barrier
	s_setprio 0
	ds_read_b128 v[18:21], v192 offset:32768
	ds_read_b128 v[22:25], v192 offset:33792
	ds_read_b128 v[26:29], v192 offset:34816
	ds_read_b128 v[30:33], v192 offset:35840
	ds_read_b128 v[2:5], v192 offset:49152
	ds_read_b128 v[6:9], v192 offset:50176
	ds_read_b128 v[184:187], v192 offset:51200
	ds_read_b128 v[188:191], v192 offset:52224
	ds_read_b128 v[194:197], v193 offset:32768
	ds_read_b128 v[198:201], v193 offset:33792
	ds_read_b128 v[202:205], v193 offset:34816
	ds_read_b128 v[206:209], v193 offset:35840
	ds_read_b128 v[210:213], v193 offset:36864
	ds_read_b128 v[214:217], v193 offset:37888
	ds_read_b128 v[218:221], v193 offset:38912
	ds_read_b128 v[222:225], v193 offset:39936
	s_add_u32 s48, s48, 0x80000
	s_addc_u32 s49, s49, 0
	s_mov_b32 m0, s68
	v_lshl_add_u64 v[226:227], s[48:49], 0, v[164:165]
	global_load_lds_dwordx4 v[226:227], off
	v_lshl_add_u64 v[226:227], s[48:49], 0, v[168:169]
	s_mov_b32 m0, s69
	s_nop 0
	global_load_lds_dwordx4 v[226:227], off
	s_waitcnt vmcnt(8)
	s_waitcnt lgkmcnt(0)
	s_setprio 1
	s_barrier
	v_mfma_f32_16x16x128_f8f6f4 v[158:161], v[18:25], v[194:201], v[158:161]
	v_mfma_f32_16x16x128_f8f6f4 v[154:157], v[26:33], v[194:201], v[154:157]
	v_mfma_f32_16x16x128_f8f6f4 v[122:125], v[184:191], v[194:201], v[122:125]
	v_mfma_f32_16x16x128_f8f6f4 v[126:129], v[2:9], v[194:201], v[126:129]
	v_mfma_f32_16x16x128_f8f6f4 v[118:121], v[2:9], v[202:209], v[118:121]
	v_mfma_f32_16x16x128_f8f6f4 v[114:117], v[184:191], v[202:209], v[114:117]
	v_mfma_f32_16x16x128_f8f6f4 v[146:149], v[26:33], v[202:209], v[146:149]
	v_mfma_f32_16x16x128_f8f6f4 v[150:153], v[18:25], v[202:209], v[150:153]
	s_setprio 0
	s_setprio 1
	v_mfma_f32_16x16x128_f8f6f4 v[142:145], v[18:25], v[210:217], v[142:145]
	v_mfma_f32_16x16x128_f8f6f4 v[138:141], v[26:33], v[210:217], v[138:141]
	v_mfma_f32_16x16x128_f8f6f4 v[106:109], v[184:191], v[210:217], v[106:109]
	v_mfma_f32_16x16x128_f8f6f4 v[110:113], v[2:9], v[210:217], v[110:113]
	v_mfma_f32_16x16x128_f8f6f4 v[102:105], v[2:9], v[218:225], v[102:105]
	v_mfma_f32_16x16x128_f8f6f4 v[98:101], v[184:191], v[218:225], v[98:101]
	v_mfma_f32_16x16x128_f8f6f4 v[130:133], v[26:33], v[218:225], v[130:133]
	v_mfma_f32_16x16x128_f8f6f4 v[134:137], v[18:25], v[218:225], v[134:137]
	s_barrier
	s_setprio 0
	ds_read_b128 v[194:197], v193 offset:49152
	ds_read_b128 v[198:201], v193 offset:50176
	ds_read_b128 v[202:205], v193 offset:51200
	ds_read_b128 v[206:209], v193 offset:52224
	ds_read_b128 v[210:213], v193 offset:53248
	ds_read_b128 v[214:217], v193 offset:54272
	ds_read_b128 v[218:221], v193 offset:55296
	ds_read_b128 v[222:225], v193 offset:56320
	s_mov_b32 m0, s74
	v_lshl_add_u64 v[10:11], v[10:11], 0, s[4:5]
	s_add_u32 s44, s44, 0x80080
	global_load_lds_dwordx4 v[10:11], off
	v_lshl_add_u64 v[10:11], v[12:13], 0, s[4:5]
	s_mov_b32 m0, s75
	s_addc_u32 s45, s45, 0
	global_load_lds_dwordx4 v[10:11], off
	v_lshl_add_u64 v[10:11], s[44:45], 0, v[166:167]
	s_mov_b32 m0, s78
	s_nop 0
	global_load_lds_dwordx4 v[10:11], off
	v_lshl_add_u64 v[10:11], s[44:45], 0, v[170:171]
	s_mov_b32 m0, s79
	s_nop 0
	global_load_lds_dwordx4 v[10:11], off
	v_lshl_add_u64 v[10:11], v[14:15], 0, s[4:5]
	s_mov_b32 m0, s76
	s_nop 0
	global_load_lds_dwordx4 v[10:11], off
	v_lshl_add_u64 v[10:11], v[16:17], 0, s[4:5]
	s_mov_b32 m0, s77
	s_nop 0
	global_load_lds_dwordx4 v[10:11], off
	s_waitcnt vmcnt(8)
	s_waitcnt lgkmcnt(0)
	s_setprio 1
	s_barrier
	v_mfma_f32_16x16x128_f8f6f4 v[94:97], v[18:25], v[194:201], v[94:97]
	v_mfma_f32_16x16x128_f8f6f4 v[90:93], v[26:33], v[194:201], v[90:93]
	v_mfma_f32_16x16x128_f8f6f4 v[58:61], v[184:191], v[194:201], v[58:61]
	v_mfma_f32_16x16x128_f8f6f4 v[62:65], v[2:9], v[194:201], v[62:65]
	v_mfma_f32_16x16x128_f8f6f4 v[54:57], v[2:9], v[202:209], v[54:57]
	v_mfma_f32_16x16x128_f8f6f4 v[50:53], v[184:191], v[202:209], v[50:53]
	v_mfma_f32_16x16x128_f8f6f4 v[82:85], v[26:33], v[202:209], v[82:85]
	v_mfma_f32_16x16x128_f8f6f4 v[86:89], v[18:25], v[202:209], v[86:89]
	s_setprio 0
	s_setprio 1
	v_mfma_f32_16x16x128_f8f6f4 v[78:81], v[18:25], v[210:217], v[78:81]
	v_mfma_f32_16x16x128_f8f6f4 v[74:77], v[26:33], v[210:217], v[74:77]
	v_mfma_f32_16x16x128_f8f6f4 v[42:45], v[184:191], v[210:217], v[42:45]
	v_mfma_f32_16x16x128_f8f6f4 v[46:49], v[2:9], v[210:217], v[46:49]
	v_mfma_f32_16x16x128_f8f6f4 v[38:41], v[2:9], v[218:225], v[38:41]
	v_mfma_f32_16x16x128_f8f6f4 v[34:37], v[184:191], v[218:225], v[34:37]
	v_mfma_f32_16x16x128_f8f6f4 v[66:69], v[26:33], v[218:225], v[66:69]
	v_mfma_f32_16x16x128_f8f6f4 v[70:73], v[18:25], v[218:225], v[70:73]
	s_barrier
	s_setprio 0
	s_add_i32 s86, s86, 2
	s_add_u32 s46, s46, 0x100
	s_addc_u32 s47, s47, 0
	s_add_u32 s62, s62, 0x100
	s_addc_u32 s63, s63, 0
	s_cmp_gt_u32 s86, 29
	s_cbranch_scc0 .LBB0_947
	s_and_b64 vcc, exec, s[6:7]
	s_cbranch_vccz .LBB0_950
	s_barrier

.LBB0_1031:
	ds_read_b128 v[2:5], v189
	ds_read_b128 v[6:9], v189 offset:1024
	ds_read_b128 v[192:195], v189 offset:2048
	ds_read_b128 v[196:199], v189 offset:3072
	ds_read_b128 v[200:203], v189 offset:16384
	ds_read_b128 v[204:207], v189 offset:17408
	ds_read_b128 v[208:211], v189 offset:18432
	ds_read_b128 v[212:215], v189 offset:19456
	ds_read_b128 v[216:219], v190
	ds_read_b128 v[220:223], v190 offset:1024
	ds_read_b128 v[224:227], v190 offset:2048
	ds_read_b128 v[228:231], v190 offset:3072
	ds_read_b128 v[232:235], v190 offset:4096
	ds_read_b128 v[236:239], v190 offset:5120
	ds_read_b128 v[240:243], v190 offset:6144
	ds_read_b128 v[244:247], v190 offset:7168
	s_add_u32 s25, s36, 0x100
	s_addc_u32 s83, s37, 0
	s_and_b64 s[40:41], s[38:39], exec
	s_cselect_b32 s41, s1, s83
	s_cselect_b32 s40, s0, s25
	s_add_u32 s25, s26, 0x100
	s_addc_u32 s83, s27, 0
	s_and_b64 s[38:39], s[38:39], exec
	s_cselect_b32 s39, s5, s83
	s_cselect_b32 s38, s4, s25
	s_add_u32 s84, s36, 0x158080
	s_addc_u32 s85, s37, 0
	s_add_i32 s25, s23, 0xc000
	v_lshl_add_u64 v[174:175], s[84:85], 0, v[154:155]
	s_mov_b32 m0, s25
	s_add_i32 s83, s23, 0xe000
	global_load_lds_dwordx4 v[174:175], off
	v_lshl_add_u64 v[174:175], s[84:85], 0, v[158:159]
	s_mov_b32 m0, s83
	s_nop 0
	global_load_lds_dwordx4 v[174:175], off
	s_waitcnt vmcnt(8)
	s_waitcnt lgkmcnt(0)
	s_setprio 1
	s_barrier
	v_mfma_f32_16x16x128_f8f6f4 v[134:137], v[2:9], v[216:223], 0
	v_mfma_f32_16x16x128_f8f6f4 v[130:133], v[192:199], v[216:223], 0
	v_mfma_f32_16x16x128_f8f6f4 v[98:101], v[208:215], v[216:223], 0
	v_mfma_f32_16x16x128_f8f6f4 v[102:105], v[200:207], v[216:223], 0
	v_mfma_f32_16x16x128_f8f6f4 v[94:97], v[200:207], v[224:231], 0
	v_mfma_f32_16x16x128_f8f6f4 v[90:93], v[208:215], v[224:231], 0
	v_mfma_f32_16x16x128_f8f6f4 v[122:125], v[192:199], v[224:231], 0
	v_mfma_f32_16x16x128_f8f6f4 v[126:129], v[2:9], v[224:231], 0
	s_setprio 0
	s_setprio 1
	v_mfma_f32_16x16x128_f8f6f4 v[118:121], v[2:9], v[232:239], 0
	v_mfma_f32_16x16x128_f8f6f4 v[114:117], v[192:199], v[232:239], 0
	v_mfma_f32_16x16x128_f8f6f4 v[82:85], v[208:215], v[232:239], 0
	v_mfma_f32_16x16x128_f8f6f4 v[86:89], v[200:207], v[232:239], 0
	v_mfma_f32_16x16x128_f8f6f4 v[78:81], v[200:207], v[240:247], 0
	v_mfma_f32_16x16x128_f8f6f4 v[74:77], v[208:215], v[240:247], 0
	v_mfma_f32_16x16x128_f8f6f4 v[106:109], v[192:199], v[240:247], 0
	v_mfma_f32_16x16x128_f8f6f4 v[110:113], v[2:9], v[240:247], 0
	s_barrier
	s_setprio 0
	ds_read_b128 v[216:219], v190 offset:16384
	ds_read_b128 v[220:223], v190 offset:17408
	ds_read_b128 v[224:227], v190 offset:18432
	ds_read_b128 v[228:231], v190 offset:19456
	ds_read_b128 v[232:235], v190 offset:20480
	ds_read_b128 v[236:239], v190 offset:21504
	ds_read_b128 v[240:243], v190 offset:22528
	ds_read_b128 v[244:247], v190 offset:23552
	s_mov_b32 m0, s33
	v_lshl_add_u64 v[174:175], s[38:39], 0, v[156:157]
	s_add_u32 s84, s38, 0x158000
	global_load_lds_dwordx4 v[174:175], off
	v_lshl_add_u64 v[176:177], s[38:39], 0, v[160:161]
	s_mov_b32 m0, s35
	s_addc_u32 s85, s39, 0
	global_load_lds_dwordx4 v[176:177], off
	v_lshl_add_u64 v[182:183], s[84:85], 0, v[156:157]
	s_mov_b32 m0, s42
	v_lshl_add_u64 v[184:185], s[40:41], 0, v[158:159]
	global_load_lds_dwordx4 v[182:183], off
	v_lshl_add_u64 v[182:183], s[84:85], 0, v[160:161]
	s_mov_b32 m0, s43
	s_nop 0
	global_load_lds_dwordx4 v[182:183], off
	v_lshl_add_u64 v[182:183], s[40:41], 0, v[154:155]
	s_mov_b32 m0, s23
	s_nop 0
	global_load_lds_dwordx4 v[182:183], off
	s_mov_b32 m0, s44
	s_nop 0
	global_load_lds_dwordx4 v[184:185], off
	s_waitcnt vmcnt(8)
	s_waitcnt lgkmcnt(0)
	s_setprio 1
	s_barrier
	v_mfma_f32_16x16x128_f8f6f4 v[70:73], v[2:9], v[216:223], 0
	v_mfma_f32_16x16x128_f8f6f4 v[66:69], v[192:199], v[216:223], 0
	v_mfma_f32_16x16x128_f8f6f4 v[34:37], v[208:215], v[216:223], 0
	v_mfma_f32_16x16x128_f8f6f4 v[38:41], v[200:207], v[216:223], 0
	v_mfma_f32_16x16x128_f8f6f4 v[30:33], v[200:207], v[224:231], 0
	v_mfma_f32_16x16x128_f8f6f4 v[26:29], v[208:215], v[224:231], 0
	v_mfma_f32_16x16x128_f8f6f4 v[58:61], v[192:199], v[224:231], 0
	v_mfma_f32_16x16x128_f8f6f4 v[62:65], v[2:9], v[224:231], 0
	s_setprio 0
	s_setprio 1
	v_mfma_f32_16x16x128_f8f6f4 v[54:57], v[2:9], v[232:239], 0
	v_mfma_f32_16x16x128_f8f6f4 v[50:53], v[192:199], v[232:239], 0
	v_mfma_f32_16x16x128_f8f6f4 v[18:21], v[208:215], v[232:239], 0
	v_mfma_f32_16x16x128_f8f6f4 v[22:25], v[200:207], v[232:239], 0
	v_mfma_f32_16x16x128_f8f6f4 v[14:17], v[200:207], v[240:247], 0
	v_mfma_f32_16x16x128_f8f6f4 v[10:13], v[208:215], v[240:247], 0
	v_mfma_f32_16x16x128_f8f6f4 v[42:45], v[192:199], v[240:247], 0
	v_mfma_f32_16x16x128_f8f6f4 v[46:49], v[2:9], v[240:247], 0
	s_barrier
	s_setprio 0
	ds_read_b128 v[2:5], v189 offset:32768
	ds_read_b128 v[6:9], v189 offset:33792
	ds_read_b128 v[192:195], v189 offset:34816
	ds_read_b128 v[196:199], v189 offset:35840
	ds_read_b128 v[200:203], v189 offset:49152
	ds_read_b128 v[204:207], v189 offset:50176
	ds_read_b128 v[208:211], v189 offset:51200
	ds_read_b128 v[212:215], v189 offset:52224
	ds_read_b128 v[216:219], v190 offset:32768
	ds_read_b128 v[220:223], v190 offset:33792
	ds_read_b128 v[224:227], v190 offset:34816
	ds_read_b128 v[228:231], v190 offset:35840
	ds_read_b128 v[232:235], v190 offset:36864
	ds_read_b128 v[236:239], v190 offset:37888
	ds_read_b128 v[240:243], v190 offset:38912
	ds_read_b128 v[244:247], v190 offset:39936
	s_add_u32 s40, s40, 0x158000
	s_addc_u32 s41, s41, 0
	s_mov_b32 m0, s45
	v_lshl_add_u64 v[186:187], s[40:41], 0, v[154:155]
	global_load_lds_dwordx4 v[186:187], off
	v_lshl_add_u64 v[186:187], s[40:41], 0, v[158:159]
	s_mov_b32 m0, s46
	s_nop 0
	global_load_lds_dwordx4 v[186:187], off
	s_waitcnt vmcnt(8)
	s_waitcnt lgkmcnt(0)
	s_setprio 1
	s_barrier
	v_mfma_f32_16x16x128_f8f6f4 v[134:137], v[2:9], v[216:223], v[134:137]
	v_mfma_f32_16x16x128_f8f6f4 v[130:133], v[192:199], v[216:223], v[130:133]
	v_mfma_f32_16x16x128_f8f6f4 v[98:101], v[208:215], v[216:223], v[98:101]
	v_mfma_f32_16x16x128_f8f6f4 v[102:105], v[200:207], v[216:223], v[102:105]
	v_mfma_f32_16x16x128_f8f6f4 v[94:97], v[200:207], v[224:231], v[94:97]
	v_mfma_f32_16x16x128_f8f6f4 v[90:93], v[208:215], v[224:231], v[90:93]
	v_mfma_f32_16x16x128_f8f6f4 v[122:125], v[192:199], v[224:231], v[122:125]
	v_mfma_f32_16x16x128_f8f6f4 v[126:129], v[2:9], v[224:231], v[126:129]
	s_setprio 0
	s_setprio 1
	v_mfma_f32_16x16x128_f8f6f4 v[118:121], v[2:9], v[232:239], v[118:121]
	v_mfma_f32_16x16x128_f8f6f4 v[114:117], v[192:199], v[232:239], v[114:117]
	v_mfma_f32_16x16x128_f8f6f4 v[82:85], v[208:215], v[232:239], v[82:85]
	v_mfma_f32_16x16x128_f8f6f4 v[86:89], v[200:207], v[232:239], v[86:89]
	v_mfma_f32_16x16x128_f8f6f4 v[78:81], v[200:207], v[240:247], v[78:81]
	v_mfma_f32_16x16x128_f8f6f4 v[74:77], v[208:215], v[240:247], v[74:77]
	v_mfma_f32_16x16x128_f8f6f4 v[106:109], v[192:199], v[240:247], v[106:109]
	v_mfma_f32_16x16x128_f8f6f4 v[110:113], v[2:9], v[240:247], v[110:113]
	s_barrier
	s_setprio 0
	ds_read_b128 v[216:219], v190 offset:49152
	ds_read_b128 v[220:223], v190 offset:50176
	ds_read_b128 v[224:227], v190 offset:51200
	ds_read_b128 v[228:231], v190 offset:52224
	ds_read_b128 v[232:235], v190 offset:53248
	ds_read_b128 v[236:239], v190 offset:54272
	ds_read_b128 v[240:243], v190 offset:55296
	ds_read_b128 v[244:247], v190 offset:56320
	s_mov_b32 m0, s52
	v_lshl_add_u64 v[174:175], v[174:175], 0, s[14:15]
	s_add_u32 s38, s38, 0x158080
	global_load_lds_dwordx4 v[174:175], off
	v_lshl_add_u64 v[174:175], v[176:177], 0, s[14:15]
	s_mov_b32 m0, s53
	s_addc_u32 s39, s39, 0
	global_load_lds_dwordx4 v[174:175], off
	v_lshl_add_u64 v[174:175], s[38:39], 0, v[156:157]
	s_mov_b32 m0, s56
	s_nop 0
	global_load_lds_dwordx4 v[174:175], off
	v_lshl_add_u64 v[174:175], s[38:39], 0, v[160:161]
	s_mov_b32 m0, s57
	s_nop 0
	global_load_lds_dwordx4 v[174:175], off
	v_lshl_add_u64 v[174:175], v[182:183], 0, s[14:15]
	s_mov_b32 m0, s54
	s_nop 0
	global_load_lds_dwordx4 v[174:175], off
	v_lshl_add_u64 v[174:175], v[184:185], 0, s[14:15]
	s_mov_b32 m0, s55
	s_nop 0
	global_load_lds_dwordx4 v[174:175], off
	s_waitcnt vmcnt(8)
	s_waitcnt lgkmcnt(0)
	s_setprio 1
	s_barrier
	v_mfma_f32_16x16x128_f8f6f4 v[70:73], v[2:9], v[216:223], v[70:73]
	v_mfma_f32_16x16x128_f8f6f4 v[66:69], v[192:199], v[216:223], v[66:69]
	v_mfma_f32_16x16x128_f8f6f4 v[34:37], v[208:215], v[216:223], v[34:37]
	v_mfma_f32_16x16x128_f8f6f4 v[38:41], v[200:207], v[216:223], v[38:41]
	v_mfma_f32_16x16x128_f8f6f4 v[30:33], v[200:207], v[224:231], v[30:33]
	v_mfma_f32_16x16x128_f8f6f4 v[26:29], v[208:215], v[224:231], v[26:29]
	v_mfma_f32_16x16x128_f8f6f4 v[58:61], v[192:199], v[224:231], v[58:61]
	v_mfma_f32_16x16x128_f8f6f4 v[62:65], v[2:9], v[224:231], v[62:65]
	s_setprio 0
	s_setprio 1
	v_mfma_f32_16x16x128_f8f6f4 v[54:57], v[2:9], v[232:239], v[54:57]
	v_mfma_f32_16x16x128_f8f6f4 v[50:53], v[192:199], v[232:239], v[50:53]
	v_mfma_f32_16x16x128_f8f6f4 v[18:21], v[208:215], v[232:239], v[18:21]
	v_mfma_f32_16x16x128_f8f6f4 v[22:25], v[200:207], v[232:239], v[22:25]
	v_mfma_f32_16x16x128_f8f6f4 v[14:17], v[200:207], v[240:247], v[14:17]
	v_mfma_f32_16x16x128_f8f6f4 v[10:13], v[208:215], v[240:247], v[10:13]
	v_mfma_f32_16x16x128_f8f6f4 v[42:45], v[192:199], v[240:247], v[42:45]
	v_mfma_f32_16x16x128_f8f6f4 v[46:49], v[2:9], v[240:247], v[46:49]
	s_barrier
	s_setprio 0
	s_cmp_lt_u32 s82, 3
	s_cbranch_scc1 .LBB0_1036
	s_add_u32 s38, s48, s63
	s_addc_u32 s39, s49, s62
	s_add_u32 s36, s36, 0x158180
	s_addc_u32 s37, s37, 0
	s_add_u32 s40, s26, 0x200
	v_lshl_add_u64 v[174:175], v[172:173], 2, s[38:39]
	s_addc_u32 s41, s27, 0
	s_mov_b32 s84, 4
	s_cmp_eq_u32 s82, s84
	s_cselect_b64 s[26:27], -1, 0
	s_cmp_lg_u32 s82, s84
	s_cbranch_scc1 .LBB0_1034

.LBB0_1034:
	ds_read_b128 v[2:5], v189
	ds_read_b128 v[6:9], v189 offset:1024
	ds_read_b128 v[192:195], v189 offset:2048
	ds_read_b128 v[196:199], v189 offset:3072
	ds_read_b128 v[200:203], v189 offset:16384
	ds_read_b128 v[204:207], v189 offset:17408
	ds_read_b128 v[208:211], v189 offset:18432
	ds_read_b128 v[212:215], v189 offset:19456
	ds_read_b128 v[216:219], v190
	ds_read_b128 v[220:223], v190 offset:1024
	ds_read_b128 v[224:227], v190 offset:2048
	ds_read_b128 v[228:231], v190 offset:3072
	ds_read_b128 v[232:235], v190 offset:4096
	ds_read_b128 v[236:239], v190 offset:5120
	ds_read_b128 v[240:243], v190 offset:6144
	ds_read_b128 v[244:247], v190 offset:7168
	s_add_u32 s38, s36, 0xffea8080
	s_addc_u32 s39, s37, -1
	s_and_b64 s[26:27], s[26:27], exec
	s_cselect_b32 s26, s4, s40
	s_cselect_b32 s39, s1, s39
	s_cselect_b32 s38, s0, s38
	s_cselect_b32 s27, s5, s41
	s_mov_b32 m0, s25
	v_lshl_add_u64 v[176:177], s[36:37], 0, v[162:163]
	global_load_lds_dwordx4 v[176:177], off
	v_lshl_add_u64 v[176:177], s[36:37], 0, v[164:165]
	s_mov_b32 m0, s83
	s_nop 0
	global_load_lds_dwordx4 v[176:177], off
	s_waitcnt vmcnt(8)
	s_waitcnt lgkmcnt(0)
	s_setprio 1
	s_barrier
	v_mfma_f32_16x16x128_f8f6f4 v[134:137], v[2:9], v[216:223], v[134:137]
	v_mfma_f32_16x16x128_f8f6f4 v[130:133], v[192:199], v[216:223], v[130:133]
	v_mfma_f32_16x16x128_f8f6f4 v[98:101], v[208:215], v[216:223], v[98:101]
	v_mfma_f32_16x16x128_f8f6f4 v[102:105], v[200:207], v[216:223], v[102:105]
	v_mfma_f32_16x16x128_f8f6f4 v[94:97], v[200:207], v[224:231], v[94:97]
	v_mfma_f32_16x16x128_f8f6f4 v[90:93], v[208:215], v[224:231], v[90:93]
	v_mfma_f32_16x16x128_f8f6f4 v[122:125], v[192:199], v[224:231], v[122:125]
	v_mfma_f32_16x16x128_f8f6f4 v[126:129], v[2:9], v[224:231], v[126:129]
	s_setprio 0
	s_setprio 1
	v_mfma_f32_16x16x128_f8f6f4 v[118:121], v[2:9], v[232:239], v[118:121]
	v_mfma_f32_16x16x128_f8f6f4 v[114:117], v[192:199], v[232:239], v[114:117]
	v_mfma_f32_16x16x128_f8f6f4 v[82:85], v[208:215], v[232:239], v[82:85]
	v_mfma_f32_16x16x128_f8f6f4 v[86:89], v[200:207], v[232:239], v[86:89]
	v_mfma_f32_16x16x128_f8f6f4 v[78:81], v[200:207], v[240:247], v[78:81]
	v_mfma_f32_16x16x128_f8f6f4 v[74:77], v[208:215], v[240:247], v[74:77]
	v_mfma_f32_16x16x128_f8f6f4 v[106:109], v[192:199], v[240:247], v[106:109]
	v_mfma_f32_16x16x128_f8f6f4 v[110:113], v[2:9], v[240:247], v[110:113]
	s_barrier
	s_setprio 0
	ds_read_b128 v[216:219], v190 offset:16384
	ds_read_b128 v[220:223], v190 offset:17408
	ds_read_b128 v[224:227], v190 offset:18432
	ds_read_b128 v[228:231], v190 offset:19456
	ds_read_b128 v[232:235], v190 offset:20480
	ds_read_b128 v[236:239], v190 offset:21504
	ds_read_b128 v[240:243], v190 offset:22528
	ds_read_b128 v[244:247], v190 offset:23552
	s_mov_b32 m0, s33
	v_lshl_add_u64 v[176:177], s[26:27], 0, v[156:157]
	s_add_u32 s62, s26, 0x158000
	global_load_lds_dwordx4 v[176:177], off
	v_lshl_add_u64 v[182:183], s[26:27], 0, v[160:161]
	s_mov_b32 m0, s35
	s_addc_u32 s63, s27, 0
	global_load_lds_dwordx4 v[182:183], off
	v_lshl_add_u64 v[184:185], s[62:63], 0, v[156:157]
	s_mov_b32 m0, s42
	v_lshl_add_u64 v[186:187], s[38:39], 0, v[158:159]
	global_load_lds_dwordx4 v[184:185], off
	v_lshl_add_u64 v[184:185], s[62:63], 0, v[160:161]
	s_mov_b32 m0, s43
	s_nop 0
	global_load_lds_dwordx4 v[184:185], off
	v_lshl_add_u64 v[184:185], s[38:39], 0, v[154:155]
	s_mov_b32 m0, s23
	s_nop 0
	global_load_lds_dwordx4 v[184:185], off
	s_mov_b32 m0, s44
	s_nop 0
	global_load_lds_dwordx4 v[186:187], off
	s_waitcnt vmcnt(8)
	s_waitcnt lgkmcnt(0)
	s_setprio 1
	s_barrier
	v_mfma_f32_16x16x128_f8f6f4 v[70:73], v[2:9], v[216:223], v[70:73]
	v_mfma_f32_16x16x128_f8f6f4 v[66:69], v[192:199], v[216:223], v[66:69]
	v_mfma_f32_16x16x128_f8f6f4 v[34:37], v[208:215], v[216:223], v[34:37]
	v_mfma_f32_16x16x128_f8f6f4 v[38:41], v[200:207], v[216:223], v[38:41]
	v_mfma_f32_16x16x128_f8f6f4 v[30:33], v[200:207], v[224:231], v[30:33]
	v_mfma_f32_16x16x128_f8f6f4 v[26:29], v[208:215], v[224:231], v[26:29]
	v_mfma_f32_16x16x128_f8f6f4 v[58:61], v[192:199], v[224:231], v[58:61]
	v_mfma_f32_16x16x128_f8f6f4 v[62:65], v[2:9], v[224:231], v[62:65]
	s_setprio 0
	s_setprio 1
	v_mfma_f32_16x16x128_f8f6f4 v[54:57], v[2:9], v[232:239], v[54:57]
	v_mfma_f32_16x16x128_f8f6f4 v[50:53], v[192:199], v[232:239], v[50:53]
	v_mfma_f32_16x16x128_f8f6f4 v[18:21], v[208:215], v[232:239], v[18:21]
	v_mfma_f32_16x16x128_f8f6f4 v[22:25], v[200:207], v[232:239], v[22:25]
	v_mfma_f32_16x16x128_f8f6f4 v[14:17], v[200:207], v[240:247], v[14:17]
	v_mfma_f32_16x16x128_f8f6f4 v[10:13], v[208:215], v[240:247], v[10:13]
	v_mfma_f32_16x16x128_f8f6f4 v[42:45], v[192:199], v[240:247], v[42:45]
	v_mfma_f32_16x16x128_f8f6f4 v[46:49], v[2:9], v[240:247], v[46:49]
	s_barrier
	s_setprio 0
	ds_read_b128 v[192:195], v189 offset:32768
	ds_read_b128 v[196:199], v189 offset:33792
	ds_read_b128 v[200:203], v189 offset:34816
	ds_read_b128 v[204:207], v189 offset:35840
	ds_read_b128 v[2:5], v189 offset:49152
	ds_read_b128 v[6:9], v189 offset:50176
	ds_read_b128 v[208:211], v189 offset:51200
	ds_read_b128 v[212:215], v189 offset:52224
	ds_read_b128 v[216:219], v190 offset:32768
	ds_read_b128 v[220:223], v190 offset:33792
	ds_read_b128 v[224:227], v190 offset:34816
	ds_read_b128 v[228:231], v190 offset:35840
	ds_read_b128 v[232:235], v190 offset:36864
	ds_read_b128 v[236:239], v190 offset:37888
	ds_read_b128 v[240:243], v190 offset:38912
	ds_read_b128 v[244:247], v190 offset:39936
	s_add_u32 s38, s38, 0x158000
	s_addc_u32 s39, s39, 0
	s_mov_b32 m0, s45
	v_lshl_add_u64 v[248:249], s[38:39], 0, v[154:155]
	global_load_lds_dwordx4 v[248:249], off
	v_lshl_add_u64 v[248:249], s[38:39], 0, v[158:159]
	s_mov_b32 m0, s46
	s_nop 0
	global_load_lds_dwordx4 v[248:249], off
	s_waitcnt vmcnt(8)
	s_waitcnt lgkmcnt(0)
	s_setprio 1
	s_barrier
	v_mfma_f32_16x16x128_f8f6f4 v[134:137], v[192:199], v[216:223], v[134:137]
	v_mfma_f32_16x16x128_f8f6f4 v[130:133], v[200:207], v[216:223], v[130:133]
	v_mfma_f32_16x16x128_f8f6f4 v[98:101], v[208:215], v[216:223], v[98:101]
	v_mfma_f32_16x16x128_f8f6f4 v[102:105], v[2:9], v[216:223], v[102:105]
	v_mfma_f32_16x16x128_f8f6f4 v[94:97], v[2:9], v[224:231], v[94:97]
	v_mfma_f32_16x16x128_f8f6f4 v[90:93], v[208:215], v[224:231], v[90:93]
	v_mfma_f32_16x16x128_f8f6f4 v[122:125], v[200:207], v[224:231], v[122:125]
	v_mfma_f32_16x16x128_f8f6f4 v[126:129], v[192:199], v[224:231], v[126:129]
	s_setprio 0
	s_setprio 1
	v_mfma_f32_16x16x128_f8f6f4 v[118:121], v[192:199], v[232:239], v[118:121]
	v_mfma_f32_16x16x128_f8f6f4 v[114:117], v[200:207], v[232:239], v[114:117]
	v_mfma_f32_16x16x128_f8f6f4 v[82:85], v[208:215], v[232:239], v[82:85]
	v_mfma_f32_16x16x128_f8f6f4 v[86:89], v[2:9], v[232:239], v[86:89]
	v_mfma_f32_16x16x128_f8f6f4 v[78:81], v[2:9], v[240:247], v[78:81]
	v_mfma_f32_16x16x128_f8f6f4 v[74:77], v[208:215], v[240:247], v[74:77]
	v_mfma_f32_16x16x128_f8f6f4 v[106:109], v[200:207], v[240:247], v[106:109]
	v_mfma_f32_16x16x128_f8f6f4 v[110:113], v[192:199], v[240:247], v[110:113]
	s_barrier
	s_setprio 0
	ds_read_b128 v[216:219], v190 offset:49152
	ds_read_b128 v[220:223], v190 offset:50176
	ds_read_b128 v[224:227], v190 offset:51200
	ds_read_b128 v[228:231], v190 offset:52224
	ds_read_b128 v[232:235], v190 offset:53248
	ds_read_b128 v[236:239], v190 offset:54272
	ds_read_b128 v[240:243], v190 offset:55296
	ds_read_b128 v[244:247], v190 offset:56320
	s_mov_b32 m0, s52
	v_lshl_add_u64 v[176:177], v[176:177], 0, s[14:15]
	s_add_u32 s26, s26, 0x158080
	global_load_lds_dwordx4 v[176:177], off
	v_lshl_add_u64 v[176:177], v[182:183], 0, s[14:15]
	s_mov_b32 m0, s53
	s_addc_u32 s27, s27, 0
	global_load_lds_dwordx4 v[176:177], off
	v_lshl_add_u64 v[176:177], s[26:27], 0, v[156:157]
	s_mov_b32 m0, s56
	s_nop 0
	global_load_lds_dwordx4 v[176:177], off
	v_lshl_add_u64 v[176:177], s[26:27], 0, v[160:161]
	s_mov_b32 m0, s57
	s_nop 0
	global_load_lds_dwordx4 v[176:177], off
	v_lshl_add_u64 v[176:177], v[184:185], 0, s[14:15]
	s_mov_b32 m0, s54
	s_nop 0
	global_load_lds_dwordx4 v[176:177], off
	v_lshl_add_u64 v[176:177], v[186:187], 0, s[14:15]
	s_mov_b32 m0, s55
	s_nop 0
	global_load_lds_dwordx4 v[176:177], off
	s_waitcnt vmcnt(8)
	s_waitcnt lgkmcnt(0)
	s_setprio 1
	s_barrier
	v_mfma_f32_16x16x128_f8f6f4 v[70:73], v[192:199], v[216:223], v[70:73]
	v_mfma_f32_16x16x128_f8f6f4 v[66:69], v[200:207], v[216:223], v[66:69]
	v_mfma_f32_16x16x128_f8f6f4 v[34:37], v[208:215], v[216:223], v[34:37]
	v_mfma_f32_16x16x128_f8f6f4 v[38:41], v[2:9], v[216:223], v[38:41]
	v_mfma_f32_16x16x128_f8f6f4 v[30:33], v[2:9], v[224:231], v[30:33]
	v_mfma_f32_16x16x128_f8f6f4 v[26:29], v[208:215], v[224:231], v[26:29]
	v_mfma_f32_16x16x128_f8f6f4 v[58:61], v[200:207], v[224:231], v[58:61]
	v_mfma_f32_16x16x128_f8f6f4 v[62:65], v[192:199], v[224:231], v[62:65]
	s_setprio 0
	s_setprio 1
	v_mfma_f32_16x16x128_f8f6f4 v[54:57], v[192:199], v[232:239], v[54:57]
	v_mfma_f32_16x16x128_f8f6f4 v[50:53], v[200:207], v[232:239], v[50:53]
	v_mfma_f32_16x16x128_f8f6f4 v[18:21], v[208:215], v[232:239], v[18:21]
	v_mfma_f32_16x16x128_f8f6f4 v[22:25], v[2:9], v[232:239], v[22:25]
	v_mfma_f32_16x16x128_f8f6f4 v[14:17], v[2:9], v[240:247], v[14:17]
	v_mfma_f32_16x16x128_f8f6f4 v[10:13], v[208:215], v[240:247], v[10:13]
	v_mfma_f32_16x16x128_f8f6f4 v[42:45], v[200:207], v[240:247], v[42:45]
	v_mfma_f32_16x16x128_f8f6f4 v[46:49], v[192:199], v[240:247], v[46:49]
	s_barrier
	s_setprio 0
	s_add_i32 s26, s84, 2
	s_add_u32 s36, s36, 0x100
	s_addc_u32 s37, s37, 0
	s_add_u32 s40, s40, 0x100
	s_addc_u32 s41, s41, 0
	s_cmp_ge_i32 s84, s82
	s_cbranch_scc1 .LBB0_1036
	s_mov_b32 s84, s26
	s_cmp_eq_u32 s82, s84
	s_cselect_b64 s[26:27], -1, 0
	s_cmp_lg_u32 s82, s84
	s_cbranch_scc0 .LBB0_1033
	s_branch .LBB0_1034
